# GDN-A W/UT/KDT via LDS images + coalesced stores; prompt diff-attn: V tile b128 conflict-free layout, ALiBi folded into one fma per score (softmax block hand-written)
# speedup vs baseline: 1.0541x; 1.0077x over previous
_Z4mega1P:
	s_mov_b32 s98, 0
	s_mov_b64 s[80:81], s[0:1]
	v_writelane_b32 v253, s2, 0
	s_load_dwordx8 s[0:7], s[80:81], 0x100
	v_and_b32_e32 v230, 0x3ff, v0
	v_cmp_gt_u32_e32 vcc, 4, v230
	s_waitcnt lgkmcnt(0)
	v_writelane_b32 v253, s0, 1
	s_nop 1
	v_writelane_b32 v253, s1, 2
	v_writelane_b32 v253, s2, 3
	v_writelane_b32 v253, s3, 4
	v_writelane_b32 v253, s4, 5
	v_writelane_b32 v253, s5, 6
	v_writelane_b32 v253, s6, 7
	v_writelane_b32 v253, s7, 8
	s_load_dwordx2 s[96:97], s[80:81], 0x120
	s_load_dwordx4 s[8:11], s[80:81], 0x128
	s_load_dword s0, s[80:81], 0x140
	s_add_u32 s4, s80, 0x138
	s_addc_u32 s5, s81, 0
	s_waitcnt lgkmcnt(0)
	v_writelane_b32 v253, s0, 9
	s_load_dwordx2 s[0:1], s[80:81], 0x138
	s_waitcnt lgkmcnt(0)
	v_writelane_b32 v253, s0, 10
	s_nop 1
	v_writelane_b32 v253, s1, 11
	s_and_saveexec_b64 s[2:3], vcc
	v_lshl_add_u32 v1, v230, 2, 0
	v_add_u32_e32 v1, 0x23fe0, v1
	v_mov_b32_e32 v2, 0
	ds_write_b32 v1, v2
	v_writelane_b32 v253, s8, 12
	s_nop 1
	v_writelane_b32 v253, s9, 13
	v_writelane_b32 v253, s10, 14
	v_writelane_b32 v253, s11, 15
	s_or_b64 exec, exec, s[2:3]
	s_add_u32 s0, s96, 0x2904c100
	s_addc_u32 s1, s97, 0
	v_writelane_b32 v253, s0, 16
	s_waitcnt lgkmcnt(0)
	s_barrier
	v_writelane_b32 v253, s1, 17
	s_getreg_b32 s0, hwreg(HW_REG_XCC_ID, 0, 4)
	s_and_b32 s0, s0, 15
	v_writelane_b32 v253, s0, 18
	v_cmp_eq_u32_e64 s[0:1], 0, v230
	s_mov_b64 s[2:3], exec
	s_nop 0
	v_writelane_b32 v253, s0, 19
	s_nop 1
	v_writelane_b32 v253, s1, 20
	s_and_b64 s[0:1], s[2:3], s[0:1]
	s_mov_b64 exec, s[0:1]
	s_cbranch_execz .LBB0_5
	s_mov_b64 s[6:7], exec
	v_mbcnt_lo_u32_b32 v1, s6, 0
	v_mbcnt_hi_u32_b32 v1, s7, v1
	v_cmp_eq_u32_e32 vcc, 0, v1
	s_and_b64 s[0:1], exec, vcc
	s_mov_b64 exec, s[0:1]
	s_cbranch_execz .LBB0_5
	v_readlane_b32 s0, v253, 18
	s_lshl_b32 s0, s0, 8
	s_bcnt1_i32_b64 s1, s[6:7]
	v_mov_b32_e32 v1, s0
	v_mov_b32_e32 v2, s1
	v_readlane_b32 s0, v253, 16
	v_readlane_b32 s1, v253, 17
	s_nop 4
	global_atomic_add v1, v2, s[0:1] offset:1024

.LBB0_744:
	v_mov_b32_e32 v0, v230
	s_barrier
	s_cmp_eq_u32 s98, 0
	s_cbranch_scc1 .Lco64_skip
	v_lshlrev_b32_e32 v200, 4, v230
	v_lshrrev_b32_e32 v201, 3, v230
	v_and_b32_e32 v202, 7, v230
	v_mul_u32_u24_e32 v201, 0x90, v201
	v_lshl_add_u32 v201, v202, 4, v201
	ds_read_b128 v[204:207], v201 offset:512
	ds_read_b128 v[208:211], v201 offset:9728
	ds_read_b128 v[212:215], v200 offset:18944
	ds_read_b128 v[216:219], v200 offset:27136
	v_add_u32_e32 v203, 0x2000, v200
	v_add_u32_e32 v220, 0x4000, v200
	v_add_u32_e32 v221, 0x6000, v200
	v_lshrrev_b32_e32 v222, 3, v230
	v_lshrrev_b32_e32 v223, 7, v230
	v_xor_b32_e32 v223, v223, v202
	v_lshlrev_b32_e32 v223, 4, v223
	v_lshl_add_u32 v222, v222, 7, v223
	v_add_u32_e32 v222, 0x1e200, v222
	v_xor_b32_e32 v223, 64, v222
	ds_read_b128 v[224:227], v222
	ds_read_b128 v[232:235], v223 offset:8192
	v_add_u32_e32 v222, 0xe000, v200
	v_add_u32_e32 v223, 0x10000, v200
	s_waitcnt lgkmcnt(0)
	global_store_dwordx4 v220, v[204:207], s[100:101]
	global_store_dwordx4 v221, v[208:211], s[100:101]
	global_store_dwordx4 v200, v[212:215], s[100:101]
	global_store_dwordx4 v203, v[216:219], s[100:101]
	global_store_dwordx4 v222, v[224:227], s[100:101]
	global_store_dwordx4 v223, v[232:235], s[100:101]
	s_mov_b32 s98, 0
.Lco64_skip:
	s_nop 0
	v_cmp_eq_u32_e32 vcc, 0, v0
	s_and_saveexec_b64 s[0:1], vcc
	s_cbranch_execz .LBB0_748
	s_mov_b64 s[38:39], exec
	v_mbcnt_lo_u32_b32 v0, s38, 0
	v_mbcnt_hi_u32_b32 v0, s39, v0
	v_cmp_eq_u32_e32 vcc, 0, v0
	s_and_saveexec_b64 s[36:37], vcc
	s_cbranch_execz .LBB0_747
	s_bcnt1_i32_b64 s4, s[38:39]
	v_mov_b32_e32 v1, s4
	global_atomic_add v1, v105, v1, s[90:91] sc0

.LBB0_902:
	s_or_b64 exec, exec, s[0:1]
	s_mul_i32 s1, s88, 0x12000
	s_mul_hi_u32 s0, s88, 0x12000
	s_add_u32 s38, s82, s1
	s_addc_u32 s39, s83, s0
	s_barrier
	s_and_saveexec_b64 s[40:41], s[36:37]
	s_cbranch_execz .LBB0_904
	v_mov_b32_e32 v24, v123
	v_mov_b32_e32 v25, v93
	v_mov_b32_e32 v22, v122
	v_mov_b32_e32 v23, v92
	v_pk_mul_f32 v[24:25], v[24:25], v[24:25]
	v_pk_mul_f32 v[12:13], v[96:97], v[96:97]
	v_pk_fma_f32 v[22:23], v[22:23], v[22:23], v[24:25]
	v_mov_b32_e32 v24, v118
	v_mov_b32_e32 v25, v90
	v_pk_fma_f32 v[22:23], v[24:25], v[24:25], v[22:23]
	v_mov_b32_e32 v24, v119
	v_mov_b32_e32 v25, v91
	v_pk_fma_f32 v[22:23], v[24:25], v[24:25], v[22:23]
	v_mov_b32_e32 v24, v120
	v_mov_b32_e32 v25, v94
	v_pk_fma_f32 v[22:23], v[24:25], v[24:25], v[22:23]
	v_mov_b32_e32 v24, v121
	v_mov_b32_e32 v25, v95
	v_pk_fma_f32 v[22:23], v[24:25], v[24:25], v[22:23]
	v_mov_b32_e32 v24, v116
	v_mov_b32_e32 v25, v88
	v_pk_mul_f32 v[20:21], v[114:115], v[114:115]
	v_pk_fma_f32 v[22:23], v[24:25], v[24:25], v[22:23]
	v_mov_b32_e32 v24, v117
	v_mov_b32_e32 v25, v89
	v_pk_fma_f32 v[22:23], v[24:25], v[24:25], v[22:23]
	v_mov_b32_e32 v24, v20
	v_mov_b32_e32 v25, v12
	v_and_b32_e32 v12, 64, v133
	v_pk_add_f32 v[22:23], v[24:25], v[22:23]
	v_add_u32_e32 v24, 64, v12
	v_xor_b32_e32 v12, 1, v133
	v_cmp_lt_i32_e32 vcc, v12, v24
	v_pk_mul_f32 v[10:11], v[86:87], v[86:87]
	v_pk_mul_f32 v[18:19], v[102:103], v[102:103]
	v_cndmask_b32_e32 v12, v133, v12, vcc
	v_lshlrev_b32_e32 v25, 2, v12
	v_mov_b32_e32 v12, v21
	v_pk_add_f32 v[12:13], v[12:13], v[22:23]
	v_mov_b32_e32 v20, v18
	v_mov_b32_e32 v21, v10
	v_pk_mul_f32 v[8:9], v[98:99], v[98:99]
	v_pk_mul_f32 v[16:17], v[112:113], v[112:113]
	v_pk_add_f32 v[12:13], v[20:21], v[12:13]
	v_mov_b32_e32 v10, v19
	v_pk_add_f32 v[10:11], v[10:11], v[12:13]
	v_mov_b32_e32 v12, v16
	v_mov_b32_e32 v13, v8
	v_pk_mul_f32 v[6:7], v[84:85], v[84:85]
	v_pk_mul_f32 v[14:15], v[100:101], v[100:101]
	v_pk_add_f32 v[10:11], v[12:13], v[10:11]
	v_mov_b32_e32 v8, v17
	v_pk_add_f32 v[8:9], v[8:9], v[10:11]
	v_mov_b32_e32 v10, v14
	v_mov_b32_e32 v11, v6
	v_pk_add_f32 v[8:9], v[10:11], v[8:9]
	v_mov_b32_e32 v6, v15
	v_pk_add_f32 v[6:7], v[6:7], v[8:9]
	ds_bpermute_b32 v9, v25, v7
	ds_bpermute_b32 v8, v25, v6
	v_xor_b32_e32 v10, 2, v133
	v_cmp_lt_i32_e32 vcc, v10, v24
	s_mov_b32 s0, 0x358637bd
	v_lshl_add_u32 v35, v82, 2, 0
	v_cndmask_b32_e32 v10, v133, v10, vcc
	v_lshlrev_b32_e32 v10, 2, v10
	s_waitcnt lgkmcnt(0)
	v_pk_add_f32 v[6:7], v[6:7], v[8:9]
	ds_bpermute_b32 v9, v10, v7
	ds_bpermute_b32 v8, v10, v6
	v_xor_b32_e32 v10, 4, v133
	v_cmp_lt_i32_e32 vcc, v10, v24
	v_ashrrev_i32_e32 v83, 31, v82
	s_waitcnt lgkmcnt(0)
	v_pk_add_f32 v[6:7], v[6:7], v[8:9]
	v_cndmask_b32_e32 v10, v133, v10, vcc
	v_lshlrev_b32_e32 v10, 2, v10
	ds_bpermute_b32 v9, v10, v7
	ds_bpermute_b32 v8, v10, v6
	ds_read2st64_b32 v[14:15], v35 offset1:1
	ds_read_b32 v10, v105 offset:252
	s_waitcnt lgkmcnt(2)
	v_pk_add_f32 v[6:7], v[6:7], v[8:9]
	s_nop 0
	v_pk_add_f32 v[6:7], v[6:7], s[0:1] op_sel_hi:[1,0]
	s_waitcnt lgkmcnt(1)
	v_mov_b32_e32 v40, v15
	v_mul_f32_e32 v8, 0x4b800000, v7
	v_cmp_gt_f32_e32 vcc, s26, v7
	v_cmp_gt_f32_e64 s[0:1], s26, v6
	s_nop 0
	v_cndmask_b32_e32 v7, v7, v8, vcc
	v_mul_f32_e32 v8, 0x4b800000, v6
	v_rsq_f32_e32 v7, v7
	v_cndmask_b32_e64 v6, v6, v8, s[0:1]
	v_rsq_f32_e32 v8, v6
	v_mul_f32_e32 v6, 0x45800000, v7
	v_cndmask_b32_e32 v6, v7, v6, vcc
	v_mul_f32_e32 v7, 0x45800000, v8
	v_cndmask_b32_e64 v34, v8, v7, s[0:1]
	v_mul_f32_e32 v7, 0x3fb8aa3b, v14
	s_waitcnt lgkmcnt(0)
	v_sub_f32_e32 v8, v10, v14
	v_exp_f32_e32 v14, v7
	v_mul_f32_e32 v6, 0x3db504f3, v6
	s_movk_i32 s0, 0x10c
	v_mul_f32_e32 v8, 0x3fb8aa3b, v8
	v_pk_mul_f32 v[16:17], v[92:93], v[6:7] op_sel_hi:[1,0]
	v_pk_mul_f32 v[18:19], v[90:91], v[6:7] op_sel_hi:[1,0]
	v_pk_mul_f32 v[20:21], v[94:95], v[6:7] op_sel_hi:[1,0]
	v_pk_mul_f32 v[22:23], v[88:89], v[6:7] op_sel_hi:[1,0]
	v_mul_lo_u32 v36, v82, s0
	v_pk_mul_f32 v[24:25], v[96:97], v[6:7] op_sel_hi:[1,0]
	v_pk_mul_f32 v[26:27], v[86:87], v[6:7] op_sel_hi:[1,0]
	v_pk_mul_f32 v[28:29], v[98:99], v[6:7] op_sel_hi:[1,0]
	v_pk_mul_f32 v[30:31], v[84:85], v[6:7] op_sel_hi:[1,0]
	v_exp_f32_e32 v37, v8
	v_cvt_pk_bf16_f32 v6, v16, v17
	v_cvt_pk_bf16_f32 v7, v18, v19
	v_cvt_pk_bf16_f32 v8, v20, v21
	v_cvt_pk_bf16_f32 v9, v22, v23
	v_add3_u32 v41, v35, v36, v104
	v_cvt_pk_bf16_f32 v10, v24, v25
	v_cvt_pk_bf16_f32 v11, v26, v27
	v_cvt_pk_bf16_f32 v12, v28, v29
	v_cvt_pk_bf16_f32 v13, v30, v31
	ds_write_b128 v41, v[6:9] offset:512
	ds_write_b128 v41, v[10:13] offset:528
	v_pk_mul_f32 v[6:7], v[14:15], v[16:17] op_sel_hi:[0,1]
	v_pk_mul_f32 v[8:9], v[14:15], v[18:19] op_sel_hi:[0,1]
	v_cvt_pk_bf16_f32 v6, v6, v7
	v_cvt_pk_bf16_f32 v7, v8, v9
	v_pk_mul_f32 v[8:9], v[14:15], v[20:21] op_sel_hi:[0,1]
	v_pk_mul_f32 v[10:11], v[14:15], v[22:23] op_sel_hi:[0,1]
	v_cvt_pk_bf16_f32 v8, v8, v9
	v_cvt_pk_bf16_f32 v9, v10, v11
	v_pk_mul_f32 v[10:11], v[14:15], v[24:25] op_sel_hi:[0,1]
	v_pk_mul_f32 v[12:13], v[14:15], v[26:27] op_sel_hi:[0,1]
	v_cvt_pk_bf16_f32 v10, v10, v11
	v_cvt_pk_bf16_f32 v11, v12, v13
	v_pk_mul_f32 v[12:13], v[14:15], v[28:29] op_sel_hi:[0,1]
	v_pk_mul_f32 v[16:17], v[14:15], v[30:31] op_sel_hi:[0,1]
	v_cvt_pk_bf16_f32 v12, v12, v13
	v_cvt_pk_bf16_f32 v13, v16, v17
	v_lshlrev_b64 v[16:17], 8, v[82:83]
	v_lshl_add_u64 v[16:17], s[38:39], 0, v[16:17]
	v_lshl_add_u64 v[16:17], v[16:17], 0, v[104:105]
	s_mov_b64 s[0:1], 0x8000
	v_lshl_add_u64 v[18:19], v[16:17], 0, s[0:1]
	s_mov_b32 s0, 0x8000
	v_add_co_u32_e32 v16, vcc, s0, v16
	v_lshlrev_b32_e32 v104, 7, v81
	s_nop 0
	v_addc_co_u32_e32 v17, vcc, 0, v17, vcc
	global_store_dwordx4 v[16:17], v[6:9], off
	global_store_dwordx4 v[18:19], v[10:13], off offset:16
	s_mov_b64 s[0:1], 0xe000
	v_lshl_add_u64 v[6:7], v[82:83], 1, s[38:39]
	v_lshlrev_b32_e32 v8, 10, v82
	v_lshlrev_b32_e32 v9, 2, v81
	v_pk_mul_f32 v[12:13], v[122:123], v[34:35] op_sel_hi:[1,0]
	v_add3_u32 v42, 0, v8, v9
	v_lshl_add_u64 v[8:9], v[6:7], 0, v[104:105]
	v_mul_f32_e32 v11, v37, v12
	v_and_b32_e32 v38, 0x38, v82
	v_lshlrev_b32_e32 v38, 1, v38
	v_xor_b32_e32 v38, v38, v81
	v_and_b32_e32 v39, 7, v82
	v_lshl_add_u32 v38, v39, 1, v38
	v_lshl_add_u32 v38, v81, 7, v38
	v_add_u32_e32 v38, 0x1e200, v38
	v_cvt_pk_bf16_f32 v11, v11, s0
	s_mov_b32 s0, 0xe000
	v_add_co_u32_e32 v8, vcc, s0, v8
	v_mul_f32_e32 v36, v15, v14
	s_nop 0
	v_addc_co_u32_e32 v9, vcc, 0, v9, vcc
	v_cvt_pk_bf16_f32 v10, v12, v13
	ds_write_b16 v38, v11
	v_mul_f32_e32 v8, v37, v13
	v_pk_mul_f32 v[14:15], v[36:37], v[12:13] op_sel_hi:[0,1]
	v_pk_mul_f32 v[12:13], v[118:119], v[34:35] op_sel_hi:[1,0]
	v_pk_mul_f32 v[20:21], v[120:121], v[34:35] op_sel_hi:[1,0]
	v_mul_f32_e32 v16, v37, v12
	v_cvt_pk_bf16_f32 v16, v16, s0
	ds_write_b16 v38, v16 offset:256
	v_mul_f32_e32 v16, v37, v13
	v_cvt_pk_bf16_f32 v16, v16, s0
	v_cvt_pk_bf16_f32 v11, v12, v13
	ds_write_b16 v38, v16 offset:384
	v_pk_mul_f32 v[16:17], v[36:37], v[12:13] op_sel_hi:[0,1]
	v_mul_f32_e32 v13, v37, v20
	v_cvt_pk_bf16_f32 v13, v13, s0
	ds_write_b16 v38, v13 offset:512
	v_mul_f32_e32 v13, v37, v21
	v_cvt_pk_bf16_f32 v13, v13, s0
	v_pk_mul_f32 v[24:25], v[116:117], v[34:35] op_sel_hi:[1,0]
	v_cvt_pk_bf16_f32 v12, v20, v21
	ds_write_b16 v38, v13 offset:640
	v_cvt_pk_bf16_f32 v13, v24, v25
	ds_write_b128 v41, v[10:13] offset:17920
	v_pk_mul_f32 v[12:13], v[114:115], v[34:35] op_sel_hi:[1,0]
	v_mul_f32_e32 v10, v37, v24
	v_mul_f32_e32 v27, v37, v12
	v_cvt_pk_bf16_f32 v10, v10, s0
	v_cvt_pk_bf16_f32 v27, v27, s0
	ds_write_b16 v38, v10 offset:768
	v_mul_f32_e32 v10, v37, v25
	v_cvt_pk_bf16_f32 v26, v12, v13
	ds_write_b16 v38, v27 offset:1024
	v_mul_f32_e32 v27, v37, v13
	v_pk_mul_f32 v[30:31], v[36:37], v[12:13] op_sel_hi:[0,1]
	v_pk_mul_f32 v[12:13], v[4:5], v[40:41] op_sel_hi:[1,0]
	v_pk_mul_f32 v[4:5], v[102:103], v[34:35] op_sel_hi:[1,0]
	v_cvt_pk_bf16_f32 v10, v10, s0
	v_cvt_pk_bf16_f32 v27, v27, s0
	v_mul_f32_e32 v28, v37, v4
	ds_write_b16 v38, v10 offset:896
	v_pk_mul_f32 v[10:11], v[32:33], v[40:41] op_sel_hi:[1,0]
	ds_write_b16 v38, v27 offset:1152
	v_cvt_pk_bf16_f32 v27, v4, v5
	v_cvt_pk_bf16_f32 v43, v28, s0
	v_mul_f32_e32 v28, v37, v5
	v_pk_mul_f32 v[32:33], v[36:37], v[4:5] op_sel_hi:[0,1]
	v_pk_mul_f32 v[4:5], v[112:113], v[34:35] op_sel_hi:[1,0]
	v_pk_mul_f32 v[34:35], v[100:101], v[34:35] op_sel_hi:[1,0]
	v_mul_f32_e32 v29, v37, v4
	v_cvt_pk_bf16_f32 v45, v29, s0
	v_mul_f32_e32 v29, v37, v5
	v_pk_mul_f32 v[6:7], v[124:125], v[40:41] op_sel_hi:[1,0]
	v_cvt_pk_bf16_f32 v8, v8, s0
	v_cvt_pk_bf16_f32 v44, v28, s0
	v_cvt_pk_bf16_f32 v28, v4, v5
	v_cvt_pk_bf16_f32 v46, v29, s0
	v_cvt_pk_bf16_f32 v29, v34, v35
	ds_write_b16 v38, v8 offset:128
	v_pk_mul_f32 v[8:9], v[52:53], v[40:41] op_sel_hi:[1,0]
	v_pk_mul_f32 v[18:19], v[48:49], v[40:41] op_sel_hi:[1,0]
	v_pk_mul_f32 v[22:23], v[36:37], v[20:21] op_sel_hi:[0,1]
	v_pk_mul_f32 v[20:21], v[50:51], v[40:41] op_sel_hi:[1,0]
	v_pk_mul_f32 v[24:25], v[36:37], v[24:25] op_sel_hi:[0,1]
	ds_write_b128 v41, v[26:29] offset:17936
	ds_write_b128 v42, v[6:9] offset:51712
	ds_write_b128 v42, v[14:17] offset:52224
	ds_write_b128 v42, v[18:21] offset:51728
	ds_write_b128 v42, v[22:25] offset:52240
	v_mul_f32_e32 v6, v37, v34
	v_cvt_pk_bf16_f32 v6, v6, s0
	ds_write_b16 v38, v43 offset:1280
	ds_write_b16 v38, v44 offset:1408
	ds_write_b128 v42, v[10:13] offset:51744
	ds_write_b128 v42, v[30:33] offset:52256
	ds_write_b16 v38, v45 offset:1536
	ds_write_b16 v38, v46 offset:1664
	ds_write_b16 v38, v6 offset:1792
	v_mul_f32_e32 v6, v37, v35
	v_cvt_pk_bf16_f32 v6, v6, s0
	v_pk_mul_f32 v[0:1], v[0:1], v[40:41] op_sel_hi:[1,0]
	v_pk_mul_f32 v[4:5], v[36:37], v[4:5] op_sel_hi:[0,1]
	v_pk_mul_f32 v[2:3], v[2:3], v[40:41] op_sel_hi:[1,0]
	ds_write_b16 v38, v6 offset:1920
	v_pk_mul_f32 v[6:7], v[36:37], v[34:35] op_sel_hi:[0,1]
	ds_write_b128 v42, v[0:3] offset:51760
	ds_write_b128 v42, v[4:7] offset:52272

.LBB0_933:
	v_cmp_gt_i32_e32 vcc, s27, v80
	s_waitcnt lgkmcnt(0)
	s_barrier
	s_mov_b32 s98, 1
	s_mov_b64 s[100:101], s[38:39]
	s_and_saveexec_b64 s[0:1], vcc
	s_xor_b64 s[0:1], exec, s[0:1]
	s_cbranch_execz .LBB0_939
	v_lshl_add_u32 v1, v80, 2, 0
	v_add_u32_e32 v1, 0xca00, v1
	ds_read_b32 v0, v1 offset:0
	ds_read2st64_b32 v[4:5], v1 offset0:4 offset1:8
	ds_read2st64_b32 v[6:7], v1 offset0:12 offset1:16
	ds_read2st64_b32 v[8:9], v1 offset0:20 offset1:24
	ds_read2st64_b32 v[10:11], v1 offset0:28 offset1:32
	ds_read2st64_b32 v[12:13], v1 offset0:36 offset1:40
	ds_read2st64_b32 v[14:15], v1 offset0:44 offset1:48
	ds_read2st64_b32 v[16:17], v1 offset0:52 offset1:56
	ds_read_b32 v18, v1 offset:15360
	ds_read2st64_b32 v[20:21], v1 offset0:64 offset1:68
	ds_read2st64_b32 v[22:23], v1 offset0:72 offset1:76
	ds_read2st64_b32 v[24:25], v1 offset0:80 offset1:84
	ds_read2st64_b32 v[26:27], v1 offset0:88 offset1:92
	ds_read2st64_b32 v[28:29], v1 offset0:96 offset1:100
	ds_read2st64_b32 v[30:31], v1 offset0:104 offset1:108
	ds_read2st64_b32 v[32:33], v1 offset0:112 offset1:116
	ds_read2st64_b32 v[34:35], v1 offset0:120 offset1:124
	ds_read2st64_b32 v[36:37], v1 offset0:128 offset1:132
	ds_read2st64_b32 v[38:39], v1 offset0:136 offset1:140
	ds_read2st64_b32 v[40:41], v1 offset0:144 offset1:148
	ds_read2st64_b32 v[42:43], v1 offset0:152 offset1:156
	ds_read2st64_b32 v[44:45], v1 offset0:160 offset1:164
	ds_read2st64_b32 v[46:47], v1 offset0:168 offset1:172
	ds_read2st64_b32 v[48:49], v1 offset0:176 offset1:180
	ds_read2st64_b32 v[50:51], v1 offset0:184 offset1:188
	ds_read2st64_b32 v[52:53], v1 offset0:192 offset1:196
	ds_read2st64_b32 v[54:55], v1 offset0:200 offset1:204
	ds_read2st64_b32 v[56:57], v1 offset0:208 offset1:212
	ds_read2st64_b32 v[58:59], v1 offset0:216 offset1:220
	ds_read2st64_b32 v[60:61], v1 offset0:224 offset1:228
	ds_read2st64_b32 v[62:63], v1 offset0:232 offset1:236
	ds_read2st64_b32 v[64:65], v1 offset0:240 offset1:244
	ds_read2st64_b32 v[2:3], v1 offset0:248 offset1:252
	ds_read_b128 v[136:139], v105 offset:35584
	ds_read_b128 v[140:143], v105 offset:35840
	ds_read_b128 v[144:147], v105 offset:36096
	ds_read_b128 v[148:151], v105 offset:36352
	ds_read_b128 v[152:155], v105 offset:36608
	ds_read_b128 v[156:159], v105 offset:36624
	ds_read_b128 v[160:163], v105 offset:36864
	ds_read_b128 v[164:167], v105 offset:36880
	ds_read_b128 v[168:171], v105 offset:37120
	ds_read_b128 v[172:175], v105 offset:37136
	ds_read_b128 v[176:179], v105 offset:37376
	ds_read_b128 v[180:183], v105 offset:37392
	s_waitcnt lgkmcnt(11)
	v_mul_f32_e32 v66, v136, v0
	v_sub_f32_e32 v4, v4, v66
	ds_read_b128 v[136:139], v105 offset:37632
	s_waitcnt lgkmcnt(11)
	v_mul_f32_e32 v66, v140, v0
	v_mul_f32_e32 v67, v141, v4
	v_sub_f32_e32 v5, v5, v66
	v_sub_f32_e32 v5, v5, v67
	ds_read_b128 v[140:143], v105 offset:37648
	s_waitcnt lgkmcnt(11)
	v_mul_f32_e32 v66, v144, v0
	v_mul_f32_e32 v67, v145, v4
	v_fmac_f32_e32 v66, v146, v5
	v_sub_f32_e32 v6, v6, v66
	v_sub_f32_e32 v6, v6, v67
	ds_read_b128 v[144:147], v105 offset:37664
	s_waitcnt lgkmcnt(11)
	v_mul_f32_e32 v66, v148, v0
	v_mul_f32_e32 v67, v149, v4
	v_fmac_f32_e32 v66, v150, v5
	v_fmac_f32_e32 v67, v151, v6
	v_sub_f32_e32 v7, v7, v66
	v_sub_f32_e32 v7, v7, v67
	ds_read_b128 v[148:151], v105 offset:37888
	s_waitcnt lgkmcnt(11)
	v_mul_f32_e32 v66, v152, v0
	v_mul_f32_e32 v67, v153, v4
	v_fmac_f32_e32 v66, v154, v5
	v_fmac_f32_e32 v67, v155, v6
	ds_read_b128 v[152:155], v105 offset:37904
	s_waitcnt lgkmcnt(11)
	v_fmac_f32_e32 v66, v156, v7
	v_sub_f32_e32 v8, v8, v66
	v_sub_f32_e32 v8, v8, v67
	ds_read_b128 v[156:159], v105 offset:37920
	s_waitcnt lgkmcnt(11)
	v_mul_f32_e32 v66, v160, v0
	v_mul_f32_e32 v67, v161, v4
	v_fmac_f32_e32 v66, v162, v5
	v_fmac_f32_e32 v67, v163, v6
	ds_read_b128 v[160:163], v105 offset:38144
	s_waitcnt lgkmcnt(11)
	v_fmac_f32_e32 v66, v164, v7
	v_fmac_f32_e32 v67, v165, v8
	v_sub_f32_e32 v9, v9, v66
	v_sub_f32_e32 v9, v9, v67
	ds_read_b128 v[164:167], v105 offset:38160
	s_waitcnt lgkmcnt(11)
	v_mul_f32_e32 v66, v168, v0
	v_mul_f32_e32 v67, v169, v4
	v_fmac_f32_e32 v66, v170, v5
	v_fmac_f32_e32 v67, v171, v6
	ds_read_b128 v[168:171], v105 offset:38176
	s_waitcnt lgkmcnt(11)
	v_fmac_f32_e32 v66, v172, v7
	v_fmac_f32_e32 v67, v173, v8
	v_fmac_f32_e32 v66, v174, v9
	v_sub_f32_e32 v10, v10, v66
	v_sub_f32_e32 v10, v10, v67
	ds_read_b128 v[172:175], v105 offset:38400
	s_waitcnt lgkmcnt(11)
	v_mul_f32_e32 v66, v176, v0
	v_mul_f32_e32 v67, v177, v4
	v_fmac_f32_e32 v66, v178, v5
	v_fmac_f32_e32 v67, v179, v6
	ds_read_b128 v[176:179], v105 offset:38416
	s_waitcnt lgkmcnt(11)
	v_fmac_f32_e32 v66, v180, v7
	v_fmac_f32_e32 v67, v181, v8
	v_fmac_f32_e32 v66, v182, v9
	v_fmac_f32_e32 v67, v183, v10
	v_sub_f32_e32 v11, v11, v66
	v_sub_f32_e32 v11, v11, v67
	ds_read_b128 v[180:183], v105 offset:38432
	s_waitcnt lgkmcnt(11)
	v_mul_f32_e32 v66, v136, v0
	v_mul_f32_e32 v67, v137, v4
	v_fmac_f32_e32 v66, v138, v5
	v_fmac_f32_e32 v67, v139, v6
	ds_read_b128 v[136:139], v105 offset:38656
	s_waitcnt lgkmcnt(11)
	v_fmac_f32_e32 v66, v140, v7
	v_fmac_f32_e32 v67, v141, v8
	v_fmac_f32_e32 v66, v142, v9
	v_fmac_f32_e32 v67, v143, v10
	ds_read_b128 v[140:143], v105 offset:38672
	s_waitcnt lgkmcnt(11)
	v_fmac_f32_e32 v66, v144, v11
	v_sub_f32_e32 v12, v12, v66
	v_sub_f32_e32 v12, v12, v67
	ds_read_b128 v[144:147], v105 offset:38688
	s_waitcnt lgkmcnt(11)
	v_mul_f32_e32 v66, v148, v0
	v_mul_f32_e32 v67, v149, v4
	v_fmac_f32_e32 v66, v150, v5
	v_fmac_f32_e32 v67, v151, v6
	ds_read_b128 v[148:151], v105 offset:38704
	s_waitcnt lgkmcnt(11)
	v_fmac_f32_e32 v66, v152, v7
	v_fmac_f32_e32 v67, v153, v8
	v_fmac_f32_e32 v66, v154, v9
	v_fmac_f32_e32 v67, v155, v10
	ds_read_b128 v[152:155], v105 offset:38912
	s_waitcnt lgkmcnt(11)
	v_fmac_f32_e32 v66, v156, v11
	v_fmac_f32_e32 v67, v157, v12
	v_sub_f32_e32 v13, v13, v66
	v_sub_f32_e32 v13, v13, v67
	ds_read_b128 v[156:159], v105 offset:38928
	s_waitcnt lgkmcnt(11)
	v_mul_f32_e32 v66, v160, v0
	v_mul_f32_e32 v67, v161, v4
	v_fmac_f32_e32 v66, v162, v5
	v_fmac_f32_e32 v67, v163, v6
	ds_read_b128 v[160:163], v105 offset:38944
	s_waitcnt lgkmcnt(11)
	v_fmac_f32_e32 v66, v164, v7
	v_fmac_f32_e32 v67, v165, v8
	v_fmac_f32_e32 v66, v166, v9
	v_fmac_f32_e32 v67, v167, v10
	ds_read_b128 v[164:167], v105 offset:38960
	s_waitcnt lgkmcnt(11)
	v_fmac_f32_e32 v66, v168, v11
	v_fmac_f32_e32 v67, v169, v12
	v_fmac_f32_e32 v66, v170, v13
	v_sub_f32_e32 v14, v14, v66
	v_sub_f32_e32 v14, v14, v67
	ds_read_b128 v[168:171], v105 offset:39168
	s_waitcnt lgkmcnt(11)
	v_mul_f32_e32 v66, v172, v0
	v_mul_f32_e32 v67, v173, v4
	v_fmac_f32_e32 v66, v174, v5
	v_fmac_f32_e32 v67, v175, v6
	ds_read_b128 v[172:175], v105 offset:39184
	s_waitcnt lgkmcnt(11)
	v_fmac_f32_e32 v66, v176, v7
	v_fmac_f32_e32 v67, v177, v8
	v_fmac_f32_e32 v66, v178, v9
	v_fmac_f32_e32 v67, v179, v10
	ds_read_b128 v[176:179], v105 offset:39200
	s_waitcnt lgkmcnt(11)
	v_fmac_f32_e32 v66, v180, v11
	v_fmac_f32_e32 v67, v181, v12
	v_fmac_f32_e32 v66, v182, v13
	v_fmac_f32_e32 v67, v183, v14
	v_sub_f32_e32 v15, v15, v66
	v_sub_f32_e32 v15, v15, v67
	ds_read_b128 v[180:183], v105 offset:39216
	s_waitcnt lgkmcnt(11)
	v_mul_f32_e32 v66, v136, v0
	v_mul_f32_e32 v67, v137, v4
	v_fmac_f32_e32 v66, v138, v5
	v_fmac_f32_e32 v67, v139, v6
	ds_read_b128 v[136:139], v105 offset:39424
	s_waitcnt lgkmcnt(11)
	v_fmac_f32_e32 v66, v140, v7
	v_fmac_f32_e32 v67, v141, v8
	v_fmac_f32_e32 v66, v142, v9
	v_fmac_f32_e32 v67, v143, v10
	ds_read_b128 v[140:143], v105 offset:39440
	s_waitcnt lgkmcnt(11)
	v_fmac_f32_e32 v66, v144, v11
	v_fmac_f32_e32 v67, v145, v12
	v_fmac_f32_e32 v66, v146, v13
	v_fmac_f32_e32 v67, v147, v14
	ds_read_b128 v[144:147], v105 offset:39456
	s_waitcnt lgkmcnt(11)
	v_fmac_f32_e32 v66, v148, v15
	v_sub_f32_e32 v16, v16, v66
	v_sub_f32_e32 v16, v16, v67
	ds_read_b128 v[148:151], v105 offset:39472
	s_waitcnt lgkmcnt(11)
	v_mul_f32_e32 v66, v152, v0
	v_mul_f32_e32 v67, v153, v4
	v_fmac_f32_e32 v66, v154, v5
	v_fmac_f32_e32 v67, v155, v6
	ds_read_b128 v[152:155], v105 offset:39680
	s_waitcnt lgkmcnt(11)
	v_fmac_f32_e32 v66, v156, v7
	v_fmac_f32_e32 v67, v157, v8
	v_fmac_f32_e32 v66, v158, v9
	v_fmac_f32_e32 v67, v159, v10
	ds_read_b128 v[156:159], v105 offset:39696
	s_waitcnt lgkmcnt(11)
	v_fmac_f32_e32 v66, v160, v11
	v_fmac_f32_e32 v67, v161, v12
	v_fmac_f32_e32 v66, v162, v13
	v_fmac_f32_e32 v67, v163, v14
	ds_read_b128 v[160:163], v105 offset:39712
	s_waitcnt lgkmcnt(11)
	v_fmac_f32_e32 v66, v164, v15
	v_fmac_f32_e32 v67, v165, v16
	v_sub_f32_e32 v17, v17, v66
	v_sub_f32_e32 v17, v17, v67
	ds_read_b128 v[164:167], v105 offset:39728
	s_waitcnt lgkmcnt(11)
	v_mul_f32_e32 v66, v168, v0
	v_mul_f32_e32 v67, v169, v4
	v_fmac_f32_e32 v66, v170, v5
	v_fmac_f32_e32 v67, v171, v6
	ds_read_b128 v[168:171], v105 offset:39744
	s_waitcnt lgkmcnt(11)
	v_fmac_f32_e32 v66, v172, v7
	v_fmac_f32_e32 v67, v173, v8
	v_fmac_f32_e32 v66, v174, v9
	v_fmac_f32_e32 v67, v175, v10
	ds_read_b128 v[172:175], v105 offset:39936
	s_waitcnt lgkmcnt(11)
	v_fmac_f32_e32 v66, v176, v11
	v_fmac_f32_e32 v67, v177, v12
	v_fmac_f32_e32 v66, v178, v13
	v_fmac_f32_e32 v67, v179, v14
	ds_read_b128 v[176:179], v105 offset:39952
	s_waitcnt lgkmcnt(11)
	v_fmac_f32_e32 v66, v180, v15
	v_fmac_f32_e32 v67, v181, v16
	v_fmac_f32_e32 v66, v182, v17
	v_sub_f32_e32 v18, v18, v66
	v_sub_f32_e32 v18, v18, v67
	ds_read_b128 v[180:183], v105 offset:39968
	s_waitcnt lgkmcnt(11)
	v_mul_f32_e32 v66, v136, v0
	v_mul_f32_e32 v67, v137, v4
	v_fmac_f32_e32 v66, v138, v5
	v_fmac_f32_e32 v67, v139, v6
	ds_read_b128 v[136:139], v105 offset:39984
	s_waitcnt lgkmcnt(11)
	v_fmac_f32_e32 v66, v140, v7
	v_fmac_f32_e32 v67, v141, v8
	v_fmac_f32_e32 v66, v142, v9
	v_fmac_f32_e32 v67, v143, v10
	ds_read_b128 v[140:143], v105 offset:40000
	s_waitcnt lgkmcnt(11)
	v_fmac_f32_e32 v66, v144, v11
	v_fmac_f32_e32 v67, v145, v12
	v_fmac_f32_e32 v66, v146, v13
	v_fmac_f32_e32 v67, v147, v14
	ds_read_b128 v[144:147], v105 offset:40192
	s_waitcnt lgkmcnt(11)
	v_fmac_f32_e32 v66, v148, v15
	v_fmac_f32_e32 v67, v149, v16
	v_fmac_f32_e32 v66, v150, v17
	v_fmac_f32_e32 v67, v151, v18
	v_sub_f32_e32 v20, v20, v66
	v_sub_f32_e32 v20, v20, v67
	ds_read_b128 v[148:151], v105 offset:40208
	s_waitcnt lgkmcnt(11)
	v_mul_f32_e32 v66, v152, v0
	v_mul_f32_e32 v67, v153, v4
	v_fmac_f32_e32 v66, v154, v5
	v_fmac_f32_e32 v67, v155, v6
	ds_read_b128 v[152:155], v105 offset:40224
	s_waitcnt lgkmcnt(11)
	v_fmac_f32_e32 v66, v156, v7
	v_fmac_f32_e32 v67, v157, v8
	v_fmac_f32_e32 v66, v158, v9
	v_fmac_f32_e32 v67, v159, v10
	ds_read_b128 v[156:159], v105 offset:40240
	s_waitcnt lgkmcnt(11)
	v_fmac_f32_e32 v66, v160, v11
	v_fmac_f32_e32 v67, v161, v12
	v_fmac_f32_e32 v66, v162, v13
	v_fmac_f32_e32 v67, v163, v14
	ds_read_b128 v[160:163], v105 offset:40256
	s_waitcnt lgkmcnt(11)
	v_fmac_f32_e32 v66, v164, v15
	v_fmac_f32_e32 v67, v165, v16
	v_fmac_f32_e32 v66, v166, v17
	v_fmac_f32_e32 v67, v167, v18
	ds_read_b128 v[164:167], v105 offset:40448
	s_waitcnt lgkmcnt(11)
	v_fmac_f32_e32 v66, v168, v20
	v_sub_f32_e32 v21, v21, v66
	v_sub_f32_e32 v21, v21, v67
	ds_read_b128 v[168:171], v105 offset:40464
	s_waitcnt lgkmcnt(11)
	v_mul_f32_e32 v66, v172, v0
	v_mul_f32_e32 v67, v173, v4
	v_fmac_f32_e32 v66, v174, v5
	v_fmac_f32_e32 v67, v175, v6
	ds_read_b128 v[172:175], v105 offset:40480
	s_waitcnt lgkmcnt(11)
	v_fmac_f32_e32 v66, v176, v7
	v_fmac_f32_e32 v67, v177, v8
	v_fmac_f32_e32 v66, v178, v9
	v_fmac_f32_e32 v67, v179, v10
	ds_read_b128 v[176:179], v105 offset:40496
	s_waitcnt lgkmcnt(11)
	v_fmac_f32_e32 v66, v180, v11
	v_fmac_f32_e32 v67, v181, v12
	v_fmac_f32_e32 v66, v182, v13
	v_fmac_f32_e32 v67, v183, v14
	ds_read_b128 v[180:183], v105 offset:40512
	s_waitcnt lgkmcnt(11)
	v_fmac_f32_e32 v66, v136, v15
	v_fmac_f32_e32 v67, v137, v16
	v_fmac_f32_e32 v66, v138, v17
	v_fmac_f32_e32 v67, v139, v18
	ds_read_b128 v[136:139], v105 offset:40704
	s_waitcnt lgkmcnt(11)
	v_fmac_f32_e32 v66, v140, v20
	v_fmac_f32_e32 v67, v141, v21
	v_sub_f32_e32 v22, v22, v66
	v_sub_f32_e32 v22, v22, v67
	ds_read_b128 v[140:143], v105 offset:40720
	s_waitcnt lgkmcnt(11)
	v_mul_f32_e32 v66, v144, v0
	v_mul_f32_e32 v67, v145, v4
	v_fmac_f32_e32 v66, v146, v5
	v_fmac_f32_e32 v67, v147, v6
	ds_read_b128 v[144:147], v105 offset:40736
	s_waitcnt lgkmcnt(11)
	v_fmac_f32_e32 v66, v148, v7
	v_fmac_f32_e32 v67, v149, v8
	v_fmac_f32_e32 v66, v150, v9
	v_fmac_f32_e32 v67, v151, v10
	ds_read_b128 v[148:151], v105 offset:40752
	s_waitcnt lgkmcnt(11)
	v_fmac_f32_e32 v66, v152, v11
	v_fmac_f32_e32 v67, v153, v12
	v_fmac_f32_e32 v66, v154, v13
	v_fmac_f32_e32 v67, v155, v14
	ds_read_b128 v[152:155], v105 offset:40768
	s_waitcnt lgkmcnt(11)
	v_fmac_f32_e32 v66, v156, v15
	v_fmac_f32_e32 v67, v157, v16
	v_fmac_f32_e32 v66, v158, v17
	v_fmac_f32_e32 v67, v159, v18
	ds_read_b128 v[156:159], v105 offset:40784
	s_waitcnt lgkmcnt(11)
	v_fmac_f32_e32 v66, v160, v20
	v_fmac_f32_e32 v67, v161, v21
	v_fmac_f32_e32 v66, v162, v22
	v_sub_f32_e32 v23, v23, v66
	v_sub_f32_e32 v23, v23, v67
	ds_read_b128 v[160:163], v105 offset:40960
	s_waitcnt lgkmcnt(11)
	v_mul_f32_e32 v66, v164, v0
	v_mul_f32_e32 v67, v165, v4
	v_fmac_f32_e32 v66, v166, v5
	v_fmac_f32_e32 v67, v167, v6
	ds_read_b128 v[164:167], v105 offset:40976
	s_waitcnt lgkmcnt(11)
	v_fmac_f32_e32 v66, v168, v7
	v_fmac_f32_e32 v67, v169, v8
	v_fmac_f32_e32 v66, v170, v9
	v_fmac_f32_e32 v67, v171, v10
	ds_read_b128 v[168:171], v105 offset:40992
	s_waitcnt lgkmcnt(11)
	v_fmac_f32_e32 v66, v172, v11
	v_fmac_f32_e32 v67, v173, v12
	v_fmac_f32_e32 v66, v174, v13
	v_fmac_f32_e32 v67, v175, v14
	ds_read_b128 v[172:175], v105 offset:41008
	s_waitcnt lgkmcnt(11)
	v_fmac_f32_e32 v66, v176, v15
	v_fmac_f32_e32 v67, v177, v16
	v_fmac_f32_e32 v66, v178, v17
	v_fmac_f32_e32 v67, v179, v18
	ds_read_b128 v[176:179], v105 offset:41024
	s_waitcnt lgkmcnt(11)
	v_fmac_f32_e32 v66, v180, v20
	v_fmac_f32_e32 v67, v181, v21
	v_fmac_f32_e32 v66, v182, v22
	v_fmac_f32_e32 v67, v183, v23
	v_sub_f32_e32 v24, v24, v66
	v_sub_f32_e32 v24, v24, v67
	ds_read_b128 v[180:183], v105 offset:41040
	s_waitcnt lgkmcnt(11)
	v_mul_f32_e32 v66, v136, v0
	v_mul_f32_e32 v67, v137, v4
	v_fmac_f32_e32 v66, v138, v5
	v_fmac_f32_e32 v67, v139, v6
	ds_read_b128 v[136:139], v105 offset:41216
	s_waitcnt lgkmcnt(11)
	v_fmac_f32_e32 v66, v140, v7
	v_fmac_f32_e32 v67, v141, v8
	v_fmac_f32_e32 v66, v142, v9
	v_fmac_f32_e32 v67, v143, v10
	ds_read_b128 v[140:143], v105 offset:41232
	s_waitcnt lgkmcnt(11)
	v_fmac_f32_e32 v66, v144, v11
	v_fmac_f32_e32 v67, v145, v12
	v_fmac_f32_e32 v66, v146, v13
	v_fmac_f32_e32 v67, v147, v14
	ds_read_b128 v[144:147], v105 offset:41248
	s_waitcnt lgkmcnt(11)
	v_fmac_f32_e32 v66, v148, v15
	v_fmac_f32_e32 v67, v149, v16
	v_fmac_f32_e32 v66, v150, v17
	v_fmac_f32_e32 v67, v151, v18
	ds_read_b128 v[148:151], v105 offset:41264
	s_waitcnt lgkmcnt(11)
	v_fmac_f32_e32 v66, v152, v20
	v_fmac_f32_e32 v67, v153, v21
	v_fmac_f32_e32 v66, v154, v22
	v_fmac_f32_e32 v67, v155, v23
	ds_read_b128 v[152:155], v105 offset:41280
	s_waitcnt lgkmcnt(11)
	v_fmac_f32_e32 v66, v156, v24
	v_sub_f32_e32 v25, v25, v66
	v_sub_f32_e32 v25, v25, v67
	ds_read_b128 v[156:159], v105 offset:41296
	s_waitcnt lgkmcnt(11)
	v_mul_f32_e32 v66, v160, v0
	v_mul_f32_e32 v67, v161, v4
	v_fmac_f32_e32 v66, v162, v5
	v_fmac_f32_e32 v67, v163, v6
	ds_read_b128 v[160:163], v105 offset:41472
	s_waitcnt lgkmcnt(11)
	v_fmac_f32_e32 v66, v164, v7
	v_fmac_f32_e32 v67, v165, v8
	v_fmac_f32_e32 v66, v166, v9
	v_fmac_f32_e32 v67, v167, v10
	ds_read_b128 v[164:167], v105 offset:41488
	s_waitcnt lgkmcnt(11)
	v_fmac_f32_e32 v66, v168, v11
	v_fmac_f32_e32 v67, v169, v12
	v_fmac_f32_e32 v66, v170, v13
	v_fmac_f32_e32 v67, v171, v14
	ds_read_b128 v[168:171], v105 offset:41504
	s_waitcnt lgkmcnt(11)
	v_fmac_f32_e32 v66, v172, v15
	v_fmac_f32_e32 v67, v173, v16
	v_fmac_f32_e32 v66, v174, v17
	v_fmac_f32_e32 v67, v175, v18
	ds_read_b128 v[172:175], v105 offset:41520
	s_waitcnt lgkmcnt(11)
	v_fmac_f32_e32 v66, v176, v20
	v_fmac_f32_e32 v67, v177, v21
	v_fmac_f32_e32 v66, v178, v22
	v_fmac_f32_e32 v67, v179, v23
	ds_read_b128 v[176:179], v105 offset:41536
	s_waitcnt lgkmcnt(11)
	v_fmac_f32_e32 v66, v180, v24
	v_fmac_f32_e32 v67, v181, v25
	v_sub_f32_e32 v26, v26, v66
	v_sub_f32_e32 v26, v26, v67
	ds_read_b128 v[180:183], v105 offset:41552
	s_waitcnt lgkmcnt(11)
	v_mul_f32_e32 v66, v136, v0
	v_mul_f32_e32 v67, v137, v4
	v_fmac_f32_e32 v66, v138, v5
	v_fmac_f32_e32 v67, v139, v6
	ds_read_b128 v[136:139], v105 offset:41728
	s_waitcnt lgkmcnt(11)
	v_fmac_f32_e32 v66, v140, v7
	v_fmac_f32_e32 v67, v141, v8
	v_fmac_f32_e32 v66, v142, v9
	v_fmac_f32_e32 v67, v143, v10
	ds_read_b128 v[140:143], v105 offset:41744
	s_waitcnt lgkmcnt(11)
	v_fmac_f32_e32 v66, v144, v11
	v_fmac_f32_e32 v67, v145, v12
	v_fmac_f32_e32 v66, v146, v13
	v_fmac_f32_e32 v67, v147, v14
	ds_read_b128 v[144:147], v105 offset:41760
	s_waitcnt lgkmcnt(11)
	v_fmac_f32_e32 v66, v148, v15
	v_fmac_f32_e32 v67, v149, v16
	v_fmac_f32_e32 v66, v150, v17
	v_fmac_f32_e32 v67, v151, v18
	ds_read_b128 v[148:151], v105 offset:41776
	s_waitcnt lgkmcnt(11)
	v_fmac_f32_e32 v66, v152, v20
	v_fmac_f32_e32 v67, v153, v21
	v_fmac_f32_e32 v66, v154, v22
	v_fmac_f32_e32 v67, v155, v23
	ds_read_b128 v[152:155], v105 offset:41792
	s_waitcnt lgkmcnt(11)
	v_fmac_f32_e32 v66, v156, v24
	v_fmac_f32_e32 v67, v157, v25
	v_fmac_f32_e32 v66, v158, v26
	v_sub_f32_e32 v27, v27, v66
	v_sub_f32_e32 v27, v27, v67
	ds_read_b128 v[156:159], v105 offset:41808
	s_waitcnt lgkmcnt(11)
	v_mul_f32_e32 v66, v160, v0
	v_mul_f32_e32 v67, v161, v4
	v_fmac_f32_e32 v66, v162, v5
	v_fmac_f32_e32 v67, v163, v6
	ds_read_b128 v[160:163], v105 offset:41824
	s_waitcnt lgkmcnt(11)
	v_fmac_f32_e32 v66, v164, v7
	v_fmac_f32_e32 v67, v165, v8
	v_fmac_f32_e32 v66, v166, v9
	v_fmac_f32_e32 v67, v167, v10
	ds_read_b128 v[164:167], v105 offset:41984
	s_waitcnt lgkmcnt(11)
	v_fmac_f32_e32 v66, v168, v11
	v_fmac_f32_e32 v67, v169, v12
	v_fmac_f32_e32 v66, v170, v13
	v_fmac_f32_e32 v67, v171, v14
	ds_read_b128 v[168:171], v105 offset:42000
	s_waitcnt lgkmcnt(11)
	v_fmac_f32_e32 v66, v172, v15
	v_fmac_f32_e32 v67, v173, v16
	v_fmac_f32_e32 v66, v174, v17
	v_fmac_f32_e32 v67, v175, v18
	ds_read_b128 v[172:175], v105 offset:42016
	s_waitcnt lgkmcnt(11)
	v_fmac_f32_e32 v66, v176, v20
	v_fmac_f32_e32 v67, v177, v21
	v_fmac_f32_e32 v66, v178, v22
	v_fmac_f32_e32 v67, v179, v23
	ds_read_b128 v[176:179], v105 offset:42032
	s_waitcnt lgkmcnt(11)
	v_fmac_f32_e32 v66, v180, v24
	v_fmac_f32_e32 v67, v181, v25
	v_fmac_f32_e32 v66, v182, v26
	v_fmac_f32_e32 v67, v183, v27
	v_sub_f32_e32 v28, v28, v66
	v_sub_f32_e32 v28, v28, v67
	ds_read_b128 v[180:183], v105 offset:42048
	s_waitcnt lgkmcnt(11)
	v_mul_f32_e32 v66, v136, v0
	v_mul_f32_e32 v67, v137, v4
	v_fmac_f32_e32 v66, v138, v5
	v_fmac_f32_e32 v67, v139, v6
	ds_read_b128 v[136:139], v105 offset:42064
	s_waitcnt lgkmcnt(11)
	v_fmac_f32_e32 v66, v140, v7
	v_fmac_f32_e32 v67, v141, v8
	v_fmac_f32_e32 v66, v142, v9
	v_fmac_f32_e32 v67, v143, v10
	ds_read_b128 v[140:143], v105 offset:42080
	s_waitcnt lgkmcnt(11)
	v_fmac_f32_e32 v66, v144, v11
	v_fmac_f32_e32 v67, v145, v12
	v_fmac_f32_e32 v66, v146, v13
	v_fmac_f32_e32 v67, v147, v14
	ds_read_b128 v[144:147], v105 offset:42240
	s_waitcnt lgkmcnt(11)
	v_fmac_f32_e32 v66, v148, v15
	v_fmac_f32_e32 v67, v149, v16
	v_fmac_f32_e32 v66, v150, v17
	v_fmac_f32_e32 v67, v151, v18
	ds_read_b128 v[148:151], v105 offset:42256
	s_waitcnt lgkmcnt(11)
	v_fmac_f32_e32 v66, v152, v20
	v_fmac_f32_e32 v67, v153, v21
	v_fmac_f32_e32 v66, v154, v22
	v_fmac_f32_e32 v67, v155, v23
	ds_read_b128 v[152:155], v105 offset:42272
	s_waitcnt lgkmcnt(11)
	v_fmac_f32_e32 v66, v156, v24
	v_fmac_f32_e32 v67, v157, v25
	v_fmac_f32_e32 v66, v158, v26
	v_fmac_f32_e32 v67, v159, v27
	ds_read_b128 v[156:159], v105 offset:42288
	s_waitcnt lgkmcnt(11)
	v_fmac_f32_e32 v66, v160, v28
	v_sub_f32_e32 v29, v29, v66
	v_sub_f32_e32 v29, v29, v67
	ds_read_b128 v[160:163], v105 offset:42304
	s_waitcnt lgkmcnt(11)
	v_mul_f32_e32 v66, v164, v0
	v_mul_f32_e32 v67, v165, v4
	v_fmac_f32_e32 v66, v166, v5
	v_fmac_f32_e32 v67, v167, v6
	ds_read_b128 v[164:167], v105 offset:42320
	s_waitcnt lgkmcnt(11)
	v_fmac_f32_e32 v66, v168, v7
	v_fmac_f32_e32 v67, v169, v8
	v_fmac_f32_e32 v66, v170, v9
	v_fmac_f32_e32 v67, v171, v10
	ds_read_b128 v[168:171], v105 offset:42336
	s_waitcnt lgkmcnt(11)
	v_fmac_f32_e32 v66, v172, v11
	v_fmac_f32_e32 v67, v173, v12
	v_fmac_f32_e32 v66, v174, v13
	v_fmac_f32_e32 v67, v175, v14
	ds_read_b128 v[172:175], v105 offset:42496
	s_waitcnt lgkmcnt(11)
	v_fmac_f32_e32 v66, v176, v15
	v_fmac_f32_e32 v67, v177, v16
	v_fmac_f32_e32 v66, v178, v17
	v_fmac_f32_e32 v67, v179, v18
	ds_read_b128 v[176:179], v105 offset:42512
	s_waitcnt lgkmcnt(11)
	v_fmac_f32_e32 v66, v180, v20
	v_fmac_f32_e32 v67, v181, v21
	v_fmac_f32_e32 v66, v182, v22
	v_fmac_f32_e32 v67, v183, v23
	ds_read_b128 v[180:183], v105 offset:42528
	s_waitcnt lgkmcnt(11)
	v_fmac_f32_e32 v66, v136, v24
	v_fmac_f32_e32 v67, v137, v25
	v_fmac_f32_e32 v66, v138, v26
	v_fmac_f32_e32 v67, v139, v27
	ds_read_b128 v[136:139], v105 offset:42544
	s_waitcnt lgkmcnt(11)
	v_fmac_f32_e32 v66, v140, v28
	v_fmac_f32_e32 v67, v141, v29
	v_sub_f32_e32 v30, v30, v66
	v_sub_f32_e32 v30, v30, v67
	ds_read_b128 v[140:143], v105 offset:42560
	s_waitcnt lgkmcnt(11)
	v_mul_f32_e32 v66, v144, v0
	v_mul_f32_e32 v67, v145, v4
	v_fmac_f32_e32 v66, v146, v5
	v_fmac_f32_e32 v67, v147, v6
	ds_read_b128 v[144:147], v105 offset:42576
	s_waitcnt lgkmcnt(11)
	v_fmac_f32_e32 v66, v148, v7
	v_fmac_f32_e32 v67, v149, v8
	v_fmac_f32_e32 v66, v150, v9
	v_fmac_f32_e32 v67, v151, v10
	ds_read_b128 v[148:151], v105 offset:42592
	s_waitcnt lgkmcnt(11)
	v_fmac_f32_e32 v66, v152, v11
	v_fmac_f32_e32 v67, v153, v12
	v_fmac_f32_e32 v66, v154, v13
	v_fmac_f32_e32 v67, v155, v14
	ds_read_b128 v[152:155], v105 offset:42752
	s_waitcnt lgkmcnt(11)
	v_fmac_f32_e32 v66, v156, v15
	v_fmac_f32_e32 v67, v157, v16
	v_fmac_f32_e32 v66, v158, v17
	v_fmac_f32_e32 v67, v159, v18
	ds_read_b128 v[156:159], v105 offset:42768
	s_waitcnt lgkmcnt(11)
	v_fmac_f32_e32 v66, v160, v20
	v_fmac_f32_e32 v67, v161, v21
	v_fmac_f32_e32 v66, v162, v22
	v_fmac_f32_e32 v67, v163, v23
	ds_read_b128 v[160:163], v105 offset:42784
	s_waitcnt lgkmcnt(11)
	v_fmac_f32_e32 v66, v164, v24
	v_fmac_f32_e32 v67, v165, v25
	v_fmac_f32_e32 v66, v166, v26
	v_fmac_f32_e32 v67, v167, v27
	ds_read_b128 v[164:167], v105 offset:42800
	s_waitcnt lgkmcnt(11)
	v_fmac_f32_e32 v66, v168, v28
	v_fmac_f32_e32 v67, v169, v29
	v_fmac_f32_e32 v66, v170, v30
	v_sub_f32_e32 v31, v31, v66
	v_sub_f32_e32 v31, v31, v67
	ds_read_b128 v[168:171], v105 offset:42816
	s_waitcnt lgkmcnt(11)
	v_mul_f32_e32 v66, v172, v0
	v_mul_f32_e32 v67, v173, v4
	v_fmac_f32_e32 v66, v174, v5
	v_fmac_f32_e32 v67, v175, v6
	ds_read_b128 v[172:175], v105 offset:42832
	s_waitcnt lgkmcnt(11)
	v_fmac_f32_e32 v66, v176, v7
	v_fmac_f32_e32 v67, v177, v8
	v_fmac_f32_e32 v66, v178, v9
	v_fmac_f32_e32 v67, v179, v10
	ds_read_b128 v[176:179], v105 offset:42848
	s_waitcnt lgkmcnt(11)
	v_fmac_f32_e32 v66, v180, v11
	v_fmac_f32_e32 v67, v181, v12
	v_fmac_f32_e32 v66, v182, v13
	v_fmac_f32_e32 v67, v183, v14
	ds_read_b128 v[180:183], v105 offset:42864
	s_waitcnt lgkmcnt(11)
	v_fmac_f32_e32 v66, v136, v15
	v_fmac_f32_e32 v67, v137, v16
	v_fmac_f32_e32 v66, v138, v17
	v_fmac_f32_e32 v67, v139, v18
	ds_read_b128 v[136:139], v105 offset:43008
	s_waitcnt lgkmcnt(11)
	v_fmac_f32_e32 v66, v140, v20
	v_fmac_f32_e32 v67, v141, v21
	v_fmac_f32_e32 v66, v142, v22
	v_fmac_f32_e32 v67, v143, v23
	ds_read_b128 v[140:143], v105 offset:43024
	s_waitcnt lgkmcnt(11)
	v_fmac_f32_e32 v66, v144, v24
	v_fmac_f32_e32 v67, v145, v25
	v_fmac_f32_e32 v66, v146, v26
	v_fmac_f32_e32 v67, v147, v27
	ds_read_b128 v[144:147], v105 offset:43040
	s_waitcnt lgkmcnt(11)
	v_fmac_f32_e32 v66, v148, v28
	v_fmac_f32_e32 v67, v149, v29
	v_fmac_f32_e32 v66, v150, v30
	v_fmac_f32_e32 v67, v151, v31
	v_sub_f32_e32 v32, v32, v66
	v_sub_f32_e32 v32, v32, v67
	ds_read_b128 v[148:151], v105 offset:43056
	s_waitcnt lgkmcnt(11)
	v_mul_f32_e32 v66, v152, v0
	v_mul_f32_e32 v67, v153, v4
	v_fmac_f32_e32 v66, v154, v5
	v_fmac_f32_e32 v67, v155, v6
	ds_read_b128 v[152:155], v105 offset:43072
	s_waitcnt lgkmcnt(11)
	v_fmac_f32_e32 v66, v156, v7
	v_fmac_f32_e32 v67, v157, v8
	v_fmac_f32_e32 v66, v158, v9
	v_fmac_f32_e32 v67, v159, v10
	ds_read_b128 v[156:159], v105 offset:43088
	s_waitcnt lgkmcnt(11)
	v_fmac_f32_e32 v66, v160, v11
	v_fmac_f32_e32 v67, v161, v12
	v_fmac_f32_e32 v66, v162, v13
	v_fmac_f32_e32 v67, v163, v14
	ds_read_b128 v[160:163], v105 offset:43104
	s_waitcnt lgkmcnt(11)
	v_fmac_f32_e32 v66, v164, v15
	v_fmac_f32_e32 v67, v165, v16
	v_fmac_f32_e32 v66, v166, v17
	v_fmac_f32_e32 v67, v167, v18
	ds_read_b128 v[164:167], v105 offset:43120
	s_waitcnt lgkmcnt(11)
	v_fmac_f32_e32 v66, v168, v20
	v_fmac_f32_e32 v67, v169, v21
	v_fmac_f32_e32 v66, v170, v22
	v_fmac_f32_e32 v67, v171, v23
	ds_read_b128 v[168:171], v105 offset:43264
	s_waitcnt lgkmcnt(11)
	v_fmac_f32_e32 v66, v172, v24
	v_fmac_f32_e32 v67, v173, v25
	v_fmac_f32_e32 v66, v174, v26
	v_fmac_f32_e32 v67, v175, v27
	ds_read_b128 v[172:175], v105 offset:43280
	s_waitcnt lgkmcnt(11)
	v_fmac_f32_e32 v66, v176, v28
	v_fmac_f32_e32 v67, v177, v29
	v_fmac_f32_e32 v66, v178, v30
	v_fmac_f32_e32 v67, v179, v31
	ds_read_b128 v[176:179], v105 offset:43296
	s_waitcnt lgkmcnt(11)
	v_fmac_f32_e32 v66, v180, v32
	v_sub_f32_e32 v33, v33, v66
	v_sub_f32_e32 v33, v33, v67
	ds_read_b128 v[180:183], v105 offset:43312
	s_waitcnt lgkmcnt(11)
	v_mul_f32_e32 v66, v136, v0
	v_mul_f32_e32 v67, v137, v4
	v_fmac_f32_e32 v66, v138, v5
	v_fmac_f32_e32 v67, v139, v6
	ds_read_b128 v[136:139], v105 offset:43328
	s_waitcnt lgkmcnt(11)
	v_fmac_f32_e32 v66, v140, v7
	v_fmac_f32_e32 v67, v141, v8
	v_fmac_f32_e32 v66, v142, v9
	v_fmac_f32_e32 v67, v143, v10
	ds_read_b128 v[140:143], v105 offset:43344
	s_waitcnt lgkmcnt(11)
	v_fmac_f32_e32 v66, v144, v11
	v_fmac_f32_e32 v67, v145, v12
	v_fmac_f32_e32 v66, v146, v13
	v_fmac_f32_e32 v67, v147, v14
	ds_read_b128 v[144:147], v105 offset:43360
	s_waitcnt lgkmcnt(11)
	v_fmac_f32_e32 v66, v148, v15
	v_fmac_f32_e32 v67, v149, v16
	v_fmac_f32_e32 v66, v150, v17
	v_fmac_f32_e32 v67, v151, v18
	ds_read_b128 v[148:151], v105 offset:43376
	s_waitcnt lgkmcnt(11)
	v_fmac_f32_e32 v66, v152, v20
	v_fmac_f32_e32 v67, v153, v21
	v_fmac_f32_e32 v66, v154, v22
	v_fmac_f32_e32 v67, v155, v23
	ds_read_b128 v[152:155], v105 offset:43520
	s_waitcnt lgkmcnt(11)
	v_fmac_f32_e32 v66, v156, v24
	v_fmac_f32_e32 v67, v157, v25
	v_fmac_f32_e32 v66, v158, v26
	v_fmac_f32_e32 v67, v159, v27
	ds_read_b128 v[156:159], v105 offset:43536
	s_waitcnt lgkmcnt(11)
	v_fmac_f32_e32 v66, v160, v28
	v_fmac_f32_e32 v67, v161, v29
	v_fmac_f32_e32 v66, v162, v30
	v_fmac_f32_e32 v67, v163, v31
	ds_read_b128 v[160:163], v105 offset:43552
	s_waitcnt lgkmcnt(11)
	v_fmac_f32_e32 v66, v164, v32
	v_fmac_f32_e32 v67, v165, v33
	v_sub_f32_e32 v34, v34, v66
	v_sub_f32_e32 v34, v34, v67
	ds_read_b128 v[164:167], v105 offset:43568
	s_waitcnt lgkmcnt(11)
	v_mul_f32_e32 v66, v168, v0
	v_mul_f32_e32 v67, v169, v4
	v_fmac_f32_e32 v66, v170, v5
	v_fmac_f32_e32 v67, v171, v6
	ds_read_b128 v[168:171], v105 offset:43584
	s_waitcnt lgkmcnt(11)
	v_fmac_f32_e32 v66, v172, v7
	v_fmac_f32_e32 v67, v173, v8
	v_fmac_f32_e32 v66, v174, v9
	v_fmac_f32_e32 v67, v175, v10
	ds_read_b128 v[172:175], v105 offset:43600
	s_waitcnt lgkmcnt(11)
	v_fmac_f32_e32 v66, v176, v11
	v_fmac_f32_e32 v67, v177, v12
	v_fmac_f32_e32 v66, v178, v13
	v_fmac_f32_e32 v67, v179, v14
	ds_read_b128 v[176:179], v105 offset:43616
	s_waitcnt lgkmcnt(11)
	v_fmac_f32_e32 v66, v180, v15
	v_fmac_f32_e32 v67, v181, v16
	v_fmac_f32_e32 v66, v182, v17
	v_fmac_f32_e32 v67, v183, v18
	ds_read_b128 v[180:183], v105 offset:43632
	s_waitcnt lgkmcnt(11)
	v_fmac_f32_e32 v66, v136, v20
	v_fmac_f32_e32 v67, v137, v21
	v_fmac_f32_e32 v66, v138, v22
	v_fmac_f32_e32 v67, v139, v23
	ds_read_b128 v[136:139], v105 offset:43776
	s_waitcnt lgkmcnt(11)
	v_fmac_f32_e32 v66, v140, v24
	v_fmac_f32_e32 v67, v141, v25
	v_fmac_f32_e32 v66, v142, v26
	v_fmac_f32_e32 v67, v143, v27
	ds_read_b128 v[140:143], v105 offset:43792
	s_waitcnt lgkmcnt(11)
	v_fmac_f32_e32 v66, v144, v28
	v_fmac_f32_e32 v67, v145, v29
	v_fmac_f32_e32 v66, v146, v30
	v_fmac_f32_e32 v67, v147, v31
	ds_read_b128 v[144:147], v105 offset:43808
	s_waitcnt lgkmcnt(11)
	v_fmac_f32_e32 v66, v148, v32
	v_fmac_f32_e32 v67, v149, v33
	v_fmac_f32_e32 v66, v150, v34
	v_sub_f32_e32 v35, v35, v66
	v_sub_f32_e32 v35, v35, v67
	ds_read_b128 v[148:151], v105 offset:43824
	s_waitcnt lgkmcnt(11)
	v_mul_f32_e32 v66, v152, v0
	v_mul_f32_e32 v67, v153, v4
	v_fmac_f32_e32 v66, v154, v5
	v_fmac_f32_e32 v67, v155, v6
	ds_read_b128 v[152:155], v105 offset:43840
	s_waitcnt lgkmcnt(11)
	v_fmac_f32_e32 v66, v156, v7
	v_fmac_f32_e32 v67, v157, v8
	v_fmac_f32_e32 v66, v158, v9
	v_fmac_f32_e32 v67, v159, v10
	ds_read_b128 v[156:159], v105 offset:43856
	s_waitcnt lgkmcnt(11)
	v_fmac_f32_e32 v66, v160, v11
	v_fmac_f32_e32 v67, v161, v12
	v_fmac_f32_e32 v66, v162, v13
	v_fmac_f32_e32 v67, v163, v14
	ds_read_b128 v[160:163], v105 offset:43872
	s_waitcnt lgkmcnt(11)
	v_fmac_f32_e32 v66, v164, v15
	v_fmac_f32_e32 v67, v165, v16
	v_fmac_f32_e32 v66, v166, v17
	v_fmac_f32_e32 v67, v167, v18
	ds_read_b128 v[164:167], v105 offset:43888
	s_waitcnt lgkmcnt(11)
	v_fmac_f32_e32 v66, v168, v20
	v_fmac_f32_e32 v67, v169, v21
	v_fmac_f32_e32 v66, v170, v22
	v_fmac_f32_e32 v67, v171, v23
	ds_read_b128 v[168:171], v105 offset:43904
	s_waitcnt lgkmcnt(11)
	v_fmac_f32_e32 v66, v172, v24
	v_fmac_f32_e32 v67, v173, v25
	v_fmac_f32_e32 v66, v174, v26
	v_fmac_f32_e32 v67, v175, v27
	ds_read_b128 v[172:175], v105 offset:44032
	s_waitcnt lgkmcnt(11)
	v_fmac_f32_e32 v66, v176, v28
	v_fmac_f32_e32 v67, v177, v29
	v_fmac_f32_e32 v66, v178, v30
	v_fmac_f32_e32 v67, v179, v31
	ds_read_b128 v[176:179], v105 offset:44048
	s_waitcnt lgkmcnt(11)
	v_fmac_f32_e32 v66, v180, v32
	v_fmac_f32_e32 v67, v181, v33
	v_fmac_f32_e32 v66, v182, v34
	v_fmac_f32_e32 v67, v183, v35
	v_sub_f32_e32 v36, v36, v66
	v_sub_f32_e32 v36, v36, v67
	ds_read_b128 v[180:183], v105 offset:44064
	s_waitcnt lgkmcnt(11)
	v_mul_f32_e32 v66, v136, v0
	v_mul_f32_e32 v67, v137, v4
	v_fmac_f32_e32 v66, v138, v5
	v_fmac_f32_e32 v67, v139, v6
	ds_read_b128 v[136:139], v105 offset:44080
	s_waitcnt lgkmcnt(11)
	v_fmac_f32_e32 v66, v140, v7
	v_fmac_f32_e32 v67, v141, v8
	v_fmac_f32_e32 v66, v142, v9
	v_fmac_f32_e32 v67, v143, v10
	ds_read_b128 v[140:143], v105 offset:44096
	s_waitcnt lgkmcnt(11)
	v_fmac_f32_e32 v66, v144, v11
	v_fmac_f32_e32 v67, v145, v12
	v_fmac_f32_e32 v66, v146, v13
	v_fmac_f32_e32 v67, v147, v14
	ds_read_b128 v[144:147], v105 offset:44112
	s_waitcnt lgkmcnt(11)
	v_fmac_f32_e32 v66, v148, v15
	v_fmac_f32_e32 v67, v149, v16
	v_fmac_f32_e32 v66, v150, v17
	v_fmac_f32_e32 v67, v151, v18
	ds_read_b128 v[148:151], v105 offset:44128
	s_waitcnt lgkmcnt(11)
	v_fmac_f32_e32 v66, v152, v20
	v_fmac_f32_e32 v67, v153, v21
	v_fmac_f32_e32 v66, v154, v22
	v_fmac_f32_e32 v67, v155, v23
	ds_read_b128 v[152:155], v105 offset:44144
	s_waitcnt lgkmcnt(11)
	v_fmac_f32_e32 v66, v156, v24
	v_fmac_f32_e32 v67, v157, v25
	v_fmac_f32_e32 v66, v158, v26
	v_fmac_f32_e32 v67, v159, v27
	ds_read_b128 v[156:159], v105 offset:44160
	s_waitcnt lgkmcnt(11)
	v_fmac_f32_e32 v66, v160, v28
	v_fmac_f32_e32 v67, v161, v29
	v_fmac_f32_e32 v66, v162, v30
	v_fmac_f32_e32 v67, v163, v31
	ds_read_b128 v[160:163], v105 offset:44288
	s_waitcnt lgkmcnt(11)
	v_fmac_f32_e32 v66, v164, v32
	v_fmac_f32_e32 v67, v165, v33
	v_fmac_f32_e32 v66, v166, v34
	v_fmac_f32_e32 v67, v167, v35
	ds_read_b128 v[164:167], v105 offset:44304
	s_waitcnt lgkmcnt(11)
	v_fmac_f32_e32 v66, v168, v36
	v_sub_f32_e32 v37, v37, v66
	v_sub_f32_e32 v37, v37, v67
	ds_read_b128 v[168:171], v105 offset:44320
	s_waitcnt lgkmcnt(11)
	v_mul_f32_e32 v66, v172, v0
	v_mul_f32_e32 v67, v173, v4
	v_fmac_f32_e32 v66, v174, v5
	v_fmac_f32_e32 v67, v175, v6
	ds_read_b128 v[172:175], v105 offset:44336
	s_waitcnt lgkmcnt(11)
	v_fmac_f32_e32 v66, v176, v7
	v_fmac_f32_e32 v67, v177, v8
	v_fmac_f32_e32 v66, v178, v9
	v_fmac_f32_e32 v67, v179, v10
	ds_read_b128 v[176:179], v105 offset:44352
	s_waitcnt lgkmcnt(11)
	v_fmac_f32_e32 v66, v180, v11
	v_fmac_f32_e32 v67, v181, v12
	v_fmac_f32_e32 v66, v182, v13
	v_fmac_f32_e32 v67, v183, v14
	ds_read_b128 v[180:183], v105 offset:44368
	s_waitcnt lgkmcnt(11)
	v_fmac_f32_e32 v66, v136, v15
	v_fmac_f32_e32 v67, v137, v16
	v_fmac_f32_e32 v66, v138, v17
	v_fmac_f32_e32 v67, v139, v18
	ds_read_b128 v[136:139], v105 offset:44384
	s_waitcnt lgkmcnt(11)
	v_fmac_f32_e32 v66, v140, v20
	v_fmac_f32_e32 v67, v141, v21
	v_fmac_f32_e32 v66, v142, v22
	v_fmac_f32_e32 v67, v143, v23
	ds_read_b128 v[140:143], v105 offset:44400
	s_waitcnt lgkmcnt(11)
	v_fmac_f32_e32 v66, v144, v24
	v_fmac_f32_e32 v67, v145, v25
	v_fmac_f32_e32 v66, v146, v26
	v_fmac_f32_e32 v67, v147, v27
	ds_read_b128 v[144:147], v105 offset:44416
	s_waitcnt lgkmcnt(11)
	v_fmac_f32_e32 v66, v148, v28
	v_fmac_f32_e32 v67, v149, v29
	v_fmac_f32_e32 v66, v150, v30
	v_fmac_f32_e32 v67, v151, v31
	ds_read_b128 v[148:151], v105 offset:44544
	s_waitcnt lgkmcnt(11)
	v_fmac_f32_e32 v66, v152, v32
	v_fmac_f32_e32 v67, v153, v33
	v_fmac_f32_e32 v66, v154, v34
	v_fmac_f32_e32 v67, v155, v35
	ds_read_b128 v[152:155], v105 offset:44560
	s_waitcnt lgkmcnt(11)
	v_fmac_f32_e32 v66, v156, v36
	v_fmac_f32_e32 v67, v157, v37
	v_sub_f32_e32 v38, v38, v66
	v_sub_f32_e32 v38, v38, v67
	ds_read_b128 v[156:159], v105 offset:44576
	s_waitcnt lgkmcnt(11)
	v_mul_f32_e32 v66, v160, v0
	v_mul_f32_e32 v67, v161, v4
	v_fmac_f32_e32 v66, v162, v5
	v_fmac_f32_e32 v67, v163, v6
	ds_read_b128 v[160:163], v105 offset:44592
	s_waitcnt lgkmcnt(11)
	v_fmac_f32_e32 v66, v164, v7
	v_fmac_f32_e32 v67, v165, v8
	v_fmac_f32_e32 v66, v166, v9
	v_fmac_f32_e32 v67, v167, v10
	ds_read_b128 v[164:167], v105 offset:44608
	s_waitcnt lgkmcnt(11)
	v_fmac_f32_e32 v66, v168, v11
	v_fmac_f32_e32 v67, v169, v12
	v_fmac_f32_e32 v66, v170, v13
	v_fmac_f32_e32 v67, v171, v14
	ds_read_b128 v[168:171], v105 offset:44624
	s_waitcnt lgkmcnt(11)
	v_fmac_f32_e32 v66, v172, v15
	v_fmac_f32_e32 v67, v173, v16
	v_fmac_f32_e32 v66, v174, v17
	v_fmac_f32_e32 v67, v175, v18
	ds_read_b128 v[172:175], v105 offset:44640
	s_waitcnt lgkmcnt(11)
	v_fmac_f32_e32 v66, v176, v20
	v_fmac_f32_e32 v67, v177, v21
	v_fmac_f32_e32 v66, v178, v22
	v_fmac_f32_e32 v67, v179, v23
	ds_read_b128 v[176:179], v105 offset:44656
	s_waitcnt lgkmcnt(11)
	v_fmac_f32_e32 v66, v180, v24
	v_fmac_f32_e32 v67, v181, v25
	v_fmac_f32_e32 v66, v182, v26
	v_fmac_f32_e32 v67, v183, v27
	ds_read_b128 v[180:183], v105 offset:44672
	s_waitcnt lgkmcnt(11)
	v_fmac_f32_e32 v66, v136, v28
	v_fmac_f32_e32 v67, v137, v29
	v_fmac_f32_e32 v66, v138, v30
	v_fmac_f32_e32 v67, v139, v31
	ds_read_b128 v[136:139], v105 offset:44800
	s_waitcnt lgkmcnt(11)
	v_fmac_f32_e32 v66, v140, v32
	v_fmac_f32_e32 v67, v141, v33
	v_fmac_f32_e32 v66, v142, v34
	v_fmac_f32_e32 v67, v143, v35
	ds_read_b128 v[140:143], v105 offset:44816
	s_waitcnt lgkmcnt(11)
	v_fmac_f32_e32 v66, v144, v36
	v_fmac_f32_e32 v67, v145, v37
	v_fmac_f32_e32 v66, v146, v38
	v_sub_f32_e32 v39, v39, v66
	v_sub_f32_e32 v39, v39, v67
	ds_read_b128 v[144:147], v105 offset:44832
	s_waitcnt lgkmcnt(11)
	v_mul_f32_e32 v66, v148, v0
	v_mul_f32_e32 v67, v149, v4
	v_fmac_f32_e32 v66, v150, v5
	v_fmac_f32_e32 v67, v151, v6
	ds_read_b128 v[148:151], v105 offset:44848
	s_waitcnt lgkmcnt(11)
	v_fmac_f32_e32 v66, v152, v7
	v_fmac_f32_e32 v67, v153, v8
	v_fmac_f32_e32 v66, v154, v9
	v_fmac_f32_e32 v67, v155, v10
	ds_read_b128 v[152:155], v105 offset:44864
	s_waitcnt lgkmcnt(11)
	v_fmac_f32_e32 v66, v156, v11
	v_fmac_f32_e32 v67, v157, v12
	v_fmac_f32_e32 v66, v158, v13
	v_fmac_f32_e32 v67, v159, v14
	ds_read_b128 v[156:159], v105 offset:44880
	s_waitcnt lgkmcnt(11)
	v_fmac_f32_e32 v66, v160, v15
	v_fmac_f32_e32 v67, v161, v16
	v_fmac_f32_e32 v66, v162, v17
	v_fmac_f32_e32 v67, v163, v18
	ds_read_b128 v[160:163], v105 offset:44896
	s_waitcnt lgkmcnt(11)
	v_fmac_f32_e32 v66, v164, v20
	v_fmac_f32_e32 v67, v165, v21
	v_fmac_f32_e32 v66, v166, v22
	v_fmac_f32_e32 v67, v167, v23
	ds_read_b128 v[164:167], v105 offset:44912
	s_waitcnt lgkmcnt(11)
	v_fmac_f32_e32 v66, v168, v24
	v_fmac_f32_e32 v67, v169, v25
	v_fmac_f32_e32 v66, v170, v26
	v_fmac_f32_e32 v67, v171, v27
	ds_read_b128 v[168:171], v105 offset:44928
	s_waitcnt lgkmcnt(11)
	v_fmac_f32_e32 v66, v172, v28
	v_fmac_f32_e32 v67, v173, v29
	v_fmac_f32_e32 v66, v174, v30
	v_fmac_f32_e32 v67, v175, v31
	ds_read_b128 v[172:175], v105 offset:44944
	s_waitcnt lgkmcnt(11)
	v_fmac_f32_e32 v66, v176, v32
	v_fmac_f32_e32 v67, v177, v33
	v_fmac_f32_e32 v66, v178, v34
	v_fmac_f32_e32 v67, v179, v35
	ds_read_b128 v[176:179], v105 offset:45056
	s_waitcnt lgkmcnt(11)
	v_fmac_f32_e32 v66, v180, v36
	v_fmac_f32_e32 v67, v181, v37
	v_fmac_f32_e32 v66, v182, v38
	v_fmac_f32_e32 v67, v183, v39
	v_sub_f32_e32 v40, v40, v66
	v_sub_f32_e32 v40, v40, v67
	ds_read_b128 v[180:183], v105 offset:45072
	s_waitcnt lgkmcnt(11)
	v_mul_f32_e32 v66, v136, v0
	v_mul_f32_e32 v67, v137, v4
	v_fmac_f32_e32 v66, v138, v5
	v_fmac_f32_e32 v67, v139, v6
	ds_read_b128 v[136:139], v105 offset:45088
	s_waitcnt lgkmcnt(11)
	v_fmac_f32_e32 v66, v140, v7
	v_fmac_f32_e32 v67, v141, v8
	v_fmac_f32_e32 v66, v142, v9
	v_fmac_f32_e32 v67, v143, v10
	ds_read_b128 v[140:143], v105 offset:45104
	s_waitcnt lgkmcnt(11)
	v_fmac_f32_e32 v66, v144, v11
	v_fmac_f32_e32 v67, v145, v12
	v_fmac_f32_e32 v66, v146, v13
	v_fmac_f32_e32 v67, v147, v14
	ds_read_b128 v[144:147], v105 offset:45120
	s_waitcnt lgkmcnt(11)
	v_fmac_f32_e32 v66, v148, v15
	v_fmac_f32_e32 v67, v149, v16
	v_fmac_f32_e32 v66, v150, v17
	v_fmac_f32_e32 v67, v151, v18
	ds_read_b128 v[148:151], v105 offset:45136
	s_waitcnt lgkmcnt(11)
	v_fmac_f32_e32 v66, v152, v20
	v_fmac_f32_e32 v67, v153, v21
	v_fmac_f32_e32 v66, v154, v22
	v_fmac_f32_e32 v67, v155, v23
	ds_read_b128 v[152:155], v105 offset:45152
	s_waitcnt lgkmcnt(11)
	v_fmac_f32_e32 v66, v156, v24
	v_fmac_f32_e32 v67, v157, v25
	v_fmac_f32_e32 v66, v158, v26
	v_fmac_f32_e32 v67, v159, v27
	ds_read_b128 v[156:159], v105 offset:45168
	s_waitcnt lgkmcnt(11)
	v_fmac_f32_e32 v66, v160, v28
	v_fmac_f32_e32 v67, v161, v29
	v_fmac_f32_e32 v66, v162, v30
	v_fmac_f32_e32 v67, v163, v31
	ds_read_b128 v[160:163], v105 offset:45184
	s_waitcnt lgkmcnt(11)
	v_fmac_f32_e32 v66, v164, v32
	v_fmac_f32_e32 v67, v165, v33
	v_fmac_f32_e32 v66, v166, v34
	v_fmac_f32_e32 v67, v167, v35
	ds_read_b128 v[164:167], v105 offset:45200
	s_waitcnt lgkmcnt(11)
	v_fmac_f32_e32 v66, v168, v36
	v_fmac_f32_e32 v67, v169, v37
	v_fmac_f32_e32 v66, v170, v38
	v_fmac_f32_e32 v67, v171, v39
	ds_read_b128 v[168:171], v105 offset:45312
	s_waitcnt lgkmcnt(11)
	v_fmac_f32_e32 v66, v172, v40
	v_sub_f32_e32 v41, v41, v66
	v_sub_f32_e32 v41, v41, v67
	ds_read_b128 v[172:175], v105 offset:45328
	s_waitcnt lgkmcnt(11)
	v_mul_f32_e32 v66, v176, v0
	v_mul_f32_e32 v67, v177, v4
	v_fmac_f32_e32 v66, v178, v5
	v_fmac_f32_e32 v67, v179, v6
	ds_read_b128 v[176:179], v105 offset:45344
	s_waitcnt lgkmcnt(11)
	v_fmac_f32_e32 v66, v180, v7
	v_fmac_f32_e32 v67, v181, v8
	v_fmac_f32_e32 v66, v182, v9
	v_fmac_f32_e32 v67, v183, v10
	ds_read_b128 v[180:183], v105 offset:45360
	s_waitcnt lgkmcnt(11)
	v_fmac_f32_e32 v66, v136, v11
	v_fmac_f32_e32 v67, v137, v12
	v_fmac_f32_e32 v66, v138, v13
	v_fmac_f32_e32 v67, v139, v14
	ds_read_b128 v[136:139], v105 offset:45376
	s_waitcnt lgkmcnt(11)
	v_fmac_f32_e32 v66, v140, v15
	v_fmac_f32_e32 v67, v141, v16
	v_fmac_f32_e32 v66, v142, v17
	v_fmac_f32_e32 v67, v143, v18
	ds_read_b128 v[140:143], v105 offset:45392
	s_waitcnt lgkmcnt(11)
	v_fmac_f32_e32 v66, v144, v20
	v_fmac_f32_e32 v67, v145, v21
	v_fmac_f32_e32 v66, v146, v22
	v_fmac_f32_e32 v67, v147, v23
	ds_read_b128 v[144:147], v105 offset:45408
	s_waitcnt lgkmcnt(11)
	v_fmac_f32_e32 v66, v148, v24
	v_fmac_f32_e32 v67, v149, v25
	v_fmac_f32_e32 v66, v150, v26
	v_fmac_f32_e32 v67, v151, v27
	ds_read_b128 v[148:151], v105 offset:45424
	s_waitcnt lgkmcnt(11)
	v_fmac_f32_e32 v66, v152, v28
	v_fmac_f32_e32 v67, v153, v29
	v_fmac_f32_e32 v66, v154, v30
	v_fmac_f32_e32 v67, v155, v31
	ds_read_b128 v[152:155], v105 offset:45440
	s_waitcnt lgkmcnt(11)
	v_fmac_f32_e32 v66, v156, v32
	v_fmac_f32_e32 v67, v157, v33
	v_fmac_f32_e32 v66, v158, v34
	v_fmac_f32_e32 v67, v159, v35
	ds_read_b128 v[156:159], v105 offset:45456
	s_waitcnt lgkmcnt(11)
	v_fmac_f32_e32 v66, v160, v36
	v_fmac_f32_e32 v67, v161, v37
	v_fmac_f32_e32 v66, v162, v38
	v_fmac_f32_e32 v67, v163, v39
	ds_read_b128 v[160:163], v105 offset:45568
	s_waitcnt lgkmcnt(11)
	v_fmac_f32_e32 v66, v164, v40
	v_fmac_f32_e32 v67, v165, v41
	v_sub_f32_e32 v42, v42, v66
	v_sub_f32_e32 v42, v42, v67
	ds_read_b128 v[164:167], v105 offset:45584
	s_waitcnt lgkmcnt(11)
	v_mul_f32_e32 v66, v168, v0
	v_mul_f32_e32 v67, v169, v4
	v_fmac_f32_e32 v66, v170, v5
	v_fmac_f32_e32 v67, v171, v6
	ds_read_b128 v[168:171], v105 offset:45600
	s_waitcnt lgkmcnt(11)
	v_fmac_f32_e32 v66, v172, v7
	v_fmac_f32_e32 v67, v173, v8
	v_fmac_f32_e32 v66, v174, v9
	v_fmac_f32_e32 v67, v175, v10
	ds_read_b128 v[172:175], v105 offset:45616
	s_waitcnt lgkmcnt(11)
	v_fmac_f32_e32 v66, v176, v11
	v_fmac_f32_e32 v67, v177, v12
	v_fmac_f32_e32 v66, v178, v13
	v_fmac_f32_e32 v67, v179, v14
	ds_read_b128 v[176:179], v105 offset:45632
	s_waitcnt lgkmcnt(11)
	v_fmac_f32_e32 v66, v180, v15
	v_fmac_f32_e32 v67, v181, v16
	v_fmac_f32_e32 v66, v182, v17
	v_fmac_f32_e32 v67, v183, v18
	ds_read_b128 v[180:183], v105 offset:45648
	s_waitcnt lgkmcnt(11)
	v_fmac_f32_e32 v66, v136, v20
	v_fmac_f32_e32 v67, v137, v21
	v_fmac_f32_e32 v66, v138, v22
	v_fmac_f32_e32 v67, v139, v23
	ds_read_b128 v[136:139], v105 offset:45664
	s_waitcnt lgkmcnt(11)
	v_fmac_f32_e32 v66, v140, v24
	v_fmac_f32_e32 v67, v141, v25
	v_fmac_f32_e32 v66, v142, v26
	v_fmac_f32_e32 v67, v143, v27
	ds_read_b128 v[140:143], v105 offset:45680
	s_waitcnt lgkmcnt(11)
	v_fmac_f32_e32 v66, v144, v28
	v_fmac_f32_e32 v67, v145, v29
	v_fmac_f32_e32 v66, v146, v30
	v_fmac_f32_e32 v67, v147, v31
	ds_read_b128 v[144:147], v105 offset:45696
	s_waitcnt lgkmcnt(11)
	v_fmac_f32_e32 v66, v148, v32
	v_fmac_f32_e32 v67, v149, v33
	v_fmac_f32_e32 v66, v150, v34
	v_fmac_f32_e32 v67, v151, v35
	ds_read_b128 v[148:151], v105 offset:45712
	s_waitcnt lgkmcnt(11)
	v_fmac_f32_e32 v66, v152, v36
	v_fmac_f32_e32 v67, v153, v37
	v_fmac_f32_e32 v66, v154, v38
	v_fmac_f32_e32 v67, v155, v39
	ds_read_b128 v[152:155], v105 offset:45824
	s_waitcnt lgkmcnt(11)
	v_fmac_f32_e32 v66, v156, v40
	v_fmac_f32_e32 v67, v157, v41
	v_fmac_f32_e32 v66, v158, v42
	v_sub_f32_e32 v43, v43, v66
	v_sub_f32_e32 v43, v43, v67
	ds_read_b128 v[156:159], v105 offset:45840
	s_waitcnt lgkmcnt(11)
	v_mul_f32_e32 v66, v160, v0
	v_mul_f32_e32 v67, v161, v4
	v_fmac_f32_e32 v66, v162, v5
	v_fmac_f32_e32 v67, v163, v6
	ds_read_b128 v[160:163], v105 offset:45856
	s_waitcnt lgkmcnt(11)
	v_fmac_f32_e32 v66, v164, v7
	v_fmac_f32_e32 v67, v165, v8
	v_fmac_f32_e32 v66, v166, v9
	v_fmac_f32_e32 v67, v167, v10
	ds_read_b128 v[164:167], v105 offset:45872
	s_waitcnt lgkmcnt(11)
	v_fmac_f32_e32 v66, v168, v11
	v_fmac_f32_e32 v67, v169, v12
	v_fmac_f32_e32 v66, v170, v13
	v_fmac_f32_e32 v67, v171, v14
	ds_read_b128 v[168:171], v105 offset:45888
	s_waitcnt lgkmcnt(11)
	v_fmac_f32_e32 v66, v172, v15
	v_fmac_f32_e32 v67, v173, v16
	v_fmac_f32_e32 v66, v174, v17
	v_fmac_f32_e32 v67, v175, v18
	ds_read_b128 v[172:175], v105 offset:45904
	s_waitcnt lgkmcnt(11)
	v_fmac_f32_e32 v66, v176, v20
	v_fmac_f32_e32 v67, v177, v21
	v_fmac_f32_e32 v66, v178, v22
	v_fmac_f32_e32 v67, v179, v23
	ds_read_b128 v[176:179], v105 offset:45920
	s_waitcnt lgkmcnt(11)
	v_fmac_f32_e32 v66, v180, v24
	v_fmac_f32_e32 v67, v181, v25
	v_fmac_f32_e32 v66, v182, v26
	v_fmac_f32_e32 v67, v183, v27
	ds_read_b128 v[180:183], v105 offset:45936
	s_waitcnt lgkmcnt(11)
	v_fmac_f32_e32 v66, v136, v28
	v_fmac_f32_e32 v67, v137, v29
	v_fmac_f32_e32 v66, v138, v30
	v_fmac_f32_e32 v67, v139, v31
	ds_read_b128 v[136:139], v105 offset:45952
	s_waitcnt lgkmcnt(11)
	v_fmac_f32_e32 v66, v140, v32
	v_fmac_f32_e32 v67, v141, v33
	v_fmac_f32_e32 v66, v142, v34
	v_fmac_f32_e32 v67, v143, v35
	ds_read_b128 v[140:143], v105 offset:45968
	s_waitcnt lgkmcnt(11)
	v_fmac_f32_e32 v66, v144, v36
	v_fmac_f32_e32 v67, v145, v37
	v_fmac_f32_e32 v66, v146, v38
	v_fmac_f32_e32 v67, v147, v39
	ds_read_b128 v[144:147], v105 offset:45984
	s_waitcnt lgkmcnt(11)
	v_fmac_f32_e32 v66, v148, v40
	v_fmac_f32_e32 v67, v149, v41
	v_fmac_f32_e32 v66, v150, v42
	v_fmac_f32_e32 v67, v151, v43
	v_sub_f32_e32 v44, v44, v66
	v_sub_f32_e32 v44, v44, v67
	ds_read_b128 v[148:151], v105 offset:46080
	s_waitcnt lgkmcnt(11)
	v_mul_f32_e32 v66, v152, v0
	v_mul_f32_e32 v67, v153, v4
	v_fmac_f32_e32 v66, v154, v5
	v_fmac_f32_e32 v67, v155, v6
	ds_read_b128 v[152:155], v105 offset:46096
	s_waitcnt lgkmcnt(11)
	v_fmac_f32_e32 v66, v156, v7
	v_fmac_f32_e32 v67, v157, v8
	v_fmac_f32_e32 v66, v158, v9
	v_fmac_f32_e32 v67, v159, v10
	ds_read_b128 v[156:159], v105 offset:46112
	s_waitcnt lgkmcnt(11)
	v_fmac_f32_e32 v66, v160, v11
	v_fmac_f32_e32 v67, v161, v12
	v_fmac_f32_e32 v66, v162, v13
	v_fmac_f32_e32 v67, v163, v14
	ds_read_b128 v[160:163], v105 offset:46128
	s_waitcnt lgkmcnt(11)
	v_fmac_f32_e32 v66, v164, v15
	v_fmac_f32_e32 v67, v165, v16
	v_fmac_f32_e32 v66, v166, v17
	v_fmac_f32_e32 v67, v167, v18
	ds_read_b128 v[164:167], v105 offset:46144
	s_waitcnt lgkmcnt(11)
	v_fmac_f32_e32 v66, v168, v20
	v_fmac_f32_e32 v67, v169, v21
	v_fmac_f32_e32 v66, v170, v22
	v_fmac_f32_e32 v67, v171, v23
	ds_read_b128 v[168:171], v105 offset:46160
	s_waitcnt lgkmcnt(11)
	v_fmac_f32_e32 v66, v172, v24
	v_fmac_f32_e32 v67, v173, v25
	v_fmac_f32_e32 v66, v174, v26
	v_fmac_f32_e32 v67, v175, v27
	ds_read_b128 v[172:175], v105 offset:46176
	s_waitcnt lgkmcnt(11)
	v_fmac_f32_e32 v66, v176, v28
	v_fmac_f32_e32 v67, v177, v29
	v_fmac_f32_e32 v66, v178, v30
	v_fmac_f32_e32 v67, v179, v31
	ds_read_b128 v[176:179], v105 offset:46192
	s_waitcnt lgkmcnt(11)
	v_fmac_f32_e32 v66, v180, v32
	v_fmac_f32_e32 v67, v181, v33
	v_fmac_f32_e32 v66, v182, v34
	v_fmac_f32_e32 v67, v183, v35
	ds_read_b128 v[180:183], v105 offset:46208
	s_waitcnt lgkmcnt(11)
	v_fmac_f32_e32 v66, v136, v36
	v_fmac_f32_e32 v67, v137, v37
	v_fmac_f32_e32 v66, v138, v38
	v_fmac_f32_e32 v67, v139, v39
	ds_read_b128 v[136:139], v105 offset:46224
	s_waitcnt lgkmcnt(11)
	v_fmac_f32_e32 v66, v140, v40
	v_fmac_f32_e32 v67, v141, v41
	v_fmac_f32_e32 v66, v142, v42
	v_fmac_f32_e32 v67, v143, v43
	ds_read_b128 v[140:143], v105 offset:46240
	s_waitcnt lgkmcnt(11)
	v_fmac_f32_e32 v66, v144, v44
	v_sub_f32_e32 v45, v45, v66
	v_sub_f32_e32 v45, v45, v67
	ds_read_b128 v[144:147], v105 offset:46336
	s_waitcnt lgkmcnt(11)
	v_mul_f32_e32 v66, v148, v0
	v_mul_f32_e32 v67, v149, v4
	v_fmac_f32_e32 v66, v150, v5
	v_fmac_f32_e32 v67, v151, v6
	ds_read_b128 v[148:151], v105 offset:46352
	s_waitcnt lgkmcnt(11)
	v_fmac_f32_e32 v66, v152, v7
	v_fmac_f32_e32 v67, v153, v8
	v_fmac_f32_e32 v66, v154, v9
	v_fmac_f32_e32 v67, v155, v10
	ds_read_b128 v[152:155], v105 offset:46368
	s_waitcnt lgkmcnt(11)
	v_fmac_f32_e32 v66, v156, v11
	v_fmac_f32_e32 v67, v157, v12
	v_fmac_f32_e32 v66, v158, v13
	v_fmac_f32_e32 v67, v159, v14
	ds_read_b128 v[156:159], v105 offset:46384
	s_waitcnt lgkmcnt(11)
	v_fmac_f32_e32 v66, v160, v15
	v_fmac_f32_e32 v67, v161, v16
	v_fmac_f32_e32 v66, v162, v17
	v_fmac_f32_e32 v67, v163, v18
	ds_read_b128 v[160:163], v105 offset:46400
	s_waitcnt lgkmcnt(11)
	v_fmac_f32_e32 v66, v164, v20
	v_fmac_f32_e32 v67, v165, v21
	v_fmac_f32_e32 v66, v166, v22
	v_fmac_f32_e32 v67, v167, v23
	ds_read_b128 v[164:167], v105 offset:46416
	s_waitcnt lgkmcnt(11)
	v_fmac_f32_e32 v66, v168, v24
	v_fmac_f32_e32 v67, v169, v25
	v_fmac_f32_e32 v66, v170, v26
	v_fmac_f32_e32 v67, v171, v27
	ds_read_b128 v[168:171], v105 offset:46432
	s_waitcnt lgkmcnt(11)
	v_fmac_f32_e32 v66, v172, v28
	v_fmac_f32_e32 v67, v173, v29
	v_fmac_f32_e32 v66, v174, v30
	v_fmac_f32_e32 v67, v175, v31
	ds_read_b128 v[172:175], v105 offset:46448
	s_waitcnt lgkmcnt(11)
	v_fmac_f32_e32 v66, v176, v32
	v_fmac_f32_e32 v67, v177, v33
	v_fmac_f32_e32 v66, v178, v34
	v_fmac_f32_e32 v67, v179, v35
	ds_read_b128 v[176:179], v105 offset:46464
	s_waitcnt lgkmcnt(11)
	v_fmac_f32_e32 v66, v180, v36
	v_fmac_f32_e32 v67, v181, v37
	v_fmac_f32_e32 v66, v182, v38
	v_fmac_f32_e32 v67, v183, v39
	ds_read_b128 v[180:183], v105 offset:46480
	s_waitcnt lgkmcnt(11)
	v_fmac_f32_e32 v66, v136, v40
	v_fmac_f32_e32 v67, v137, v41
	v_fmac_f32_e32 v66, v138, v42
	v_fmac_f32_e32 v67, v139, v43
	ds_read_b128 v[136:139], v105 offset:46496
	s_waitcnt lgkmcnt(11)
	v_fmac_f32_e32 v66, v140, v44
	v_fmac_f32_e32 v67, v141, v45
	v_sub_f32_e32 v46, v46, v66
	v_sub_f32_e32 v46, v46, v67
	ds_read_b128 v[140:143], v105 offset:46592
	s_waitcnt lgkmcnt(11)
	v_mul_f32_e32 v66, v144, v0
	v_mul_f32_e32 v67, v145, v4
	v_fmac_f32_e32 v66, v146, v5
	v_fmac_f32_e32 v67, v147, v6
	ds_read_b128 v[144:147], v105 offset:46608
	s_waitcnt lgkmcnt(11)
	v_fmac_f32_e32 v66, v148, v7
	v_fmac_f32_e32 v67, v149, v8
	v_fmac_f32_e32 v66, v150, v9
	v_fmac_f32_e32 v67, v151, v10
	ds_read_b128 v[148:151], v105 offset:46624
	s_waitcnt lgkmcnt(11)
	v_fmac_f32_e32 v66, v152, v11
	v_fmac_f32_e32 v67, v153, v12
	v_fmac_f32_e32 v66, v154, v13
	v_fmac_f32_e32 v67, v155, v14
	ds_read_b128 v[152:155], v105 offset:46640
	s_waitcnt lgkmcnt(11)
	v_fmac_f32_e32 v66, v156, v15
	v_fmac_f32_e32 v67, v157, v16
	v_fmac_f32_e32 v66, v158, v17
	v_fmac_f32_e32 v67, v159, v18
	ds_read_b128 v[156:159], v105 offset:46656
	s_waitcnt lgkmcnt(11)
	v_fmac_f32_e32 v66, v160, v20
	v_fmac_f32_e32 v67, v161, v21
	v_fmac_f32_e32 v66, v162, v22
	v_fmac_f32_e32 v67, v163, v23
	ds_read_b128 v[160:163], v105 offset:46672
	s_waitcnt lgkmcnt(11)
	v_fmac_f32_e32 v66, v164, v24
	v_fmac_f32_e32 v67, v165, v25
	v_fmac_f32_e32 v66, v166, v26
	v_fmac_f32_e32 v67, v167, v27
	ds_read_b128 v[164:167], v105 offset:46688
	s_waitcnt lgkmcnt(11)
	v_fmac_f32_e32 v66, v168, v28
	v_fmac_f32_e32 v67, v169, v29
	v_fmac_f32_e32 v66, v170, v30
	v_fmac_f32_e32 v67, v171, v31
	ds_read_b128 v[168:171], v105 offset:46704
	s_waitcnt lgkmcnt(11)
	v_fmac_f32_e32 v66, v172, v32
	v_fmac_f32_e32 v67, v173, v33
	v_fmac_f32_e32 v66, v174, v34
	v_fmac_f32_e32 v67, v175, v35
	ds_read_b128 v[172:175], v105 offset:46720
	s_waitcnt lgkmcnt(11)
	v_fmac_f32_e32 v66, v176, v36
	v_fmac_f32_e32 v67, v177, v37
	v_fmac_f32_e32 v66, v178, v38
	v_fmac_f32_e32 v67, v179, v39
	ds_read_b128 v[176:179], v105 offset:46736
	s_waitcnt lgkmcnt(11)
	v_fmac_f32_e32 v66, v180, v40
	v_fmac_f32_e32 v67, v181, v41
	v_fmac_f32_e32 v66, v182, v42
	v_fmac_f32_e32 v67, v183, v43
	ds_read_b128 v[180:183], v105 offset:46752
	s_waitcnt lgkmcnt(11)
	v_fmac_f32_e32 v66, v136, v44
	v_fmac_f32_e32 v67, v137, v45
	v_fmac_f32_e32 v66, v138, v46
	v_sub_f32_e32 v47, v47, v66
	v_sub_f32_e32 v47, v47, v67
	ds_read_b128 v[136:139], v105 offset:46848
	s_waitcnt lgkmcnt(11)
	v_mul_f32_e32 v66, v140, v0
	v_mul_f32_e32 v67, v141, v4
	v_fmac_f32_e32 v66, v142, v5
	v_fmac_f32_e32 v67, v143, v6
	ds_read_b128 v[140:143], v105 offset:46864
	s_waitcnt lgkmcnt(11)
	v_fmac_f32_e32 v66, v144, v7
	v_fmac_f32_e32 v67, v145, v8
	v_fmac_f32_e32 v66, v146, v9
	v_fmac_f32_e32 v67, v147, v10
	ds_read_b128 v[144:147], v105 offset:46880
	s_waitcnt lgkmcnt(11)
	v_fmac_f32_e32 v66, v148, v11
	v_fmac_f32_e32 v67, v149, v12
	v_fmac_f32_e32 v66, v150, v13
	v_fmac_f32_e32 v67, v151, v14
	ds_read_b128 v[148:151], v105 offset:46896
	s_waitcnt lgkmcnt(11)
	v_fmac_f32_e32 v66, v152, v15
	v_fmac_f32_e32 v67, v153, v16
	v_fmac_f32_e32 v66, v154, v17
	v_fmac_f32_e32 v67, v155, v18
	ds_read_b128 v[152:155], v105 offset:46912
	s_waitcnt lgkmcnt(11)
	v_fmac_f32_e32 v66, v156, v20
	v_fmac_f32_e32 v67, v157, v21
	v_fmac_f32_e32 v66, v158, v22
	v_fmac_f32_e32 v67, v159, v23
	ds_read_b128 v[156:159], v105 offset:46928
	s_waitcnt lgkmcnt(11)
	v_fmac_f32_e32 v66, v160, v24
	v_fmac_f32_e32 v67, v161, v25
	v_fmac_f32_e32 v66, v162, v26
	v_fmac_f32_e32 v67, v163, v27
	ds_read_b128 v[160:163], v105 offset:46944
	s_waitcnt lgkmcnt(11)
	v_fmac_f32_e32 v66, v164, v28
	v_fmac_f32_e32 v67, v165, v29
	v_fmac_f32_e32 v66, v166, v30
	v_fmac_f32_e32 v67, v167, v31
	ds_read_b128 v[164:167], v105 offset:46960
	s_waitcnt lgkmcnt(11)
	v_fmac_f32_e32 v66, v168, v32
	v_fmac_f32_e32 v67, v169, v33
	v_fmac_f32_e32 v66, v170, v34
	v_fmac_f32_e32 v67, v171, v35
	ds_read_b128 v[168:171], v105 offset:46976
	s_waitcnt lgkmcnt(11)
	v_fmac_f32_e32 v66, v172, v36
	v_fmac_f32_e32 v67, v173, v37
	v_fmac_f32_e32 v66, v174, v38
	v_fmac_f32_e32 v67, v175, v39
	ds_read_b128 v[172:175], v105 offset:46992
	s_waitcnt lgkmcnt(11)
	v_fmac_f32_e32 v66, v176, v40
	v_fmac_f32_e32 v67, v177, v41
	v_fmac_f32_e32 v66, v178, v42
	v_fmac_f32_e32 v67, v179, v43
	ds_read_b128 v[176:179], v105 offset:47008
	s_waitcnt lgkmcnt(11)
	v_fmac_f32_e32 v66, v180, v44
	v_fmac_f32_e32 v67, v181, v45
	v_fmac_f32_e32 v66, v182, v46
	v_fmac_f32_e32 v67, v183, v47
	v_sub_f32_e32 v48, v48, v66
	v_sub_f32_e32 v48, v48, v67
	ds_read_b128 v[180:183], v105 offset:47024
	s_waitcnt lgkmcnt(11)
	v_mul_f32_e32 v66, v136, v0
	v_mul_f32_e32 v67, v137, v4
	v_fmac_f32_e32 v66, v138, v5
	v_fmac_f32_e32 v67, v139, v6
	ds_read_b128 v[136:139], v105 offset:47104
	s_waitcnt lgkmcnt(11)
	v_fmac_f32_e32 v66, v140, v7
	v_fmac_f32_e32 v67, v141, v8
	v_fmac_f32_e32 v66, v142, v9
	v_fmac_f32_e32 v67, v143, v10
	ds_read_b128 v[140:143], v105 offset:47120
	s_waitcnt lgkmcnt(11)
	v_fmac_f32_e32 v66, v144, v11
	v_fmac_f32_e32 v67, v145, v12
	v_fmac_f32_e32 v66, v146, v13
	v_fmac_f32_e32 v67, v147, v14
	ds_read_b128 v[144:147], v105 offset:47136
	s_waitcnt lgkmcnt(11)
	v_fmac_f32_e32 v66, v148, v15
	v_fmac_f32_e32 v67, v149, v16
	v_fmac_f32_e32 v66, v150, v17
	v_fmac_f32_e32 v67, v151, v18
	ds_read_b128 v[148:151], v105 offset:47152
	s_waitcnt lgkmcnt(11)
	v_fmac_f32_e32 v66, v152, v20
	v_fmac_f32_e32 v67, v153, v21
	v_fmac_f32_e32 v66, v154, v22
	v_fmac_f32_e32 v67, v155, v23
	ds_read_b128 v[152:155], v105 offset:47168
	s_waitcnt lgkmcnt(11)
	v_fmac_f32_e32 v66, v156, v24
	v_fmac_f32_e32 v67, v157, v25
	v_fmac_f32_e32 v66, v158, v26
	v_fmac_f32_e32 v67, v159, v27
	ds_read_b128 v[156:159], v105 offset:47184
	s_waitcnt lgkmcnt(11)
	v_fmac_f32_e32 v66, v160, v28
	v_fmac_f32_e32 v67, v161, v29
	v_fmac_f32_e32 v66, v162, v30
	v_fmac_f32_e32 v67, v163, v31
	ds_read_b128 v[160:163], v105 offset:47200
	s_waitcnt lgkmcnt(11)
	v_fmac_f32_e32 v66, v164, v32
	v_fmac_f32_e32 v67, v165, v33
	v_fmac_f32_e32 v66, v166, v34
	v_fmac_f32_e32 v67, v167, v35
	ds_read_b128 v[164:167], v105 offset:47216
	s_waitcnt lgkmcnt(11)
	v_fmac_f32_e32 v66, v168, v36
	v_fmac_f32_e32 v67, v169, v37
	v_fmac_f32_e32 v66, v170, v38
	v_fmac_f32_e32 v67, v171, v39
	ds_read_b128 v[168:171], v105 offset:47232
	s_waitcnt lgkmcnt(11)
	v_fmac_f32_e32 v66, v172, v40
	v_fmac_f32_e32 v67, v173, v41
	v_fmac_f32_e32 v66, v174, v42
	v_fmac_f32_e32 v67, v175, v43
	ds_read_b128 v[172:175], v105 offset:47248
	s_waitcnt lgkmcnt(11)
	v_fmac_f32_e32 v66, v176, v44
	v_fmac_f32_e32 v67, v177, v45
	v_fmac_f32_e32 v66, v178, v46
	v_fmac_f32_e32 v67, v179, v47
	ds_read_b128 v[176:179], v105 offset:47264
	s_waitcnt lgkmcnt(11)
	v_fmac_f32_e32 v66, v180, v48
	v_sub_f32_e32 v49, v49, v66
	v_sub_f32_e32 v49, v49, v67
	ds_read_b128 v[180:183], v105 offset:47280
	s_waitcnt lgkmcnt(11)
	v_mul_f32_e32 v66, v136, v0
	v_mul_f32_e32 v67, v137, v4
	v_fmac_f32_e32 v66, v138, v5
	v_fmac_f32_e32 v67, v139, v6
	ds_read_b128 v[136:139], v105 offset:47360
	s_waitcnt lgkmcnt(11)
	v_fmac_f32_e32 v66, v140, v7
	v_fmac_f32_e32 v67, v141, v8
	v_fmac_f32_e32 v66, v142, v9
	v_fmac_f32_e32 v67, v143, v10
	ds_read_b128 v[140:143], v105 offset:47376
	s_waitcnt lgkmcnt(11)
	v_fmac_f32_e32 v66, v144, v11
	v_fmac_f32_e32 v67, v145, v12
	v_fmac_f32_e32 v66, v146, v13
	v_fmac_f32_e32 v67, v147, v14
	ds_read_b128 v[144:147], v105 offset:47392
	s_waitcnt lgkmcnt(11)
	v_fmac_f32_e32 v66, v148, v15
	v_fmac_f32_e32 v67, v149, v16
	v_fmac_f32_e32 v66, v150, v17
	v_fmac_f32_e32 v67, v151, v18
	ds_read_b128 v[148:151], v105 offset:47408
	s_waitcnt lgkmcnt(11)
	v_fmac_f32_e32 v66, v152, v20
	v_fmac_f32_e32 v67, v153, v21
	v_fmac_f32_e32 v66, v154, v22
	v_fmac_f32_e32 v67, v155, v23
	ds_read_b128 v[152:155], v105 offset:47424
	s_waitcnt lgkmcnt(11)
	v_fmac_f32_e32 v66, v156, v24
	v_fmac_f32_e32 v67, v157, v25
	v_fmac_f32_e32 v66, v158, v26
	v_fmac_f32_e32 v67, v159, v27
	ds_read_b128 v[156:159], v105 offset:47440
	s_waitcnt lgkmcnt(11)
	v_fmac_f32_e32 v66, v160, v28
	v_fmac_f32_e32 v67, v161, v29
	v_fmac_f32_e32 v66, v162, v30
	v_fmac_f32_e32 v67, v163, v31
	ds_read_b128 v[160:163], v105 offset:47456
	s_waitcnt lgkmcnt(11)
	v_fmac_f32_e32 v66, v164, v32
	v_fmac_f32_e32 v67, v165, v33
	v_fmac_f32_e32 v66, v166, v34
	v_fmac_f32_e32 v67, v167, v35
	ds_read_b128 v[164:167], v105 offset:47472
	s_waitcnt lgkmcnt(11)
	v_fmac_f32_e32 v66, v168, v36
	v_fmac_f32_e32 v67, v169, v37
	v_fmac_f32_e32 v66, v170, v38
	v_fmac_f32_e32 v67, v171, v39
	ds_read_b128 v[168:171], v105 offset:47488
	s_waitcnt lgkmcnt(11)
	v_fmac_f32_e32 v66, v172, v40
	v_fmac_f32_e32 v67, v173, v41
	v_fmac_f32_e32 v66, v174, v42
	v_fmac_f32_e32 v67, v175, v43
	ds_read_b128 v[172:175], v105 offset:47504
	s_waitcnt lgkmcnt(11)
	v_fmac_f32_e32 v66, v176, v44
	v_fmac_f32_e32 v67, v177, v45
	v_fmac_f32_e32 v66, v178, v46
	v_fmac_f32_e32 v67, v179, v47
	ds_read_b128 v[176:179], v105 offset:47520
	s_waitcnt lgkmcnt(11)
	v_fmac_f32_e32 v66, v180, v48
	v_fmac_f32_e32 v67, v181, v49
	v_sub_f32_e32 v50, v50, v66
	v_sub_f32_e32 v50, v50, v67
	ds_read_b128 v[180:183], v105 offset:47536
	s_waitcnt lgkmcnt(11)
	v_mul_f32_e32 v66, v136, v0
	v_mul_f32_e32 v67, v137, v4
	v_fmac_f32_e32 v66, v138, v5
	v_fmac_f32_e32 v67, v139, v6
	ds_read_b128 v[136:139], v105 offset:47616
	s_waitcnt lgkmcnt(11)
	v_fmac_f32_e32 v66, v140, v7
	v_fmac_f32_e32 v67, v141, v8
	v_fmac_f32_e32 v66, v142, v9
	v_fmac_f32_e32 v67, v143, v10
	ds_read_b128 v[140:143], v105 offset:47632
	s_waitcnt lgkmcnt(11)
	v_fmac_f32_e32 v66, v144, v11
	v_fmac_f32_e32 v67, v145, v12
	v_fmac_f32_e32 v66, v146, v13
	v_fmac_f32_e32 v67, v147, v14
	ds_read_b128 v[144:147], v105 offset:47648
	s_waitcnt lgkmcnt(11)
	v_fmac_f32_e32 v66, v148, v15
	v_fmac_f32_e32 v67, v149, v16
	v_fmac_f32_e32 v66, v150, v17
	v_fmac_f32_e32 v67, v151, v18
	ds_read_b128 v[148:151], v105 offset:47664
	s_waitcnt lgkmcnt(11)
	v_fmac_f32_e32 v66, v152, v20
	v_fmac_f32_e32 v67, v153, v21
	v_fmac_f32_e32 v66, v154, v22
	v_fmac_f32_e32 v67, v155, v23
	ds_read_b128 v[152:155], v105 offset:47680
	s_waitcnt lgkmcnt(11)
	v_fmac_f32_e32 v66, v156, v24
	v_fmac_f32_e32 v67, v157, v25
	v_fmac_f32_e32 v66, v158, v26
	v_fmac_f32_e32 v67, v159, v27
	ds_read_b128 v[156:159], v105 offset:47696
	s_waitcnt lgkmcnt(11)
	v_fmac_f32_e32 v66, v160, v28
	v_fmac_f32_e32 v67, v161, v29
	v_fmac_f32_e32 v66, v162, v30
	v_fmac_f32_e32 v67, v163, v31
	ds_read_b128 v[160:163], v105 offset:47712
	s_waitcnt lgkmcnt(11)
	v_fmac_f32_e32 v66, v164, v32
	v_fmac_f32_e32 v67, v165, v33
	v_fmac_f32_e32 v66, v166, v34
	v_fmac_f32_e32 v67, v167, v35
	ds_read_b128 v[164:167], v105 offset:47728
	s_waitcnt lgkmcnt(11)
	v_fmac_f32_e32 v66, v168, v36
	v_fmac_f32_e32 v67, v169, v37
	v_fmac_f32_e32 v66, v170, v38
	v_fmac_f32_e32 v67, v171, v39
	ds_read_b128 v[168:171], v105 offset:47744
	s_waitcnt lgkmcnt(11)
	v_fmac_f32_e32 v66, v172, v40
	v_fmac_f32_e32 v67, v173, v41
	v_fmac_f32_e32 v66, v174, v42
	v_fmac_f32_e32 v67, v175, v43
	ds_read_b128 v[172:175], v105 offset:47760
	s_waitcnt lgkmcnt(11)
	v_fmac_f32_e32 v66, v176, v44
	v_fmac_f32_e32 v67, v177, v45
	v_fmac_f32_e32 v66, v178, v46
	v_fmac_f32_e32 v67, v179, v47
	ds_read_b128 v[176:179], v105 offset:47776
	s_waitcnt lgkmcnt(11)
	v_fmac_f32_e32 v66, v180, v48
	v_fmac_f32_e32 v67, v181, v49
	v_fmac_f32_e32 v66, v182, v50
	v_sub_f32_e32 v51, v51, v66
	v_sub_f32_e32 v51, v51, v67
	ds_read_b128 v[180:183], v105 offset:47792
	s_waitcnt lgkmcnt(11)
	v_mul_f32_e32 v66, v136, v0
	v_mul_f32_e32 v67, v137, v4
	v_fmac_f32_e32 v66, v138, v5
	v_fmac_f32_e32 v67, v139, v6
	ds_read_b128 v[136:139], v105 offset:47872
	s_waitcnt lgkmcnt(11)
	v_fmac_f32_e32 v66, v140, v7
	v_fmac_f32_e32 v67, v141, v8
	v_fmac_f32_e32 v66, v142, v9
	v_fmac_f32_e32 v67, v143, v10
	ds_read_b128 v[140:143], v105 offset:47888
	s_waitcnt lgkmcnt(11)
	v_fmac_f32_e32 v66, v144, v11
	v_fmac_f32_e32 v67, v145, v12
	v_fmac_f32_e32 v66, v146, v13
	v_fmac_f32_e32 v67, v147, v14
	ds_read_b128 v[144:147], v105 offset:47904
	s_waitcnt lgkmcnt(11)
	v_fmac_f32_e32 v66, v148, v15
	v_fmac_f32_e32 v67, v149, v16
	v_fmac_f32_e32 v66, v150, v17
	v_fmac_f32_e32 v67, v151, v18
	ds_read_b128 v[148:151], v105 offset:47920
	s_waitcnt lgkmcnt(11)
	v_fmac_f32_e32 v66, v152, v20
	v_fmac_f32_e32 v67, v153, v21
	v_fmac_f32_e32 v66, v154, v22
	v_fmac_f32_e32 v67, v155, v23
	ds_read_b128 v[152:155], v105 offset:47936
	s_waitcnt lgkmcnt(11)
	v_fmac_f32_e32 v66, v156, v24
	v_fmac_f32_e32 v67, v157, v25
	v_fmac_f32_e32 v66, v158, v26
	v_fmac_f32_e32 v67, v159, v27
	ds_read_b128 v[156:159], v105 offset:47952
	s_waitcnt lgkmcnt(11)
	v_fmac_f32_e32 v66, v160, v28
	v_fmac_f32_e32 v67, v161, v29
	v_fmac_f32_e32 v66, v162, v30
	v_fmac_f32_e32 v67, v163, v31
	ds_read_b128 v[160:163], v105 offset:47968
	s_waitcnt lgkmcnt(11)
	v_fmac_f32_e32 v66, v164, v32
	v_fmac_f32_e32 v67, v165, v33
	v_fmac_f32_e32 v66, v166, v34
	v_fmac_f32_e32 v67, v167, v35
	ds_read_b128 v[164:167], v105 offset:47984
	s_waitcnt lgkmcnt(11)
	v_fmac_f32_e32 v66, v168, v36
	v_fmac_f32_e32 v67, v169, v37
	v_fmac_f32_e32 v66, v170, v38
	v_fmac_f32_e32 v67, v171, v39
	ds_read_b128 v[168:171], v105 offset:48000
	s_waitcnt lgkmcnt(11)
	v_fmac_f32_e32 v66, v172, v40
	v_fmac_f32_e32 v67, v173, v41
	v_fmac_f32_e32 v66, v174, v42
	v_fmac_f32_e32 v67, v175, v43
	ds_read_b128 v[172:175], v105 offset:48016
	s_waitcnt lgkmcnt(11)
	v_fmac_f32_e32 v66, v176, v44
	v_fmac_f32_e32 v67, v177, v45
	v_fmac_f32_e32 v66, v178, v46
	v_fmac_f32_e32 v67, v179, v47
	ds_read_b128 v[176:179], v105 offset:48032
	s_waitcnt lgkmcnt(11)
	v_fmac_f32_e32 v66, v180, v48
	v_fmac_f32_e32 v67, v181, v49
	v_fmac_f32_e32 v66, v182, v50
	v_fmac_f32_e32 v67, v183, v51
	v_sub_f32_e32 v52, v52, v66
	v_sub_f32_e32 v52, v52, v67
	ds_read_b128 v[180:183], v105 offset:48048
	s_waitcnt lgkmcnt(11)
	v_mul_f32_e32 v66, v136, v0
	v_mul_f32_e32 v67, v137, v4
	v_fmac_f32_e32 v66, v138, v5
	v_fmac_f32_e32 v67, v139, v6
	ds_read_b128 v[136:139], v105 offset:48064
	s_waitcnt lgkmcnt(11)
	v_fmac_f32_e32 v66, v140, v7
	v_fmac_f32_e32 v67, v141, v8
	v_fmac_f32_e32 v66, v142, v9
	v_fmac_f32_e32 v67, v143, v10
	ds_read_b128 v[140:143], v105 offset:48128
	s_waitcnt lgkmcnt(11)
	v_fmac_f32_e32 v66, v144, v11
	v_fmac_f32_e32 v67, v145, v12
	v_fmac_f32_e32 v66, v146, v13
	v_fmac_f32_e32 v67, v147, v14
	ds_read_b128 v[144:147], v105 offset:48144
	s_waitcnt lgkmcnt(11)
	v_fmac_f32_e32 v66, v148, v15
	v_fmac_f32_e32 v67, v149, v16
	v_fmac_f32_e32 v66, v150, v17
	v_fmac_f32_e32 v67, v151, v18
	ds_read_b128 v[148:151], v105 offset:48160
	s_waitcnt lgkmcnt(11)
	v_fmac_f32_e32 v66, v152, v20
	v_fmac_f32_e32 v67, v153, v21
	v_fmac_f32_e32 v66, v154, v22
	v_fmac_f32_e32 v67, v155, v23
	ds_read_b128 v[152:155], v105 offset:48176
	s_waitcnt lgkmcnt(11)
	v_fmac_f32_e32 v66, v156, v24
	v_fmac_f32_e32 v67, v157, v25
	v_fmac_f32_e32 v66, v158, v26
	v_fmac_f32_e32 v67, v159, v27
	ds_read_b128 v[156:159], v105 offset:48192
	s_waitcnt lgkmcnt(11)
	v_fmac_f32_e32 v66, v160, v28
	v_fmac_f32_e32 v67, v161, v29
	v_fmac_f32_e32 v66, v162, v30
	v_fmac_f32_e32 v67, v163, v31
	ds_read_b128 v[160:163], v105 offset:48208
	s_waitcnt lgkmcnt(11)
	v_fmac_f32_e32 v66, v164, v32
	v_fmac_f32_e32 v67, v165, v33
	v_fmac_f32_e32 v66, v166, v34
	v_fmac_f32_e32 v67, v167, v35
	ds_read_b128 v[164:167], v105 offset:48224
	s_waitcnt lgkmcnt(11)
	v_fmac_f32_e32 v66, v168, v36
	v_fmac_f32_e32 v67, v169, v37
	v_fmac_f32_e32 v66, v170, v38
	v_fmac_f32_e32 v67, v171, v39
	ds_read_b128 v[168:171], v105 offset:48240
	s_waitcnt lgkmcnt(11)
	v_fmac_f32_e32 v66, v172, v40
	v_fmac_f32_e32 v67, v173, v41
	v_fmac_f32_e32 v66, v174, v42
	v_fmac_f32_e32 v67, v175, v43
	ds_read_b128 v[172:175], v105 offset:48256
	s_waitcnt lgkmcnt(11)
	v_fmac_f32_e32 v66, v176, v44
	v_fmac_f32_e32 v67, v177, v45
	v_fmac_f32_e32 v66, v178, v46
	v_fmac_f32_e32 v67, v179, v47
	ds_read_b128 v[176:179], v105 offset:48272
	s_waitcnt lgkmcnt(11)
	v_fmac_f32_e32 v66, v180, v48
	v_fmac_f32_e32 v67, v181, v49
	v_fmac_f32_e32 v66, v182, v50
	v_fmac_f32_e32 v67, v183, v51
	ds_read_b128 v[180:183], v105 offset:48288
	s_waitcnt lgkmcnt(11)
	v_fmac_f32_e32 v66, v136, v52
	v_sub_f32_e32 v53, v53, v66
	v_sub_f32_e32 v53, v53, v67
	ds_read_b128 v[136:139], v105 offset:48304
	s_waitcnt lgkmcnt(11)
	v_mul_f32_e32 v66, v140, v0
	v_mul_f32_e32 v67, v141, v4
	v_fmac_f32_e32 v66, v142, v5
	v_fmac_f32_e32 v67, v143, v6
	ds_read_b128 v[140:143], v105 offset:48320
	s_waitcnt lgkmcnt(11)
	v_fmac_f32_e32 v66, v144, v7
	v_fmac_f32_e32 v67, v145, v8
	v_fmac_f32_e32 v66, v146, v9
	v_fmac_f32_e32 v67, v147, v10
	ds_read_b128 v[144:147], v105 offset:48384
	s_waitcnt lgkmcnt(11)
	v_fmac_f32_e32 v66, v148, v11
	v_fmac_f32_e32 v67, v149, v12
	v_fmac_f32_e32 v66, v150, v13
	v_fmac_f32_e32 v67, v151, v14
	ds_read_b128 v[148:151], v105 offset:48400
	s_waitcnt lgkmcnt(11)
	v_fmac_f32_e32 v66, v152, v15
	v_fmac_f32_e32 v67, v153, v16
	v_fmac_f32_e32 v66, v154, v17
	v_fmac_f32_e32 v67, v155, v18
	ds_read_b128 v[152:155], v105 offset:48416
	s_waitcnt lgkmcnt(11)
	v_fmac_f32_e32 v66, v156, v20
	v_fmac_f32_e32 v67, v157, v21
	v_fmac_f32_e32 v66, v158, v22
	v_fmac_f32_e32 v67, v159, v23
	ds_read_b128 v[156:159], v105 offset:48432
	s_waitcnt lgkmcnt(11)
	v_fmac_f32_e32 v66, v160, v24
	v_fmac_f32_e32 v67, v161, v25
	v_fmac_f32_e32 v66, v162, v26
	v_fmac_f32_e32 v67, v163, v27
	ds_read_b128 v[160:163], v105 offset:48448
	s_waitcnt lgkmcnt(11)
	v_fmac_f32_e32 v66, v164, v28
	v_fmac_f32_e32 v67, v165, v29
	v_fmac_f32_e32 v66, v166, v30
	v_fmac_f32_e32 v67, v167, v31
	ds_read_b128 v[164:167], v105 offset:48464
	s_waitcnt lgkmcnt(11)
	v_fmac_f32_e32 v66, v168, v32
	v_fmac_f32_e32 v67, v169, v33
	v_fmac_f32_e32 v66, v170, v34
	v_fmac_f32_e32 v67, v171, v35
	ds_read_b128 v[168:171], v105 offset:48480
	s_waitcnt lgkmcnt(11)
	v_fmac_f32_e32 v66, v172, v36
	v_fmac_f32_e32 v67, v173, v37
	v_fmac_f32_e32 v66, v174, v38
	v_fmac_f32_e32 v67, v175, v39
	ds_read_b128 v[172:175], v105 offset:48496
	s_waitcnt lgkmcnt(11)
	v_fmac_f32_e32 v66, v176, v40
	v_fmac_f32_e32 v67, v177, v41
	v_fmac_f32_e32 v66, v178, v42
	v_fmac_f32_e32 v67, v179, v43
	ds_read_b128 v[176:179], v105 offset:48512
	s_waitcnt lgkmcnt(11)
	v_fmac_f32_e32 v66, v180, v44
	v_fmac_f32_e32 v67, v181, v45
	v_fmac_f32_e32 v66, v182, v46
	v_fmac_f32_e32 v67, v183, v47
	ds_read_b128 v[180:183], v105 offset:48528
	s_waitcnt lgkmcnt(11)
	v_fmac_f32_e32 v66, v136, v48
	v_fmac_f32_e32 v67, v137, v49
	v_fmac_f32_e32 v66, v138, v50
	v_fmac_f32_e32 v67, v139, v51
	ds_read_b128 v[136:139], v105 offset:48544
	s_waitcnt lgkmcnt(11)
	v_fmac_f32_e32 v66, v140, v52
	v_fmac_f32_e32 v67, v141, v53
	v_sub_f32_e32 v54, v54, v66
	v_sub_f32_e32 v54, v54, v67
	ds_read_b128 v[140:143], v105 offset:48560
	s_waitcnt lgkmcnt(11)
	v_mul_f32_e32 v66, v144, v0
	v_mul_f32_e32 v67, v145, v4
	v_fmac_f32_e32 v66, v146, v5
	v_fmac_f32_e32 v67, v147, v6
	ds_read_b128 v[144:147], v105 offset:48576
	s_waitcnt lgkmcnt(11)
	v_fmac_f32_e32 v66, v148, v7
	v_fmac_f32_e32 v67, v149, v8
	v_fmac_f32_e32 v66, v150, v9
	v_fmac_f32_e32 v67, v151, v10
	ds_read_b128 v[148:151], v105 offset:48640
	s_waitcnt lgkmcnt(11)
	v_fmac_f32_e32 v66, v152, v11
	v_fmac_f32_e32 v67, v153, v12
	v_fmac_f32_e32 v66, v154, v13
	v_fmac_f32_e32 v67, v155, v14
	ds_read_b128 v[152:155], v105 offset:48656
	s_waitcnt lgkmcnt(11)
	v_fmac_f32_e32 v66, v156, v15
	v_fmac_f32_e32 v67, v157, v16
	v_fmac_f32_e32 v66, v158, v17
	v_fmac_f32_e32 v67, v159, v18
	ds_read_b128 v[156:159], v105 offset:48672
	s_waitcnt lgkmcnt(11)
	v_fmac_f32_e32 v66, v160, v20
	v_fmac_f32_e32 v67, v161, v21
	v_fmac_f32_e32 v66, v162, v22
	v_fmac_f32_e32 v67, v163, v23
	ds_read_b128 v[160:163], v105 offset:48688
	s_waitcnt lgkmcnt(11)
	v_fmac_f32_e32 v66, v164, v24
	v_fmac_f32_e32 v67, v165, v25
	v_fmac_f32_e32 v66, v166, v26
	v_fmac_f32_e32 v67, v167, v27
	ds_read_b128 v[164:167], v105 offset:48704
	s_waitcnt lgkmcnt(11)
	v_fmac_f32_e32 v66, v168, v28
	v_fmac_f32_e32 v67, v169, v29
	v_fmac_f32_e32 v66, v170, v30
	v_fmac_f32_e32 v67, v171, v31
	ds_read_b128 v[168:171], v105 offset:48720
	s_waitcnt lgkmcnt(11)
	v_fmac_f32_e32 v66, v172, v32
	v_fmac_f32_e32 v67, v173, v33
	v_fmac_f32_e32 v66, v174, v34
	v_fmac_f32_e32 v67, v175, v35
	ds_read_b128 v[172:175], v105 offset:48736
	s_waitcnt lgkmcnt(11)
	v_fmac_f32_e32 v66, v176, v36
	v_fmac_f32_e32 v67, v177, v37
	v_fmac_f32_e32 v66, v178, v38
	v_fmac_f32_e32 v67, v179, v39
	ds_read_b128 v[176:179], v105 offset:48752
	s_waitcnt lgkmcnt(11)
	v_fmac_f32_e32 v66, v180, v40
	v_fmac_f32_e32 v67, v181, v41
	v_fmac_f32_e32 v66, v182, v42
	v_fmac_f32_e32 v67, v183, v43
	ds_read_b128 v[180:183], v105 offset:48768
	s_waitcnt lgkmcnt(11)
	v_fmac_f32_e32 v66, v136, v44
	v_fmac_f32_e32 v67, v137, v45
	v_fmac_f32_e32 v66, v138, v46
	v_fmac_f32_e32 v67, v139, v47
	ds_read_b128 v[136:139], v105 offset:48784
	s_waitcnt lgkmcnt(11)
	v_fmac_f32_e32 v66, v140, v48
	v_fmac_f32_e32 v67, v141, v49
	v_fmac_f32_e32 v66, v142, v50
	v_fmac_f32_e32 v67, v143, v51
	ds_read_b128 v[140:143], v105 offset:48800
	s_waitcnt lgkmcnt(11)
	v_fmac_f32_e32 v66, v144, v52
	v_fmac_f32_e32 v67, v145, v53
	v_fmac_f32_e32 v66, v146, v54
	v_sub_f32_e32 v55, v55, v66
	v_sub_f32_e32 v55, v55, v67
	ds_read_b128 v[144:147], v105 offset:48816
	s_waitcnt lgkmcnt(11)
	v_mul_f32_e32 v66, v148, v0
	v_mul_f32_e32 v67, v149, v4
	v_fmac_f32_e32 v66, v150, v5
	v_fmac_f32_e32 v67, v151, v6
	ds_read_b128 v[148:151], v105 offset:48832
	s_waitcnt lgkmcnt(11)
	v_fmac_f32_e32 v66, v152, v7
	v_fmac_f32_e32 v67, v153, v8
	v_fmac_f32_e32 v66, v154, v9
	v_fmac_f32_e32 v67, v155, v10
	ds_read_b128 v[152:155], v105 offset:48896
	s_waitcnt lgkmcnt(11)
	v_fmac_f32_e32 v66, v156, v11
	v_fmac_f32_e32 v67, v157, v12
	v_fmac_f32_e32 v66, v158, v13
	v_fmac_f32_e32 v67, v159, v14
	ds_read_b128 v[156:159], v105 offset:48912
	s_waitcnt lgkmcnt(11)
	v_fmac_f32_e32 v66, v160, v15
	v_fmac_f32_e32 v67, v161, v16
	v_fmac_f32_e32 v66, v162, v17
	v_fmac_f32_e32 v67, v163, v18
	ds_read_b128 v[160:163], v105 offset:48928
	s_waitcnt lgkmcnt(11)
	v_fmac_f32_e32 v66, v164, v20
	v_fmac_f32_e32 v67, v165, v21
	v_fmac_f32_e32 v66, v166, v22
	v_fmac_f32_e32 v67, v167, v23
	ds_read_b128 v[164:167], v105 offset:48944
	s_waitcnt lgkmcnt(11)
	v_fmac_f32_e32 v66, v168, v24
	v_fmac_f32_e32 v67, v169, v25
	v_fmac_f32_e32 v66, v170, v26
	v_fmac_f32_e32 v67, v171, v27
	ds_read_b128 v[168:171], v105 offset:48960
	s_waitcnt lgkmcnt(11)
	v_fmac_f32_e32 v66, v172, v28
	v_fmac_f32_e32 v67, v173, v29
	v_fmac_f32_e32 v66, v174, v30
	v_fmac_f32_e32 v67, v175, v31
	ds_read_b128 v[172:175], v105 offset:48976
	s_waitcnt lgkmcnt(11)
	v_fmac_f32_e32 v66, v176, v32
	v_fmac_f32_e32 v67, v177, v33
	v_fmac_f32_e32 v66, v178, v34
	v_fmac_f32_e32 v67, v179, v35
	ds_read_b128 v[176:179], v105 offset:48992
	s_waitcnt lgkmcnt(11)
	v_fmac_f32_e32 v66, v180, v36
	v_fmac_f32_e32 v67, v181, v37
	v_fmac_f32_e32 v66, v182, v38
	v_fmac_f32_e32 v67, v183, v39
	ds_read_b128 v[180:183], v105 offset:49008
	s_waitcnt lgkmcnt(11)
	v_fmac_f32_e32 v66, v136, v40
	v_fmac_f32_e32 v67, v137, v41
	v_fmac_f32_e32 v66, v138, v42
	v_fmac_f32_e32 v67, v139, v43
	ds_read_b128 v[136:139], v105 offset:49024
	s_waitcnt lgkmcnt(11)
	v_fmac_f32_e32 v66, v140, v44
	v_fmac_f32_e32 v67, v141, v45
	v_fmac_f32_e32 v66, v142, v46
	v_fmac_f32_e32 v67, v143, v47
	ds_read_b128 v[140:143], v105 offset:49040
	s_waitcnt lgkmcnt(11)
	v_fmac_f32_e32 v66, v144, v48
	v_fmac_f32_e32 v67, v145, v49
	v_fmac_f32_e32 v66, v146, v50
	v_fmac_f32_e32 v67, v147, v51
	ds_read_b128 v[144:147], v105 offset:49056
	s_waitcnt lgkmcnt(11)
	v_fmac_f32_e32 v66, v148, v52
	v_fmac_f32_e32 v67, v149, v53
	v_fmac_f32_e32 v66, v150, v54
	v_fmac_f32_e32 v67, v151, v55
	v_sub_f32_e32 v56, v56, v66
	v_sub_f32_e32 v56, v56, v67
	ds_read_b128 v[148:151], v105 offset:49072
	s_waitcnt lgkmcnt(11)
	v_mul_f32_e32 v66, v152, v0
	v_mul_f32_e32 v67, v153, v4
	v_fmac_f32_e32 v66, v154, v5
	v_fmac_f32_e32 v67, v155, v6
	ds_read_b128 v[152:155], v105 offset:49088
	s_waitcnt lgkmcnt(11)
	v_fmac_f32_e32 v66, v156, v7
	v_fmac_f32_e32 v67, v157, v8
	v_fmac_f32_e32 v66, v158, v9
	v_fmac_f32_e32 v67, v159, v10
	ds_read_b128 v[156:159], v105 offset:49104
	s_waitcnt lgkmcnt(11)
	v_fmac_f32_e32 v66, v160, v11
	v_fmac_f32_e32 v67, v161, v12
	v_fmac_f32_e32 v66, v162, v13
	v_fmac_f32_e32 v67, v163, v14
	ds_read_b128 v[160:163], v105 offset:49152
	s_waitcnt lgkmcnt(11)
	v_fmac_f32_e32 v66, v164, v15
	v_fmac_f32_e32 v67, v165, v16
	v_fmac_f32_e32 v66, v166, v17
	v_fmac_f32_e32 v67, v167, v18
	ds_read_b128 v[164:167], v105 offset:49168
	s_waitcnt lgkmcnt(11)
	v_fmac_f32_e32 v66, v168, v20
	v_fmac_f32_e32 v67, v169, v21
	v_fmac_f32_e32 v66, v170, v22
	v_fmac_f32_e32 v67, v171, v23
	ds_read_b128 v[168:171], v105 offset:49184
	s_waitcnt lgkmcnt(11)
	v_fmac_f32_e32 v66, v172, v24
	v_fmac_f32_e32 v67, v173, v25
	v_fmac_f32_e32 v66, v174, v26
	v_fmac_f32_e32 v67, v175, v27
	ds_read_b128 v[172:175], v105 offset:49200
	s_waitcnt lgkmcnt(11)
	v_fmac_f32_e32 v66, v176, v28
	v_fmac_f32_e32 v67, v177, v29
	v_fmac_f32_e32 v66, v178, v30
	v_fmac_f32_e32 v67, v179, v31
	ds_read_b128 v[176:179], v105 offset:49216
	s_waitcnt lgkmcnt(11)
	v_fmac_f32_e32 v66, v180, v32
	v_fmac_f32_e32 v67, v181, v33
	v_fmac_f32_e32 v66, v182, v34
	v_fmac_f32_e32 v67, v183, v35
	ds_read_b128 v[180:183], v105 offset:49232
	s_waitcnt lgkmcnt(11)
	v_fmac_f32_e32 v66, v136, v36
	v_fmac_f32_e32 v67, v137, v37
	v_fmac_f32_e32 v66, v138, v38
	v_fmac_f32_e32 v67, v139, v39
	ds_read_b128 v[136:139], v105 offset:49248
	s_waitcnt lgkmcnt(11)
	v_fmac_f32_e32 v66, v140, v40
	v_fmac_f32_e32 v67, v141, v41
	v_fmac_f32_e32 v66, v142, v42
	v_fmac_f32_e32 v67, v143, v43
	ds_read_b128 v[140:143], v105 offset:49264
	s_waitcnt lgkmcnt(11)
	v_fmac_f32_e32 v66, v144, v44
	v_fmac_f32_e32 v67, v145, v45
	v_fmac_f32_e32 v66, v146, v46
	v_fmac_f32_e32 v67, v147, v47
	ds_read_b128 v[144:147], v105 offset:49280
	s_waitcnt lgkmcnt(11)
	v_fmac_f32_e32 v66, v148, v48
	v_fmac_f32_e32 v67, v149, v49
	v_fmac_f32_e32 v66, v150, v50
	v_fmac_f32_e32 v67, v151, v51
	ds_read_b128 v[148:151], v105 offset:49296
	s_waitcnt lgkmcnt(11)
	v_fmac_f32_e32 v66, v152, v52
	v_fmac_f32_e32 v67, v153, v53
	v_fmac_f32_e32 v66, v154, v54
	v_fmac_f32_e32 v67, v155, v55
	ds_read_b128 v[152:155], v105 offset:49312
	s_waitcnt lgkmcnt(11)
	v_fmac_f32_e32 v66, v156, v56
	v_sub_f32_e32 v57, v57, v66
	v_sub_f32_e32 v57, v57, v67
	ds_read_b128 v[156:159], v105 offset:49328
	s_waitcnt lgkmcnt(11)
	v_mul_f32_e32 v66, v160, v0
	v_mul_f32_e32 v67, v161, v4
	v_fmac_f32_e32 v66, v162, v5
	v_fmac_f32_e32 v67, v163, v6
	ds_read_b128 v[160:163], v105 offset:49344
	s_waitcnt lgkmcnt(11)
	v_fmac_f32_e32 v66, v164, v7
	v_fmac_f32_e32 v67, v165, v8
	v_fmac_f32_e32 v66, v166, v9
	v_fmac_f32_e32 v67, v167, v10
	ds_read_b128 v[164:167], v105 offset:49360
	s_waitcnt lgkmcnt(11)
	v_fmac_f32_e32 v66, v168, v11
	v_fmac_f32_e32 v67, v169, v12
	v_fmac_f32_e32 v66, v170, v13
	v_fmac_f32_e32 v67, v171, v14
	ds_read_b128 v[168:171], v105 offset:49408
	s_waitcnt lgkmcnt(11)
	v_fmac_f32_e32 v66, v172, v15
	v_fmac_f32_e32 v67, v173, v16
	v_fmac_f32_e32 v66, v174, v17
	v_fmac_f32_e32 v67, v175, v18
	ds_read_b128 v[172:175], v105 offset:49424
	s_waitcnt lgkmcnt(11)
	v_fmac_f32_e32 v66, v176, v20
	v_fmac_f32_e32 v67, v177, v21
	v_fmac_f32_e32 v66, v178, v22
	v_fmac_f32_e32 v67, v179, v23
	ds_read_b128 v[176:179], v105 offset:49440
	s_waitcnt lgkmcnt(11)
	v_fmac_f32_e32 v66, v180, v24
	v_fmac_f32_e32 v67, v181, v25
	v_fmac_f32_e32 v66, v182, v26
	v_fmac_f32_e32 v67, v183, v27
	ds_read_b128 v[180:183], v105 offset:49456
	s_waitcnt lgkmcnt(11)
	v_fmac_f32_e32 v66, v136, v28
	v_fmac_f32_e32 v67, v137, v29
	v_fmac_f32_e32 v66, v138, v30
	v_fmac_f32_e32 v67, v139, v31
	ds_read_b128 v[136:139], v105 offset:49472
	s_waitcnt lgkmcnt(11)
	v_fmac_f32_e32 v66, v140, v32
	v_fmac_f32_e32 v67, v141, v33
	v_fmac_f32_e32 v66, v142, v34
	v_fmac_f32_e32 v67, v143, v35
	ds_read_b128 v[140:143], v105 offset:49488
	s_waitcnt lgkmcnt(11)
	v_fmac_f32_e32 v66, v144, v36
	v_fmac_f32_e32 v67, v145, v37
	v_fmac_f32_e32 v66, v146, v38
	v_fmac_f32_e32 v67, v147, v39
	ds_read_b128 v[144:147], v105 offset:49504
	s_waitcnt lgkmcnt(11)
	v_fmac_f32_e32 v66, v148, v40
	v_fmac_f32_e32 v67, v149, v41
	v_fmac_f32_e32 v66, v150, v42
	v_fmac_f32_e32 v67, v151, v43
	ds_read_b128 v[148:151], v105 offset:49520
	s_waitcnt lgkmcnt(11)
	v_fmac_f32_e32 v66, v152, v44
	v_fmac_f32_e32 v67, v153, v45
	v_fmac_f32_e32 v66, v154, v46
	v_fmac_f32_e32 v67, v155, v47
	ds_read_b128 v[152:155], v105 offset:49536
	s_waitcnt lgkmcnt(11)
	v_fmac_f32_e32 v66, v156, v48
	v_fmac_f32_e32 v67, v157, v49
	v_fmac_f32_e32 v66, v158, v50
	v_fmac_f32_e32 v67, v159, v51
	ds_read_b128 v[156:159], v105 offset:49552
	s_waitcnt lgkmcnt(11)
	v_fmac_f32_e32 v66, v160, v52
	v_fmac_f32_e32 v67, v161, v53
	v_fmac_f32_e32 v66, v162, v54
	v_fmac_f32_e32 v67, v163, v55
	ds_read_b128 v[160:163], v105 offset:49568
	s_waitcnt lgkmcnt(11)
	v_fmac_f32_e32 v66, v164, v56
	v_fmac_f32_e32 v67, v165, v57
	v_sub_f32_e32 v58, v58, v66
	v_sub_f32_e32 v58, v58, v67
	ds_read_b128 v[164:167], v105 offset:49584
	s_waitcnt lgkmcnt(11)
	v_mul_f32_e32 v66, v168, v0
	v_mul_f32_e32 v67, v169, v4
	v_fmac_f32_e32 v66, v170, v5
	v_fmac_f32_e32 v67, v171, v6
	ds_read_b128 v[168:171], v105 offset:49600
	s_waitcnt lgkmcnt(11)
	v_fmac_f32_e32 v66, v172, v7
	v_fmac_f32_e32 v67, v173, v8
	v_fmac_f32_e32 v66, v174, v9
	v_fmac_f32_e32 v67, v175, v10
	ds_read_b128 v[172:175], v105 offset:49616
	s_waitcnt lgkmcnt(11)
	v_fmac_f32_e32 v66, v176, v11
	v_fmac_f32_e32 v67, v177, v12
	v_fmac_f32_e32 v66, v178, v13
	v_fmac_f32_e32 v67, v179, v14
	ds_read_b128 v[176:179], v105 offset:49664
	s_waitcnt lgkmcnt(11)
	v_fmac_f32_e32 v66, v180, v15
	v_fmac_f32_e32 v67, v181, v16
	v_fmac_f32_e32 v66, v182, v17
	v_fmac_f32_e32 v67, v183, v18
	ds_read_b128 v[180:183], v105 offset:49680
	s_waitcnt lgkmcnt(11)
	v_fmac_f32_e32 v66, v136, v20
	v_fmac_f32_e32 v67, v137, v21
	v_fmac_f32_e32 v66, v138, v22
	v_fmac_f32_e32 v67, v139, v23
	ds_read_b128 v[136:139], v105 offset:49696
	s_waitcnt lgkmcnt(11)
	v_fmac_f32_e32 v66, v140, v24
	v_fmac_f32_e32 v67, v141, v25
	v_fmac_f32_e32 v66, v142, v26
	v_fmac_f32_e32 v67, v143, v27
	ds_read_b128 v[140:143], v105 offset:49712
	s_waitcnt lgkmcnt(11)
	v_fmac_f32_e32 v66, v144, v28
	v_fmac_f32_e32 v67, v145, v29
	v_fmac_f32_e32 v66, v146, v30
	v_fmac_f32_e32 v67, v147, v31
	ds_read_b128 v[144:147], v105 offset:49728
	s_waitcnt lgkmcnt(11)
	v_fmac_f32_e32 v66, v148, v32
	v_fmac_f32_e32 v67, v149, v33
	v_fmac_f32_e32 v66, v150, v34
	v_fmac_f32_e32 v67, v151, v35
	ds_read_b128 v[148:151], v105 offset:49744
	s_waitcnt lgkmcnt(11)
	v_fmac_f32_e32 v66, v152, v36
	v_fmac_f32_e32 v67, v153, v37
	v_fmac_f32_e32 v66, v154, v38
	v_fmac_f32_e32 v67, v155, v39
	ds_read_b128 v[152:155], v105 offset:49760
	s_waitcnt lgkmcnt(11)
	v_fmac_f32_e32 v66, v156, v40
	v_fmac_f32_e32 v67, v157, v41
	v_fmac_f32_e32 v66, v158, v42
	v_fmac_f32_e32 v67, v159, v43
	ds_read_b128 v[156:159], v105 offset:49776
	s_waitcnt lgkmcnt(11)
	v_fmac_f32_e32 v66, v160, v44
	v_fmac_f32_e32 v67, v161, v45
	v_fmac_f32_e32 v66, v162, v46
	v_fmac_f32_e32 v67, v163, v47
	ds_read_b128 v[160:163], v105 offset:49792
	s_waitcnt lgkmcnt(11)
	v_fmac_f32_e32 v66, v164, v48
	v_fmac_f32_e32 v67, v165, v49
	v_fmac_f32_e32 v66, v166, v50
	v_fmac_f32_e32 v67, v167, v51
	ds_read_b128 v[164:167], v105 offset:49808
	s_waitcnt lgkmcnt(11)
	v_fmac_f32_e32 v66, v168, v52
	v_fmac_f32_e32 v67, v169, v53
	v_fmac_f32_e32 v66, v170, v54
	v_fmac_f32_e32 v67, v171, v55
	ds_read_b128 v[168:171], v105 offset:49824
	s_waitcnt lgkmcnt(11)
	v_fmac_f32_e32 v66, v172, v56
	v_fmac_f32_e32 v67, v173, v57
	v_fmac_f32_e32 v66, v174, v58
	v_sub_f32_e32 v59, v59, v66
	v_sub_f32_e32 v59, v59, v67
	ds_read_b128 v[172:175], v105 offset:49840
	s_waitcnt lgkmcnt(11)
	v_mul_f32_e32 v66, v176, v0
	v_mul_f32_e32 v67, v177, v4
	v_fmac_f32_e32 v66, v178, v5
	v_fmac_f32_e32 v67, v179, v6
	ds_read_b128 v[176:179], v105 offset:49856
	s_waitcnt lgkmcnt(11)
	v_fmac_f32_e32 v66, v180, v7
	v_fmac_f32_e32 v67, v181, v8
	v_fmac_f32_e32 v66, v182, v9
	v_fmac_f32_e32 v67, v183, v10
	ds_read_b128 v[180:183], v105 offset:49872
	s_waitcnt lgkmcnt(11)
	v_fmac_f32_e32 v66, v136, v11
	v_fmac_f32_e32 v67, v137, v12
	v_fmac_f32_e32 v66, v138, v13
	v_fmac_f32_e32 v67, v139, v14
	ds_read_b128 v[136:139], v105 offset:49920
	s_waitcnt lgkmcnt(11)
	v_fmac_f32_e32 v66, v140, v15
	v_fmac_f32_e32 v67, v141, v16
	v_fmac_f32_e32 v66, v142, v17
	v_fmac_f32_e32 v67, v143, v18
	ds_read_b128 v[140:143], v105 offset:49936
	s_waitcnt lgkmcnt(11)
	v_fmac_f32_e32 v66, v144, v20
	v_fmac_f32_e32 v67, v145, v21
	v_fmac_f32_e32 v66, v146, v22
	v_fmac_f32_e32 v67, v147, v23
	ds_read_b128 v[144:147], v105 offset:49952
	s_waitcnt lgkmcnt(11)
	v_fmac_f32_e32 v66, v148, v24
	v_fmac_f32_e32 v67, v149, v25
	v_fmac_f32_e32 v66, v150, v26
	v_fmac_f32_e32 v67, v151, v27
	ds_read_b128 v[148:151], v105 offset:49968
	s_waitcnt lgkmcnt(11)
	v_fmac_f32_e32 v66, v152, v28
	v_fmac_f32_e32 v67, v153, v29
	v_fmac_f32_e32 v66, v154, v30
	v_fmac_f32_e32 v67, v155, v31
	ds_read_b128 v[152:155], v105 offset:49984
	s_waitcnt lgkmcnt(11)
	v_fmac_f32_e32 v66, v156, v32
	v_fmac_f32_e32 v67, v157, v33
	v_fmac_f32_e32 v66, v158, v34
	v_fmac_f32_e32 v67, v159, v35
	ds_read_b128 v[156:159], v105 offset:50000
	s_waitcnt lgkmcnt(11)
	v_fmac_f32_e32 v66, v160, v36
	v_fmac_f32_e32 v67, v161, v37
	v_fmac_f32_e32 v66, v162, v38
	v_fmac_f32_e32 v67, v163, v39
	ds_read_b128 v[160:163], v105 offset:50016
	s_waitcnt lgkmcnt(11)
	v_fmac_f32_e32 v66, v164, v40
	v_fmac_f32_e32 v67, v165, v41
	v_fmac_f32_e32 v66, v166, v42
	v_fmac_f32_e32 v67, v167, v43
	ds_read_b128 v[164:167], v105 offset:50032
	s_waitcnt lgkmcnt(11)
	v_fmac_f32_e32 v66, v168, v44
	v_fmac_f32_e32 v67, v169, v45
	v_fmac_f32_e32 v66, v170, v46
	v_fmac_f32_e32 v67, v171, v47
	ds_read_b128 v[168:171], v105 offset:50048
	s_waitcnt lgkmcnt(11)
	v_fmac_f32_e32 v66, v172, v48
	v_fmac_f32_e32 v67, v173, v49
	v_fmac_f32_e32 v66, v174, v50
	v_fmac_f32_e32 v67, v175, v51
	ds_read_b128 v[172:175], v105 offset:50064
	s_waitcnt lgkmcnt(11)
	v_fmac_f32_e32 v66, v176, v52
	v_fmac_f32_e32 v67, v177, v53
	v_fmac_f32_e32 v66, v178, v54
	v_fmac_f32_e32 v67, v179, v55
	ds_read_b128 v[176:179], v105 offset:50080
	s_waitcnt lgkmcnt(11)
	v_fmac_f32_e32 v66, v180, v56
	v_fmac_f32_e32 v67, v181, v57
	v_fmac_f32_e32 v66, v182, v58
	v_fmac_f32_e32 v67, v183, v59
	v_sub_f32_e32 v60, v60, v66
	v_sub_f32_e32 v60, v60, v67
	ds_read_b128 v[180:183], v105 offset:50096
	s_waitcnt lgkmcnt(11)
	v_mul_f32_e32 v66, v136, v0
	v_mul_f32_e32 v67, v137, v4
	v_fmac_f32_e32 v66, v138, v5
	v_fmac_f32_e32 v67, v139, v6
	ds_read_b128 v[136:139], v105 offset:50112
	s_waitcnt lgkmcnt(11)
	v_fmac_f32_e32 v66, v140, v7
	v_fmac_f32_e32 v67, v141, v8
	v_fmac_f32_e32 v66, v142, v9
	v_fmac_f32_e32 v67, v143, v10
	ds_read_b128 v[140:143], v105 offset:50128
	s_waitcnt lgkmcnt(11)
	v_fmac_f32_e32 v66, v144, v11
	v_fmac_f32_e32 v67, v145, v12
	v_fmac_f32_e32 v66, v146, v13
	v_fmac_f32_e32 v67, v147, v14
	ds_read_b128 v[144:147], v105 offset:50144
	s_waitcnt lgkmcnt(11)
	v_fmac_f32_e32 v66, v148, v15
	v_fmac_f32_e32 v67, v149, v16
	v_fmac_f32_e32 v66, v150, v17
	v_fmac_f32_e32 v67, v151, v18
	ds_read_b128 v[148:151], v105 offset:50176
	s_waitcnt lgkmcnt(11)
	v_fmac_f32_e32 v66, v152, v20
	v_fmac_f32_e32 v67, v153, v21
	v_fmac_f32_e32 v66, v154, v22
	v_fmac_f32_e32 v67, v155, v23
	ds_read_b128 v[152:155], v105 offset:50192
	s_waitcnt lgkmcnt(11)
	v_fmac_f32_e32 v66, v156, v24
	v_fmac_f32_e32 v67, v157, v25
	v_fmac_f32_e32 v66, v158, v26
	v_fmac_f32_e32 v67, v159, v27
	ds_read_b128 v[156:159], v105 offset:50208
	s_waitcnt lgkmcnt(11)
	v_fmac_f32_e32 v66, v160, v28
	v_fmac_f32_e32 v67, v161, v29
	v_fmac_f32_e32 v66, v162, v30
	v_fmac_f32_e32 v67, v163, v31
	ds_read_b128 v[160:163], v105 offset:50224
	s_waitcnt lgkmcnt(11)
	v_fmac_f32_e32 v66, v164, v32
	v_fmac_f32_e32 v67, v165, v33
	v_fmac_f32_e32 v66, v166, v34
	v_fmac_f32_e32 v67, v167, v35
	ds_read_b128 v[164:167], v105 offset:50240
	s_waitcnt lgkmcnt(11)
	v_fmac_f32_e32 v66, v168, v36
	v_fmac_f32_e32 v67, v169, v37
	v_fmac_f32_e32 v66, v170, v38
	v_fmac_f32_e32 v67, v171, v39
	ds_read_b128 v[168:171], v105 offset:50256
	s_waitcnt lgkmcnt(11)
	v_fmac_f32_e32 v66, v172, v40
	v_fmac_f32_e32 v67, v173, v41
	v_fmac_f32_e32 v66, v174, v42
	v_fmac_f32_e32 v67, v175, v43
	ds_read_b128 v[172:175], v105 offset:50272
	s_waitcnt lgkmcnt(11)
	v_fmac_f32_e32 v66, v176, v44
	v_fmac_f32_e32 v67, v177, v45
	v_fmac_f32_e32 v66, v178, v46
	v_fmac_f32_e32 v67, v179, v47
	ds_read_b128 v[176:179], v105 offset:50288
	s_waitcnt lgkmcnt(11)
	v_fmac_f32_e32 v66, v180, v48
	v_fmac_f32_e32 v67, v181, v49
	v_fmac_f32_e32 v66, v182, v50
	v_fmac_f32_e32 v67, v183, v51
	ds_read_b128 v[180:183], v105 offset:50304
	s_waitcnt lgkmcnt(11)
	v_fmac_f32_e32 v66, v136, v52
	v_fmac_f32_e32 v67, v137, v53
	v_fmac_f32_e32 v66, v138, v54
	v_fmac_f32_e32 v67, v139, v55
	ds_read_b128 v[136:139], v105 offset:50320
	s_waitcnt lgkmcnt(11)
	v_fmac_f32_e32 v66, v140, v56
	v_fmac_f32_e32 v67, v141, v57
	v_fmac_f32_e32 v66, v142, v58
	v_fmac_f32_e32 v67, v143, v59
	ds_read_b128 v[140:143], v105 offset:50336
	s_waitcnt lgkmcnt(11)
	v_fmac_f32_e32 v66, v144, v60
	v_sub_f32_e32 v61, v61, v66
	v_sub_f32_e32 v61, v61, v67
	ds_read_b128 v[144:147], v105 offset:50352
	s_waitcnt lgkmcnt(11)
	v_mul_f32_e32 v66, v148, v0
	v_mul_f32_e32 v67, v149, v4
	v_fmac_f32_e32 v66, v150, v5
	v_fmac_f32_e32 v67, v151, v6
	ds_read_b128 v[148:151], v105 offset:50368
	s_waitcnt lgkmcnt(11)
	v_fmac_f32_e32 v66, v152, v7
	v_fmac_f32_e32 v67, v153, v8
	v_fmac_f32_e32 v66, v154, v9
	v_fmac_f32_e32 v67, v155, v10
	ds_read_b128 v[152:155], v105 offset:50384
	s_waitcnt lgkmcnt(11)
	v_fmac_f32_e32 v66, v156, v11
	v_fmac_f32_e32 v67, v157, v12
	v_fmac_f32_e32 v66, v158, v13
	v_fmac_f32_e32 v67, v159, v14
	ds_read_b128 v[156:159], v105 offset:50400
	s_waitcnt lgkmcnt(11)
	v_fmac_f32_e32 v66, v160, v15
	v_fmac_f32_e32 v67, v161, v16
	v_fmac_f32_e32 v66, v162, v17
	v_fmac_f32_e32 v67, v163, v18
	ds_read_b128 v[160:163], v105 offset:50432
	s_waitcnt lgkmcnt(11)
	v_fmac_f32_e32 v66, v164, v20
	v_fmac_f32_e32 v67, v165, v21
	v_fmac_f32_e32 v66, v166, v22
	v_fmac_f32_e32 v67, v167, v23
	ds_read_b128 v[164:167], v105 offset:50448
	s_waitcnt lgkmcnt(11)
	v_fmac_f32_e32 v66, v168, v24
	v_fmac_f32_e32 v67, v169, v25
	v_fmac_f32_e32 v66, v170, v26
	v_fmac_f32_e32 v67, v171, v27
	ds_read_b128 v[168:171], v105 offset:50464
	s_waitcnt lgkmcnt(11)
	v_fmac_f32_e32 v66, v172, v28
	v_fmac_f32_e32 v67, v173, v29
	v_fmac_f32_e32 v66, v174, v30
	v_fmac_f32_e32 v67, v175, v31
	ds_read_b128 v[172:175], v105 offset:50480
	s_waitcnt lgkmcnt(11)
	v_fmac_f32_e32 v66, v176, v32
	v_fmac_f32_e32 v67, v177, v33
	v_fmac_f32_e32 v66, v178, v34
	v_fmac_f32_e32 v67, v179, v35
	ds_read_b128 v[176:179], v105 offset:50496
	s_waitcnt lgkmcnt(11)
	v_fmac_f32_e32 v66, v180, v36
	v_fmac_f32_e32 v67, v181, v37
	v_fmac_f32_e32 v66, v182, v38
	v_fmac_f32_e32 v67, v183, v39
	ds_read_b128 v[180:183], v105 offset:50512
	s_waitcnt lgkmcnt(11)
	v_fmac_f32_e32 v66, v136, v40
	v_fmac_f32_e32 v67, v137, v41
	v_fmac_f32_e32 v66, v138, v42
	v_fmac_f32_e32 v67, v139, v43
	ds_read_b128 v[136:139], v105 offset:50528
	s_waitcnt lgkmcnt(11)
	v_fmac_f32_e32 v66, v140, v44
	v_fmac_f32_e32 v67, v141, v45
	v_fmac_f32_e32 v66, v142, v46
	v_fmac_f32_e32 v67, v143, v47
	ds_read_b128 v[140:143], v105 offset:50544
	s_waitcnt lgkmcnt(11)
	v_fmac_f32_e32 v66, v144, v48
	v_fmac_f32_e32 v67, v145, v49
	v_fmac_f32_e32 v66, v146, v50
	v_fmac_f32_e32 v67, v147, v51
	ds_read_b128 v[144:147], v105 offset:50560
	s_waitcnt lgkmcnt(11)
	v_fmac_f32_e32 v66, v148, v52
	v_fmac_f32_e32 v67, v149, v53
	v_fmac_f32_e32 v66, v150, v54
	v_fmac_f32_e32 v67, v151, v55
	ds_read_b128 v[148:151], v105 offset:50576
	s_waitcnt lgkmcnt(11)
	v_fmac_f32_e32 v66, v152, v56
	v_fmac_f32_e32 v67, v153, v57
	v_fmac_f32_e32 v66, v154, v58
	v_fmac_f32_e32 v67, v155, v59
	ds_read_b128 v[152:155], v105 offset:50592
	s_waitcnt lgkmcnt(11)
	v_fmac_f32_e32 v66, v156, v60
	v_fmac_f32_e32 v67, v157, v61
	v_sub_f32_e32 v62, v62, v66
	v_sub_f32_e32 v62, v62, v67
	ds_read_b128 v[156:159], v105 offset:50608
	s_waitcnt lgkmcnt(11)
	v_mul_f32_e32 v66, v160, v0
	v_mul_f32_e32 v67, v161, v4
	v_fmac_f32_e32 v66, v162, v5
	v_fmac_f32_e32 v67, v163, v6
	ds_read_b128 v[160:163], v105 offset:50624
	s_waitcnt lgkmcnt(11)
	v_fmac_f32_e32 v66, v164, v7
	v_fmac_f32_e32 v67, v165, v8
	v_fmac_f32_e32 v66, v166, v9
	v_fmac_f32_e32 v67, v167, v10
	ds_read_b128 v[164:167], v105 offset:50640
	s_waitcnt lgkmcnt(11)
	v_fmac_f32_e32 v66, v168, v11
	v_fmac_f32_e32 v67, v169, v12
	v_fmac_f32_e32 v66, v170, v13
	v_fmac_f32_e32 v67, v171, v14
	ds_read_b128 v[168:171], v105 offset:50656
	s_waitcnt lgkmcnt(11)
	v_fmac_f32_e32 v66, v172, v15
	v_fmac_f32_e32 v67, v173, v16
	v_fmac_f32_e32 v66, v174, v17
	v_fmac_f32_e32 v67, v175, v18
	ds_read_b128 v[172:175], v105 offset:50688
	s_waitcnt lgkmcnt(11)
	v_fmac_f32_e32 v66, v176, v20
	v_fmac_f32_e32 v67, v177, v21
	v_fmac_f32_e32 v66, v178, v22
	v_fmac_f32_e32 v67, v179, v23
	ds_read_b128 v[176:179], v105 offset:50704
	s_waitcnt lgkmcnt(11)
	v_fmac_f32_e32 v66, v180, v24
	v_fmac_f32_e32 v67, v181, v25
	v_fmac_f32_e32 v66, v182, v26
	v_fmac_f32_e32 v67, v183, v27
	ds_read_b128 v[180:183], v105 offset:50720
	s_waitcnt lgkmcnt(11)
	v_fmac_f32_e32 v66, v136, v28
	v_fmac_f32_e32 v67, v137, v29
	v_fmac_f32_e32 v66, v138, v30
	v_fmac_f32_e32 v67, v139, v31
	ds_read_b128 v[136:139], v105 offset:50736
	s_waitcnt lgkmcnt(11)
	v_fmac_f32_e32 v66, v140, v32
	v_fmac_f32_e32 v67, v141, v33
	v_fmac_f32_e32 v66, v142, v34
	v_fmac_f32_e32 v67, v143, v35
	ds_read_b128 v[140:143], v105 offset:50752
	s_waitcnt lgkmcnt(11)
	v_fmac_f32_e32 v66, v144, v36
	v_fmac_f32_e32 v67, v145, v37
	v_fmac_f32_e32 v66, v146, v38
	v_fmac_f32_e32 v67, v147, v39
	ds_read_b128 v[144:147], v105 offset:50768
	s_waitcnt lgkmcnt(11)
	v_fmac_f32_e32 v66, v148, v40
	v_fmac_f32_e32 v67, v149, v41
	v_fmac_f32_e32 v66, v150, v42
	v_fmac_f32_e32 v67, v151, v43
	ds_read_b128 v[148:151], v105 offset:50784
	s_waitcnt lgkmcnt(11)
	v_fmac_f32_e32 v66, v152, v44
	v_fmac_f32_e32 v67, v153, v45
	v_fmac_f32_e32 v66, v154, v46
	v_fmac_f32_e32 v67, v155, v47
	ds_read_b128 v[152:155], v105 offset:50800
	s_waitcnt lgkmcnt(11)
	v_fmac_f32_e32 v66, v156, v48
	v_fmac_f32_e32 v67, v157, v49
	v_fmac_f32_e32 v66, v158, v50
	v_fmac_f32_e32 v67, v159, v51
	ds_read_b128 v[156:159], v105 offset:50816
	s_waitcnt lgkmcnt(11)
	v_fmac_f32_e32 v66, v160, v52
	v_fmac_f32_e32 v67, v161, v53
	v_fmac_f32_e32 v66, v162, v54
	v_fmac_f32_e32 v67, v163, v55
	ds_read_b128 v[160:163], v105 offset:50832
	s_waitcnt lgkmcnt(11)
	v_fmac_f32_e32 v66, v164, v56
	v_fmac_f32_e32 v67, v165, v57
	v_fmac_f32_e32 v66, v166, v58
	v_fmac_f32_e32 v67, v167, v59
	ds_read_b128 v[164:167], v105 offset:50848
	s_waitcnt lgkmcnt(11)
	v_fmac_f32_e32 v66, v168, v60
	v_fmac_f32_e32 v67, v169, v61
	v_fmac_f32_e32 v66, v170, v62
	v_sub_f32_e32 v63, v63, v66
	v_sub_f32_e32 v63, v63, v67
	ds_read_b128 v[168:171], v105 offset:50864
	s_waitcnt lgkmcnt(11)
	v_mul_f32_e32 v66, v172, v0
	v_mul_f32_e32 v67, v173, v4
	v_fmac_f32_e32 v66, v174, v5
	v_fmac_f32_e32 v67, v175, v6
	ds_read_b128 v[172:175], v105 offset:50880
	s_waitcnt lgkmcnt(11)
	v_fmac_f32_e32 v66, v176, v7
	v_fmac_f32_e32 v67, v177, v8
	v_fmac_f32_e32 v66, v178, v9
	v_fmac_f32_e32 v67, v179, v10
	ds_read_b128 v[176:179], v105 offset:50896
	s_waitcnt lgkmcnt(11)
	v_fmac_f32_e32 v66, v180, v11
	v_fmac_f32_e32 v67, v181, v12
	v_fmac_f32_e32 v66, v182, v13
	v_fmac_f32_e32 v67, v183, v14
	ds_read_b128 v[180:183], v105 offset:50912
	s_waitcnt lgkmcnt(11)
	v_fmac_f32_e32 v66, v136, v15
	v_fmac_f32_e32 v67, v137, v16
	v_fmac_f32_e32 v66, v138, v17
	v_fmac_f32_e32 v67, v139, v18
	ds_read_b128 v[136:139], v105 offset:50944
	s_waitcnt lgkmcnt(11)
	v_fmac_f32_e32 v66, v140, v20
	v_fmac_f32_e32 v67, v141, v21
	v_fmac_f32_e32 v66, v142, v22
	v_fmac_f32_e32 v67, v143, v23
	ds_read_b128 v[140:143], v105 offset:50960
	s_waitcnt lgkmcnt(11)
	v_fmac_f32_e32 v66, v144, v24
	v_fmac_f32_e32 v67, v145, v25
	v_fmac_f32_e32 v66, v146, v26
	v_fmac_f32_e32 v67, v147, v27
	ds_read_b128 v[144:147], v105 offset:50976
	s_waitcnt lgkmcnt(11)
	v_fmac_f32_e32 v66, v148, v28
	v_fmac_f32_e32 v67, v149, v29
	v_fmac_f32_e32 v66, v150, v30
	v_fmac_f32_e32 v67, v151, v31
	ds_read_b128 v[148:151], v105 offset:50992
	s_waitcnt lgkmcnt(11)
	v_fmac_f32_e32 v66, v152, v32
	v_fmac_f32_e32 v67, v153, v33
	v_fmac_f32_e32 v66, v154, v34
	v_fmac_f32_e32 v67, v155, v35
	ds_read_b128 v[152:155], v105 offset:51008
	s_waitcnt lgkmcnt(11)
	v_fmac_f32_e32 v66, v156, v36
	v_fmac_f32_e32 v67, v157, v37
	v_fmac_f32_e32 v66, v158, v38
	v_fmac_f32_e32 v67, v159, v39
	ds_read_b128 v[156:159], v105 offset:51024
	s_waitcnt lgkmcnt(11)
	v_fmac_f32_e32 v66, v160, v40
	v_fmac_f32_e32 v67, v161, v41
	v_fmac_f32_e32 v66, v162, v42
	v_fmac_f32_e32 v67, v163, v43
	ds_read_b128 v[160:163], v105 offset:51040
	s_waitcnt lgkmcnt(11)
	v_fmac_f32_e32 v66, v164, v44
	v_fmac_f32_e32 v67, v165, v45
	v_fmac_f32_e32 v66, v166, v46
	v_fmac_f32_e32 v67, v167, v47
	ds_read_b128 v[164:167], v105 offset:51056
	s_waitcnt lgkmcnt(11)
	v_fmac_f32_e32 v66, v168, v48
	v_fmac_f32_e32 v67, v169, v49
	v_fmac_f32_e32 v66, v170, v50
	v_fmac_f32_e32 v67, v171, v51
	ds_read_b128 v[168:171], v105 offset:51072
	s_waitcnt lgkmcnt(11)
	v_fmac_f32_e32 v66, v172, v52
	v_fmac_f32_e32 v67, v173, v53
	v_fmac_f32_e32 v66, v174, v54
	v_fmac_f32_e32 v67, v175, v55
	ds_read_b128 v[172:175], v105 offset:51088
	s_waitcnt lgkmcnt(11)
	v_fmac_f32_e32 v66, v176, v56
	v_fmac_f32_e32 v67, v177, v57
	v_fmac_f32_e32 v66, v178, v58
	v_fmac_f32_e32 v67, v179, v59
	ds_read_b128 v[176:179], v105 offset:51104
	s_waitcnt lgkmcnt(11)
	v_fmac_f32_e32 v66, v180, v60
	v_fmac_f32_e32 v67, v181, v61
	v_fmac_f32_e32 v66, v182, v62
	v_fmac_f32_e32 v67, v183, v63
	v_sub_f32_e32 v64, v64, v66
	v_sub_f32_e32 v64, v64, v67
	ds_read_b128 v[180:183], v105 offset:51120
	s_waitcnt lgkmcnt(11)
	v_mul_f32_e32 v66, v136, v0
	v_mul_f32_e32 v67, v137, v4
	v_fmac_f32_e32 v66, v138, v5
	v_fmac_f32_e32 v67, v139, v6
	ds_read_b128 v[136:139], v105 offset:51136
	s_waitcnt lgkmcnt(11)
	v_fmac_f32_e32 v66, v140, v7
	v_fmac_f32_e32 v67, v141, v8
	v_fmac_f32_e32 v66, v142, v9
	v_fmac_f32_e32 v67, v143, v10
	ds_read_b128 v[140:143], v105 offset:51152
	s_waitcnt lgkmcnt(11)
	v_fmac_f32_e32 v66, v144, v11
	v_fmac_f32_e32 v67, v145, v12
	v_fmac_f32_e32 v66, v146, v13
	v_fmac_f32_e32 v67, v147, v14
	ds_read_b128 v[144:147], v105 offset:51168
	s_waitcnt lgkmcnt(11)
	v_fmac_f32_e32 v66, v148, v15
	v_fmac_f32_e32 v67, v149, v16
	v_fmac_f32_e32 v66, v150, v17
	v_fmac_f32_e32 v67, v151, v18
	ds_read_b128 v[148:151], v105 offset:51184
	s_waitcnt lgkmcnt(11)
	v_fmac_f32_e32 v66, v152, v20
	v_fmac_f32_e32 v67, v153, v21
	v_fmac_f32_e32 v66, v154, v22
	v_fmac_f32_e32 v67, v155, v23
	ds_read_b128 v[152:155], v105 offset:51200
	s_waitcnt lgkmcnt(11)
	v_fmac_f32_e32 v66, v156, v24
	v_fmac_f32_e32 v67, v157, v25
	v_fmac_f32_e32 v66, v158, v26
	v_fmac_f32_e32 v67, v159, v27
	ds_read_b128 v[156:159], v105 offset:51216
	s_waitcnt lgkmcnt(11)
	v_fmac_f32_e32 v66, v160, v28
	v_fmac_f32_e32 v67, v161, v29
	v_fmac_f32_e32 v66, v162, v30
	v_fmac_f32_e32 v67, v163, v31
	ds_read_b128 v[160:163], v105 offset:51232
	s_waitcnt lgkmcnt(11)
	v_fmac_f32_e32 v66, v164, v32
	v_fmac_f32_e32 v67, v165, v33
	v_fmac_f32_e32 v66, v166, v34
	v_fmac_f32_e32 v67, v167, v35
	ds_read_b128 v[164:167], v105 offset:51248
	s_waitcnt lgkmcnt(11)
	v_fmac_f32_e32 v66, v168, v36
	v_fmac_f32_e32 v67, v169, v37
	v_fmac_f32_e32 v66, v170, v38
	v_fmac_f32_e32 v67, v171, v39
	ds_read_b128 v[168:171], v105 offset:51264
	s_waitcnt lgkmcnt(11)
	v_fmac_f32_e32 v66, v172, v40
	v_fmac_f32_e32 v67, v173, v41
	v_fmac_f32_e32 v66, v174, v42
	v_fmac_f32_e32 v67, v175, v43
	ds_read_b128 v[172:175], v105 offset:51280
	s_waitcnt lgkmcnt(11)
	v_fmac_f32_e32 v66, v176, v44
	v_fmac_f32_e32 v67, v177, v45
	v_fmac_f32_e32 v66, v178, v46
	v_fmac_f32_e32 v67, v179, v47
	ds_read_b128 v[176:179], v105 offset:51296
	s_waitcnt lgkmcnt(11)
	v_fmac_f32_e32 v66, v180, v48
	v_fmac_f32_e32 v67, v181, v49
	v_fmac_f32_e32 v66, v182, v50
	v_fmac_f32_e32 v67, v183, v51
	ds_read_b128 v[180:183], v105 offset:51312
	s_waitcnt lgkmcnt(11)
	v_fmac_f32_e32 v66, v136, v52
	v_fmac_f32_e32 v67, v137, v53
	v_fmac_f32_e32 v66, v138, v54
	v_fmac_f32_e32 v67, v139, v55
	ds_read_b128 v[136:139], v105 offset:51328
	s_waitcnt lgkmcnt(11)
	v_fmac_f32_e32 v66, v140, v56
	v_fmac_f32_e32 v67, v141, v57
	v_fmac_f32_e32 v66, v142, v58
	v_fmac_f32_e32 v67, v143, v59
	ds_read_b128 v[140:143], v105 offset:51344
	s_waitcnt lgkmcnt(11)
	v_fmac_f32_e32 v66, v144, v60
	v_fmac_f32_e32 v67, v145, v61
	v_fmac_f32_e32 v66, v146, v62
	v_fmac_f32_e32 v67, v147, v63
	ds_read_b128 v[144:147], v105 offset:51360
	s_waitcnt lgkmcnt(11)
	v_fmac_f32_e32 v66, v148, v64
	v_sub_f32_e32 v65, v65, v66
	v_sub_f32_e32 v65, v65, v67
	ds_read_b128 v[148:151], v105 offset:51376
	s_waitcnt lgkmcnt(11)
	v_mul_f32_e32 v66, v152, v0
	v_mul_f32_e32 v67, v153, v4
	v_fmac_f32_e32 v66, v154, v5
	v_fmac_f32_e32 v67, v155, v6
	ds_read_b128 v[152:155], v105 offset:51392
	s_waitcnt lgkmcnt(11)
	v_fmac_f32_e32 v66, v156, v7
	v_fmac_f32_e32 v67, v157, v8
	v_fmac_f32_e32 v66, v158, v9
	v_fmac_f32_e32 v67, v159, v10
	ds_read_b128 v[156:159], v105 offset:51408
	s_waitcnt lgkmcnt(11)
	v_fmac_f32_e32 v66, v160, v11
	v_fmac_f32_e32 v67, v161, v12
	v_fmac_f32_e32 v66, v162, v13
	v_fmac_f32_e32 v67, v163, v14
	ds_read_b128 v[160:163], v105 offset:51424
	s_waitcnt lgkmcnt(11)
	v_fmac_f32_e32 v66, v164, v15
	v_fmac_f32_e32 v67, v165, v16
	v_fmac_f32_e32 v66, v166, v17
	v_fmac_f32_e32 v67, v167, v18
	ds_read_b128 v[164:167], v105 offset:51440
	s_waitcnt lgkmcnt(11)
	v_fmac_f32_e32 v66, v168, v20
	v_fmac_f32_e32 v67, v169, v21
	v_fmac_f32_e32 v66, v170, v22
	v_fmac_f32_e32 v67, v171, v23
	ds_read_b128 v[168:171], v105 offset:51456
	s_waitcnt lgkmcnt(11)
	v_fmac_f32_e32 v66, v172, v24
	v_fmac_f32_e32 v67, v173, v25
	v_fmac_f32_e32 v66, v174, v26
	v_fmac_f32_e32 v67, v175, v27
	ds_read_b128 v[172:175], v105 offset:51472
	s_waitcnt lgkmcnt(11)
	v_fmac_f32_e32 v66, v176, v28
	v_fmac_f32_e32 v67, v177, v29
	v_fmac_f32_e32 v66, v178, v30
	v_fmac_f32_e32 v67, v179, v31
	ds_read_b128 v[176:179], v105 offset:51488
	s_waitcnt lgkmcnt(11)
	v_fmac_f32_e32 v66, v180, v32
	v_fmac_f32_e32 v67, v181, v33
	v_fmac_f32_e32 v66, v182, v34
	v_fmac_f32_e32 v67, v183, v35
	ds_read_b128 v[180:183], v105 offset:51504
	s_waitcnt lgkmcnt(11)
	v_fmac_f32_e32 v66, v136, v36
	v_fmac_f32_e32 v67, v137, v37
	v_fmac_f32_e32 v66, v138, v38
	v_fmac_f32_e32 v67, v139, v39
	ds_read_b128 v[136:139], v105 offset:51520
	s_waitcnt lgkmcnt(11)
	v_fmac_f32_e32 v66, v140, v40
	v_fmac_f32_e32 v67, v141, v41
	v_fmac_f32_e32 v66, v142, v42
	v_fmac_f32_e32 v67, v143, v43
	ds_read_b128 v[140:143], v105 offset:51536
	s_waitcnt lgkmcnt(11)
	v_fmac_f32_e32 v66, v144, v44
	v_fmac_f32_e32 v67, v145, v45
	v_fmac_f32_e32 v66, v146, v46
	v_fmac_f32_e32 v67, v147, v47
	ds_read_b128 v[144:147], v105 offset:51552
	s_waitcnt lgkmcnt(11)
	v_fmac_f32_e32 v66, v148, v48
	v_fmac_f32_e32 v67, v149, v49
	v_fmac_f32_e32 v66, v150, v50
	v_fmac_f32_e32 v67, v151, v51
	ds_read_b128 v[148:151], v105 offset:51568
	s_waitcnt lgkmcnt(11)
	v_fmac_f32_e32 v66, v152, v52
	v_fmac_f32_e32 v67, v153, v53
	v_fmac_f32_e32 v66, v154, v54
	v_fmac_f32_e32 v67, v155, v55
	ds_read_b128 v[152:155], v105 offset:51584
	s_waitcnt lgkmcnt(11)
	v_fmac_f32_e32 v66, v156, v56
	v_fmac_f32_e32 v67, v157, v57
	v_fmac_f32_e32 v66, v158, v58
	v_fmac_f32_e32 v67, v159, v59
	ds_read_b128 v[156:159], v105 offset:51600
	s_waitcnt lgkmcnt(11)
	v_fmac_f32_e32 v66, v160, v60
	v_fmac_f32_e32 v67, v161, v61
	v_fmac_f32_e32 v66, v162, v62
	v_fmac_f32_e32 v67, v163, v63
	ds_read_b128 v[160:163], v105 offset:51616
	s_waitcnt lgkmcnt(11)
	v_fmac_f32_e32 v66, v164, v64
	v_fmac_f32_e32 v67, v165, v65
	v_sub_f32_e32 v2, v2, v66
	v_sub_f32_e32 v2, v2, v67
	ds_read_b128 v[164:167], v105 offset:51632
	s_waitcnt lgkmcnt(11)
	v_mul_f32_e32 v66, v168, v0
	v_mul_f32_e32 v67, v169, v4
	v_fmac_f32_e32 v66, v170, v5
	v_fmac_f32_e32 v67, v171, v6
	ds_read_b128 v[168:171], v105 offset:51648
	s_waitcnt lgkmcnt(11)
	v_fmac_f32_e32 v66, v172, v7
	v_fmac_f32_e32 v67, v173, v8
	v_fmac_f32_e32 v66, v174, v9
	v_fmac_f32_e32 v67, v175, v10
	ds_read_b128 v[172:175], v105 offset:51664
	s_waitcnt lgkmcnt(11)
	v_fmac_f32_e32 v66, v176, v11
	v_fmac_f32_e32 v67, v177, v12
	v_fmac_f32_e32 v66, v178, v13
	v_fmac_f32_e32 v67, v179, v14
	ds_read_b128 v[176:179], v105 offset:51680
	s_waitcnt lgkmcnt(11)
	v_fmac_f32_e32 v66, v180, v15
	v_fmac_f32_e32 v67, v181, v16
	v_fmac_f32_e32 v66, v182, v17
	v_fmac_f32_e32 v67, v183, v18
	ds_read_b128 v[180:183], v105 offset:51696
	s_waitcnt lgkmcnt(11)
	v_fmac_f32_e32 v66, v136, v20
	v_fmac_f32_e32 v67, v137, v21
	v_fmac_f32_e32 v66, v138, v22
	v_fmac_f32_e32 v67, v139, v23
	s_waitcnt lgkmcnt(10)
	v_fmac_f32_e32 v66, v140, v24
	v_fmac_f32_e32 v67, v141, v25
	v_fmac_f32_e32 v66, v142, v26
	v_fmac_f32_e32 v67, v143, v27
	s_waitcnt lgkmcnt(9)
	v_fmac_f32_e32 v66, v144, v28
	v_fmac_f32_e32 v67, v145, v29
	v_fmac_f32_e32 v66, v146, v30
	v_fmac_f32_e32 v67, v147, v31
	s_waitcnt lgkmcnt(8)
	v_fmac_f32_e32 v66, v148, v32
	v_fmac_f32_e32 v67, v149, v33
	v_fmac_f32_e32 v66, v150, v34
	v_fmac_f32_e32 v67, v151, v35
	s_waitcnt lgkmcnt(7)
	v_fmac_f32_e32 v66, v152, v36
	v_fmac_f32_e32 v67, v153, v37
	v_fmac_f32_e32 v66, v154, v38
	v_fmac_f32_e32 v67, v155, v39
	s_waitcnt lgkmcnt(6)
	v_fmac_f32_e32 v66, v156, v40
	v_fmac_f32_e32 v67, v157, v41
	v_fmac_f32_e32 v66, v158, v42
	v_fmac_f32_e32 v67, v159, v43
	s_waitcnt lgkmcnt(5)
	v_fmac_f32_e32 v66, v160, v44
	v_fmac_f32_e32 v67, v161, v45
	v_fmac_f32_e32 v66, v162, v46
	v_fmac_f32_e32 v67, v163, v47
	s_waitcnt lgkmcnt(4)
	v_fmac_f32_e32 v66, v164, v48
	v_fmac_f32_e32 v67, v165, v49
	v_fmac_f32_e32 v66, v166, v50
	v_fmac_f32_e32 v67, v167, v51
	s_waitcnt lgkmcnt(3)
	v_fmac_f32_e32 v66, v168, v52
	v_fmac_f32_e32 v67, v169, v53
	v_fmac_f32_e32 v66, v170, v54
	v_fmac_f32_e32 v67, v171, v55
	s_waitcnt lgkmcnt(2)
	v_fmac_f32_e32 v66, v172, v56
	v_fmac_f32_e32 v67, v173, v57
	v_fmac_f32_e32 v66, v174, v58
	v_fmac_f32_e32 v67, v175, v59
	s_waitcnt lgkmcnt(1)
	v_fmac_f32_e32 v66, v176, v60
	v_fmac_f32_e32 v67, v177, v61
	v_fmac_f32_e32 v66, v178, v62
	v_fmac_f32_e32 v67, v179, v63
	s_waitcnt lgkmcnt(0)
	v_fmac_f32_e32 v66, v180, v64
	v_fmac_f32_e32 v67, v181, v65
	v_fmac_f32_e32 v66, v182, v2
	v_sub_f32_e32 v3, v3, v66
	v_sub_f32_e32 v3, v3, v67
	s_movk_i32 s4, 0x7f
	v_cmp_lt_i32_e32 vcc, s4, v80
	s_and_saveexec_b64 s[4:5], vcc
	s_xor_b64 s[36:37], exec, s[4:5]
	s_cbranch_execz .LBB0_936
	v_lshlrev_b32_e32 v1, 1, v80
	v_cvt_pk_bf16_f32 v66, v0, v4
	ds_write_b16 v1, v66 offset:18688
	ds_write_b16_d16_hi v1, v66 offset:18944
	v_cvt_pk_bf16_f32 v67, v5, v6
	ds_write_b16 v1, v67 offset:19200
	ds_write_b16_d16_hi v1, v67 offset:19456
	v_cvt_pk_bf16_f32 v68, v7, v8
	ds_write_b16 v1, v68 offset:19712
	ds_write_b16_d16_hi v1, v68 offset:19968
	v_cvt_pk_bf16_f32 v69, v9, v10
	ds_write_b16 v1, v69 offset:20224
	ds_write_b16_d16_hi v1, v69 offset:20480
	v_cvt_pk_bf16_f32 v66, v11, v12
	ds_write_b16 v1, v66 offset:20736
	ds_write_b16_d16_hi v1, v66 offset:20992
	v_cvt_pk_bf16_f32 v67, v13, v14
	ds_write_b16 v1, v67 offset:21248
	ds_write_b16_d16_hi v1, v67 offset:21504
	v_cvt_pk_bf16_f32 v68, v15, v16
	ds_write_b16 v1, v68 offset:21760
	ds_write_b16_d16_hi v1, v68 offset:22016
	v_cvt_pk_bf16_f32 v69, v17, v18
	ds_write_b16 v1, v69 offset:22272
	ds_write_b16_d16_hi v1, v69 offset:22528
	v_cvt_pk_bf16_f32 v66, v20, v21
	ds_write_b16 v1, v66 offset:22784
	ds_write_b16_d16_hi v1, v66 offset:23040
	v_cvt_pk_bf16_f32 v67, v22, v23
	ds_write_b16 v1, v67 offset:23296
	ds_write_b16_d16_hi v1, v67 offset:23552
	v_cvt_pk_bf16_f32 v68, v24, v25
	ds_write_b16 v1, v68 offset:23808
	ds_write_b16_d16_hi v1, v68 offset:24064
	v_cvt_pk_bf16_f32 v69, v26, v27
	ds_write_b16 v1, v69 offset:24320
	ds_write_b16_d16_hi v1, v69 offset:24576
	v_cvt_pk_bf16_f32 v66, v28, v29
	ds_write_b16 v1, v66 offset:24832
	ds_write_b16_d16_hi v1, v66 offset:25088
	v_cvt_pk_bf16_f32 v67, v30, v31
	ds_write_b16 v1, v67 offset:25344
	ds_write_b16_d16_hi v1, v67 offset:25600
	v_cvt_pk_bf16_f32 v68, v32, v33
	ds_write_b16 v1, v68 offset:25856
	ds_write_b16_d16_hi v1, v68 offset:26112
	v_cvt_pk_bf16_f32 v69, v34, v35
	ds_write_b16 v1, v69 offset:26368
	ds_write_b16_d16_hi v1, v69 offset:26624
	v_cvt_pk_bf16_f32 v66, v36, v37
	ds_write_b16 v1, v66 offset:26880
	ds_write_b16_d16_hi v1, v66 offset:27136
	v_cvt_pk_bf16_f32 v67, v38, v39
	ds_write_b16 v1, v67 offset:27392
	ds_write_b16_d16_hi v1, v67 offset:27648
	v_cvt_pk_bf16_f32 v68, v40, v41
	ds_write_b16 v1, v68 offset:27904
	ds_write_b16_d16_hi v1, v68 offset:28160
	v_cvt_pk_bf16_f32 v69, v42, v43
	ds_write_b16 v1, v69 offset:28416
	ds_write_b16_d16_hi v1, v69 offset:28672
	v_cvt_pk_bf16_f32 v66, v44, v45
	ds_write_b16 v1, v66 offset:28928
	ds_write_b16_d16_hi v1, v66 offset:29184
	v_cvt_pk_bf16_f32 v67, v46, v47
	ds_write_b16 v1, v67 offset:29440
	ds_write_b16_d16_hi v1, v67 offset:29696
	v_cvt_pk_bf16_f32 v68, v48, v49
	ds_write_b16 v1, v68 offset:29952
	ds_write_b16_d16_hi v1, v68 offset:30208
	v_cvt_pk_bf16_f32 v69, v50, v51
	ds_write_b16 v1, v69 offset:30464
	ds_write_b16_d16_hi v1, v69 offset:30720
	v_cvt_pk_bf16_f32 v66, v52, v53
	ds_write_b16 v1, v66 offset:30976
	ds_write_b16_d16_hi v1, v66 offset:31232
	v_cvt_pk_bf16_f32 v67, v54, v55
	ds_write_b16 v1, v67 offset:31488
	ds_write_b16_d16_hi v1, v67 offset:31744
	v_cvt_pk_bf16_f32 v68, v56, v57
	ds_write_b16 v1, v68 offset:32000
	ds_write_b16_d16_hi v1, v68 offset:32256
	v_cvt_pk_bf16_f32 v69, v58, v59
	ds_write_b16 v1, v69 offset:32512
	ds_write_b16_d16_hi v1, v69 offset:32768
	v_cvt_pk_bf16_f32 v66, v60, v61
	ds_write_b16 v1, v66 offset:33024
	ds_write_b16_d16_hi v1, v66 offset:33280
	v_cvt_pk_bf16_f32 v67, v62, v63
	ds_write_b16 v1, v67 offset:33536
	ds_write_b16_d16_hi v1, v67 offset:33792
	v_cvt_pk_bf16_f32 v68, v64, v65
	ds_write_b16 v1, v68 offset:34048
	ds_write_b16_d16_hi v1, v68 offset:34304
	v_cvt_pk_bf16_f32 v69, v2, v3
	ds_write_b16 v1, v69 offset:34560
	ds_write_b16_d16_hi v1, v69 offset:34816
.LBB0_936:
	s_andn2_saveexec_b64 s[36:37], s[36:37]
	s_cbranch_execz .LBB0_938
	v_mul_u32_u24_e32 v1, 0x90, v80
	v_cvt_pk_bf16_f32 v66, v0, v4
	v_cvt_pk_bf16_f32 v67, v5, v6
	v_cvt_pk_bf16_f32 v68, v7, v8
	v_cvt_pk_bf16_f32 v69, v9, v10
	ds_write_b128 v1, v[66:69] offset:512
	v_cvt_pk_bf16_f32 v136, v11, v12
	v_cvt_pk_bf16_f32 v137, v13, v14
	v_cvt_pk_bf16_f32 v138, v15, v16
	v_cvt_pk_bf16_f32 v139, v17, v18
	ds_write_b128 v1, v[136:139] offset:528
	v_cvt_pk_bf16_f32 v66, v20, v21
	v_cvt_pk_bf16_f32 v67, v22, v23
	v_cvt_pk_bf16_f32 v68, v24, v25
	v_cvt_pk_bf16_f32 v69, v26, v27
	ds_write_b128 v1, v[66:69] offset:544
	v_cvt_pk_bf16_f32 v136, v28, v29
	v_cvt_pk_bf16_f32 v137, v30, v31
	v_cvt_pk_bf16_f32 v138, v32, v33
	v_cvt_pk_bf16_f32 v139, v34, v35
	ds_write_b128 v1, v[136:139] offset:560
	v_cvt_pk_bf16_f32 v66, v36, v37
	v_cvt_pk_bf16_f32 v67, v38, v39
	v_cvt_pk_bf16_f32 v68, v40, v41
	v_cvt_pk_bf16_f32 v69, v42, v43
	ds_write_b128 v1, v[66:69] offset:576
	v_cvt_pk_bf16_f32 v136, v44, v45
	v_cvt_pk_bf16_f32 v137, v46, v47
	v_cvt_pk_bf16_f32 v138, v48, v49
	v_cvt_pk_bf16_f32 v139, v50, v51
	ds_write_b128 v1, v[136:139] offset:592
	v_cvt_pk_bf16_f32 v66, v52, v53
	v_cvt_pk_bf16_f32 v67, v54, v55
	v_cvt_pk_bf16_f32 v68, v56, v57
	v_cvt_pk_bf16_f32 v69, v58, v59
	ds_write_b128 v1, v[66:69] offset:608
	v_cvt_pk_bf16_f32 v136, v60, v61
	v_cvt_pk_bf16_f32 v137, v62, v63
	v_cvt_pk_bf16_f32 v138, v64, v65
	v_cvt_pk_bf16_f32 v139, v2, v3
	ds_write_b128 v1, v[136:139] offset:624
.LBB0_938:
	s_or_b64 exec, exec, s[36:37]
	s_waitcnt lgkmcnt(0)
.LBB0_939:
	s_or_b64 exec, exec, s[0:1]
	s_cbranch_execnz .LBB0_742
	s_branch .LBB0_867

.LBB0_1078:
	s_and_b64 vcc, exec, s[0:1]
	s_cbranch_vccz .LBB0_1091
	s_sub_i32 s0, s28, 64
	v_mov_b32_e32 v49, v230
	s_lshr_b32 s33, s0, 5
	s_sub_i32 s1, 31, s33
	v_readfirstlane_b32 s10, v49
	s_bfe_u32 s0, s10, 0x10006
	s_ashr_i32 s11, s10, 7
	s_lshl_b32 s10, s28, 8
	s_and_b32 s34, s10, 0x1800
	s_lshl_b32 s10, s1, 6
	s_and_b32 s29, s28, 7
	v_and_b32_e32 v141, 15, v49
	s_or_b32 s10, s34, s10
	v_or_b32_e32 v0, s10, v141
	s_lshl_b32 s10, s29, 8
	s_lshl_b32 s26, s29, 9
	s_add_i32 s29, s29, 1
	v_cvt_f32_ubyte0_e32 v16, s29
	v_ashrrev_i32_e32 v48, 5, v49
	v_exp_f32_e64 v55, -v16
	v_add_u32_e32 v16, s34, v48
	v_ashrrev_i32_e32 v17, 31, v16
	s_lshl_b32 s35, s11, 4
	v_lshlrev_b64 v[16:17], 12, v[16:17]
	v_add_u32_e32 v0, s35, v0
	v_lshl_add_u64 v[16:17], s[22:23], 0, v[16:17]
	v_lshlrev_b32_e32 v18, 4, v49
	v_ashrrev_i32_e32 v1, 31, v0
	v_lshl_add_u64 v[16:17], v[16:17], 0, s[26:27]
	v_and_b32_e32 v50, 0x1f0, v18
	v_mov_b32_e32 v51, v125
	v_lshlrev_b64 v[130:131], 12, v[0:1]
	v_lshl_add_u64 v[40:41], v[16:17], 0, v[50:51]
	s_or_b32 s29, s10, s34
	v_ashrrev_i32_e32 v51, 3, v49
	v_lshl_add_u64 v[0:1], s[20:21], 0, v[130:131]
	v_add_u32_e32 v16, s29, v51
	v_lshl_add_u64 v[0:1], v[0:1], 0, s[26:27]
	s_lshl_b32 s30, s0, 8
	s_mov_b32 s31, s27
	v_ashrrev_i32_e32 v17, 31, v16
	v_lshl_add_u64 v[0:1], v[0:1], 0, s[30:31]
	v_lshlrev_b64 v[132:133], 12, v[16:17]
	s_mov_b32 s31, 0x10000
	v_lshl_add_u64 v[16:17], s[24:25], 0, v[132:133]
	v_and_b32_e32 v52, 0x70, v18
	v_mov_b32_e32 v53, v125
	v_add_co_u32_e32 v24, vcc, s31, v40
	v_lshl_add_u64 v[42:43], v[16:17], 0, v[52:53]
	s_nop 0
	v_addc_co_u32_e32 v25, vcc, 0, v41, vcc
	s_mov_b32 s31, 0x40000
	v_add_co_u32_e32 v28, vcc, s31, v42
	s_mov_b32 s31, 0x20000
	s_nop 0
	v_addc_co_u32_e32 v29, vcc, 0, v43, vcc
	v_add_co_u32_e32 v32, vcc, s31, v40
	s_mov_b32 s31, 0x80000
	s_nop 0
	v_addc_co_u32_e32 v33, vcc, 0, v41, vcc
	v_and_b32_e32 v124, 48, v49
	v_add_co_u32_e32 v36, vcc, s31, v42
	v_lshl_add_u64 v[12:13], v[0:1], 0, v[124:125]
	s_nop 0
	v_addc_co_u32_e32 v37, vcc, 0, v43, vcc
	s_mov_b32 s31, 0x30000
	global_load_dwordx4 v[0:3], v[12:13], off
	global_load_dwordx4 v[4:7], v[12:13], off offset:64
	global_load_dwordx4 v[8:11], v[12:13], off offset:128
	s_nop 0
	global_load_dwordx4 v[12:15], v[12:13], off offset:192
	s_nop 0
	global_load_dwordx4 v[16:19], v[40:41], off
	global_load_dwordx4 v[20:23], v[42:43], off
	v_add_co_u32_e32 v40, vcc, s31, v40
	s_mov_b32 s31, 0xc0000
	s_nop 0
	v_addc_co_u32_e32 v41, vcc, 0, v41, vcc
	v_add_co_u32_e32 v44, vcc, s31, v42
	global_load_dwordx4 v[24:27], v[24:25], off
	s_nop 0
	global_load_dwordx4 v[28:31], v[28:29], off
	v_addc_co_u32_e32 v45, vcc, 0, v43, vcc
	global_load_dwordx4 v[32:35], v[32:33], off
	s_nop 0
	global_load_dwordx4 v[36:39], v[36:37], off
	s_nop 0
	global_load_dwordx4 v[40:43], v[40:41], off
	s_nop 0
	global_load_dwordx4 v[44:47], v[44:45], off
	v_and_b32_e32 v60, 64, v164
	v_and_b32_e32 v54, 63, v49
	v_bfe_u32 v142, v49, 4, 2
	v_xor_b32_e32 v49, 16, v164
	v_add_u32_e32 v60, 64, v60
	v_cmp_lt_i32_e32 vcc, v49, v60
	s_addk_i32 s35, 0x78d
	v_or_b32_e32 v58, 48, v54
	v_cndmask_b32_e32 v49, v164, v49, vcc
	v_lshlrev_b32_e32 v139, 2, v49
	v_xor_b32_e32 v49, 32, v164
	v_cmp_lt_i32_e32 vcc, v49, v60
	v_lshlrev_b32_e32 v138, 2, v142
	s_lshl_b32 s31, s33, 6
	v_cndmask_b32_e32 v49, v164, v49, vcc
	v_lshlrev_b32_e32 v140, 2, v49
	v_or_b32_e32 v49, 0x70, v54
	v_mul_u32_u24_e32 v62, 0x90, v49
	v_or_b32_e32 v49, 0xb0, v54
	v_mul_u32_u24_e32 v63, 0x90, v49
	v_or_b32_e32 v49, 0xf0, v54
	v_mul_u32_u24_e32 v54, 0x90, v49
	v_add_u32_e32 v49, s35, v141
	v_sub_u32_e32 v49, v49, v138
	s_add_i32 s30, s30, 0
	v_lshl_add_u32 v60, v142, 3, 0
	v_subrev_u32_e32 v144, s31, v49
	s_lshl_b32 s31, s28, 20
	v_ashrrev_i32_e32 v49, 31, v48
	v_mul_lo_u32 v53, v48, s7
	v_mul_lo_u32 v51, v51, s52
	v_mov_b32_e32 v56, s30
	v_mul_u32_u24_e32 v143, 0xa0, v141
	v_lshl_add_u32 v143, v142, 4, v143
	v_add_u32_e32 v143, 0x8400, v143
	s_and_b32 s34, s31, 0x1800000
	s_mov_b32 s35, s27
	v_lshlrev_b64 v[48:49], 12, v[48:49]
	v_mul_f32_e32 v135, 0x3fb8aa3b, v55
	v_add_u32_e32 v53, 0, v53
	v_add_u32_e32 v51, 0, v51
	v_mul_u32_u24_e32 v55, 0x210, v141
	v_mad_u32_u24 v56, v141, s7, v56
	v_add_u32_e32 v57, s30, v124
	v_mul_u32_u24_e32 v59, 0x210, v58
	v_add_u32_e32 v61, 0x8400, v143
	v_mul_u32_u24_e32 v58, 0x90, v58
	v_add_u32_e32 v64, 0x8440, v143
	v_lshl_add_u64 v[136:137], s[34:35], 0, v[48:49]
	v_mov_b32_e32 v155, 0
	s_mov_b32 s29, 0
	s_sub_i32 s30, 32, s33
	v_or_b32_e32 v132, v132, v52
	v_or3_b32 v136, v136, s26, v50
	v_mov_b32_e32 v156, 0xff800000
	v_add_u32_e32 v145, v53, v50
	v_lshrrev_b32_e32 v146, 3, v230
	v_mul_u32_u24_e32 v146, 0xa0, v146
	v_and_b32_e32 v203, 4, v230
	v_lshl_add_u32 v146, v203, 4, v146
	v_and_b32_e32 v203, 1, v230
	v_lshl_add_u32 v146, v203, 5, v146
	v_and_b32_e32 v203, 2, v230
	v_lshl_add_u32 v146, v203, 2, v146
	v_add_u32_e32 v124, v56, v124
	v_add_u32_e32 v147, v57, v55
	v_add_u32_e32 v148, v57, v59
	v_add_u32_e32 v149, v60, v58
	v_add_u32_e32 v150, v60, v62
	v_add_u32_e32 v151, v60, v63
	v_add_u32_e32 v152, v60, v54
	v_add_u32_e32 v153, 0x7800, v61
	v_add_u32_e32 v154, 0x7800, v64
	v_mov_b32_e32 v48, 0
	v_mov_b32_e32 v49, v155
	v_mov_b32_e32 v50, v155
	v_mov_b32_e32 v51, v155
	v_mov_b32_e32 v52, 0
	v_mov_b32_e32 v53, v155
	v_mov_b32_e32 v54, v155
	v_mov_b32_e32 v55, v155
	v_mov_b32_e32 v56, 0
	v_mov_b32_e32 v57, v155
	v_mov_b32_e32 v58, v155
	v_mov_b32_e32 v59, v155
	v_mov_b32_e32 v60, 0
	v_mov_b32_e32 v61, v155
	v_mov_b32_e32 v62, v155
	v_mov_b32_e32 v63, v155
	v_mov_b32_e32 v64, 0
	v_mov_b32_e32 v65, v155
	v_mov_b32_e32 v66, v155
	v_mov_b32_e32 v67, v155
	v_mov_b32_e32 v68, 0
	v_mov_b32_e32 v69, v155
	v_mov_b32_e32 v70, v155
	v_mov_b32_e32 v71, v155
	v_mov_b32_e32 v72, 0
	v_mov_b32_e32 v73, v155
	v_mov_b32_e32 v74, v155
	v_mov_b32_e32 v75, v155
	v_mov_b32_e32 v76, 0
	v_mov_b32_e32 v77, v155
	v_mov_b32_e32 v78, v155
	v_mov_b32_e32 v79, v155
	v_mov_b32_e32 v80, 0
	v_mov_b32_e32 v81, v155
	v_mov_b32_e32 v82, v155
	v_mov_b32_e32 v83, v155
	v_mov_b32_e32 v84, 0
	v_mov_b32_e32 v85, v155
	v_mov_b32_e32 v86, v155
	v_mov_b32_e32 v87, v155
	v_mov_b32_e32 v88, 0
	v_mov_b32_e32 v89, v155
	v_mov_b32_e32 v90, v155
	v_mov_b32_e32 v91, v155
	v_mov_b32_e32 v96, 0
	v_mov_b32_e32 v97, v155
	v_mov_b32_e32 v98, v155
	v_mov_b32_e32 v99, v155
	v_mov_b32_e32 v92, 0
	v_mov_b32_e32 v93, v155
	v_mov_b32_e32 v94, v155
	v_mov_b32_e32 v95, v155
	v_mov_b32_e32 v100, 0
	v_mov_b32_e32 v101, v155
	v_mov_b32_e32 v102, v155
	v_mov_b32_e32 v103, v155
	v_mov_b32_e32 v104, 0
	v_mov_b32_e32 v105, v155
	v_mov_b32_e32 v106, v155
	v_mov_b32_e32 v107, v155
	v_mov_b32_e32 v108, 0
	v_mov_b32_e32 v109, v155
	v_mov_b32_e32 v110, v155
	v_mov_b32_e32 v111, v155
	v_add_u32_e32 v204, 51, v144
	v_cvt_f32_i32_e32 v204, v204
	v_add_u32_e32 v205, 50, v144
	v_cvt_f32_i32_e32 v205, v205
	v_add_u32_e32 v206, 49, v144
	v_cvt_f32_i32_e32 v206, v206
	v_add_u32_e32 v207, 48, v144
	v_cvt_f32_i32_e32 v207, v207
	v_add_u32_e32 v208, 35, v144
	v_cvt_f32_i32_e32 v208, v208
	v_add_u32_e32 v209, 34, v144
	v_cvt_f32_i32_e32 v209, v209
	v_add_u32_e32 v210, 33, v144
	v_cvt_f32_i32_e32 v210, v210
	v_add_u32_e32 v211, 32, v144
	v_cvt_f32_i32_e32 v211, v211
	v_add_u32_e32 v212, 19, v144
	v_cvt_f32_i32_e32 v212, v212
	v_add_u32_e32 v213, 18, v144
	v_cvt_f32_i32_e32 v213, v213
	v_add_u32_e32 v214, 17, v144
	v_cvt_f32_i32_e32 v214, v214
	v_add_u32_e32 v215, 16, v144
	v_cvt_f32_i32_e32 v215, v215
	v_add_u32_e32 v216, 3, v144
	v_cvt_f32_i32_e32 v216, v216
	v_add_u32_e32 v217, 2, v144
	v_cvt_f32_i32_e32 v217, v217
	v_add_u32_e32 v218, 1, v144
	v_cvt_f32_i32_e32 v218, v218
	v_add_u32_e32 v219, 0, v144
	v_cvt_f32_i32_e32 v219, v219
	v_mul_f32_e32 v204, v135, v204
	v_mul_f32_e32 v205, v135, v205
	v_mul_f32_e32 v206, v135, v206
	v_mul_f32_e32 v207, v135, v207
	v_mul_f32_e32 v208, v135, v208
	v_mul_f32_e32 v209, v135, v209
	v_mul_f32_e32 v210, v135, v210
	v_mul_f32_e32 v211, v135, v211
	v_mul_f32_e32 v212, v135, v212
	v_mul_f32_e32 v213, v135, v213
	v_mul_f32_e32 v214, v135, v214
	v_mul_f32_e32 v215, v135, v215
	v_mul_f32_e32 v216, v135, v216
	v_mul_f32_e32 v217, v135, v217
	v_mul_f32_e32 v218, v135, v218
	v_mul_f32_e32 v219, v135, v219
	v_mul_f32_e32 v220, 0x42800000, v135
	v_cvt_f32_u32_e32 v221, s1
	v_mul_f32_e32 v221, v221, v220
.LBB0_1080:
	s_cmp_ge_u32 s29, s1
	s_barrier
	s_waitcnt vmcnt(7)
	ds_write_b128 v145, v[16:19]
	s_waitcnt vmcnt(6)
	ds_write_b64 v146, v[20:21] offset:33792
	ds_write_b64 v146, v[22:23] offset:33808
	s_waitcnt vmcnt(5)
	ds_write_b128 v145, v[24:27] offset:8448
	s_waitcnt vmcnt(4)
	ds_write_b64 v146, v[28:29] offset:44032
	ds_write_b64 v146, v[30:31] offset:44048
	s_waitcnt vmcnt(3)
	ds_write_b128 v145, v[32:35] offset:16896
	s_waitcnt vmcnt(2)
	ds_write_b64 v146, v[36:37] offset:54272
	ds_write_b64 v146, v[38:39] offset:54288
	s_waitcnt vmcnt(1)
	ds_write_b128 v145, v[40:43] offset:25344
	s_waitcnt vmcnt(0)
	ds_write_b64 v146, v[44:45] offset:64512
	ds_write_b64 v146, v[46:47] offset:64528
	s_waitcnt lgkmcnt(0)
	s_barrier
	s_cbranch_scc1 .Lda_last
	v_lshl_add_u64 v[40:41], s[96:97], 0, v[136:137]
	v_add_co_u32_e32 v16, vcc, 0x11140000, v40
	v_lshl_add_u64 v[42:43], s[96:97], 0, v[132:133]
	s_nop 0
	v_addc_co_u32_e32 v17, vcc, 0, v41, vcc
	v_add_co_u32_e32 v20, vcc, 0xd000000, v42
	s_nop 1
	v_addc_co_u32_e32 v21, vcc, 0, v43, vcc
	v_add_co_u32_e32 v24, vcc, 0x11150000, v40
	global_load_dwordx4 v[16:19], v[16:17], off
	s_nop 0
	global_load_dwordx4 v[20:23], v[20:21], off offset:128
	v_addc_co_u32_e32 v25, vcc, 0, v41, vcc
	v_add_co_u32_e32 v28, vcc, 0xd040000, v42
	s_nop 1
	v_addc_co_u32_e32 v29, vcc, 0, v43, vcc
	v_add_co_u32_e32 v32, vcc, 0x11160000, v40
	global_load_dwordx4 v[24:27], v[24:25], off
	s_nop 0
	global_load_dwordx4 v[28:31], v[28:29], off offset:128
	v_addc_co_u32_e32 v33, vcc, 0, v41, vcc
	v_add_co_u32_e32 v36, vcc, 0xd080000, v42
	s_nop 1
	v_addc_co_u32_e32 v37, vcc, 0, v43, vcc
	v_add_co_u32_e32 v40, vcc, 0x11170000, v40
	global_load_dwordx4 v[32:35], v[32:33], off
	s_nop 0
	global_load_dwordx4 v[36:39], v[36:37], off offset:128
	v_addc_co_u32_e32 v41, vcc, 0, v41, vcc
	v_add_co_u32_e32 v44, vcc, 0xd0c0000, v42
	s_nop 1
	v_addc_co_u32_e32 v45, vcc, 0, v43, vcc
	global_load_dwordx4 v[40:43], v[40:41], off
	s_nop 0
	global_load_dwordx4 v[44:47], v[44:45], off offset:128
.LBB0_1082:
	ds_read_b128 v[112:115], v124
	ds_read_b128 v[116:119], v124 offset:64
	ds_read_b128 v[120:123], v124 offset:128
	ds_read_b128 v[166:169], v124 offset:192
	ds_read_b128 v[170:173], v147 offset:8448
	ds_read_b128 v[174:177], v147 offset:8512
	ds_read_b128 v[178:181], v147 offset:8576
	ds_read_b128 v[182:185], v147 offset:8640
	s_add_i32 s29, s29, 1
	s_waitcnt lgkmcnt(7)
	v_mfma_f32_16x16x32_bf16 v[112:115], v[112:115], v[0:3], 0
	s_waitcnt lgkmcnt(6)
	v_mfma_f32_16x16x32_bf16 v[112:115], v[116:119], v[4:7], v[112:115]
	s_waitcnt lgkmcnt(5)
	v_mfma_f32_16x16x32_bf16 v[112:115], v[120:123], v[8:11], v[112:115]
	s_waitcnt lgkmcnt(4)
	v_mfma_f32_16x16x32_bf16 v[166:169], v[166:169], v[12:15], v[112:115]
	s_nop 5
	ds_read_b128 v[112:115], v147 offset:16896
	ds_read_b128 v[116:119], v147 offset:16960
	ds_read_b128 v[186:189], v147 offset:17024
	ds_read_b128 v[190:193], v147 offset:17088
	s_waitcnt lgkmcnt(7)
	v_mfma_f32_16x16x32_bf16 v[120:123], v[170:173], v[0:3], 0
	s_waitcnt lgkmcnt(6)
	v_mfma_f32_16x16x32_bf16 v[120:123], v[174:177], v[4:7], v[120:123]
	s_waitcnt lgkmcnt(5)
	v_mfma_f32_16x16x32_bf16 v[120:123], v[178:181], v[8:11], v[120:123]
	s_waitcnt lgkmcnt(4)
	v_mfma_f32_16x16x32_bf16 v[120:123], v[182:185], v[12:15], v[120:123]
	ds_read_b128 v[170:173], v148
	ds_read_b128 v[174:177], v148 offset:64
	ds_read_b128 v[178:181], v148 offset:128
	ds_read_b128 v[182:185], v148 offset:192
	s_waitcnt lgkmcnt(7)
	v_mfma_f32_16x16x32_bf16 v[112:115], v[112:115], v[0:3], 0
	s_waitcnt lgkmcnt(6)
	v_mfma_f32_16x16x32_bf16 v[112:115], v[116:119], v[4:7], v[112:115]
	s_waitcnt lgkmcnt(5)
	v_mfma_f32_16x16x32_bf16 v[112:115], v[186:189], v[8:11], v[112:115]
	s_waitcnt lgkmcnt(4)
	v_mfma_f32_16x16x32_bf16 v[116:119], v[190:193], v[12:15], v[112:115]
	s_waitcnt lgkmcnt(3)
	v_mfma_f32_16x16x32_bf16 v[112:115], v[170:173], v[0:3], 0
	s_waitcnt lgkmcnt(2)
	v_mfma_f32_16x16x32_bf16 v[112:115], v[174:177], v[4:7], v[112:115]
	s_waitcnt lgkmcnt(1)
	v_mfma_f32_16x16x32_bf16 v[112:115], v[178:181], v[8:11], v[112:115]
	s_waitcnt lgkmcnt(0)
	v_mfma_f32_16x16x32_bf16 v[112:115], v[182:185], v[12:15], v[112:115]
	ds_read_b128 v[186:189], v143 offset:15360
	ds_read_b128 v[190:193], v143 offset:17920
	s_mov_b32 s26, 0xff800000
	v_sub_f32_e32 v156, v156, v220
	v_fma_f32 v170, v166, v126, -v204
	v_fma_f32 v171, v167, v126, -v205
	v_fma_f32 v172, v168, v126, -v206
	v_fma_f32 v173, v169, v126, -v207
	v_fma_f32 v174, v120, v126, -v208
	v_fma_f32 v175, v121, v126, -v209
	v_fma_f32 v176, v122, v126, -v210
	v_fma_f32 v177, v123, v126, -v211
	v_fma_f32 v178, v116, v126, -v212
	v_fma_f32 v179, v117, v126, -v213
	v_fma_f32 v180, v118, v126, -v214
	v_fma_f32 v181, v119, v126, -v215
	v_fma_f32 v182, v112, v126, -v216
	v_fma_f32 v183, v113, v126, -v217
	v_fma_f32 v184, v114, v126, -v218
	v_fma_f32 v185, v115, v126, -v219
	v_max3_f32 v112, v170, v171, v172
	v_max3_f32 v112, v112, v173, v174
	v_max3_f32 v112, v112, v175, v176
	v_max3_f32 v112, v112, v177, v178
	v_max3_f32 v112, v112, v179, v180
	v_max3_f32 v112, v112, v181, v182
	v_max3_f32 v112, v112, v183, v184
	v_max_f32_e32 v112, v112, v185
	ds_bpermute_b32 v115, v139, v112
	s_waitcnt lgkmcnt(0)
	v_max_f32_e32 v115, v115, v115
	v_max_f32_e32 v112, v112, v115
	ds_bpermute_b32 v115, v140, v112
	s_waitcnt lgkmcnt(0)
	v_max3_f32 v112, v156, v112, v115
	v_sub_f32_e32 v115, v156, v112
	v_sub_f32_e32 v170, v170, v112
	v_exp_f32_e32 v170, v170
	v_sub_f32_e32 v171, v171, v112
	v_exp_f32_e32 v118, v115
	v_exp_f32_e32 v171, v171
	v_sub_f32_e32 v172, v172, v112
	v_exp_f32_e32 v172, v172
	v_sub_f32_e32 v173, v173, v112
	v_exp_f32_e32 v173, v173
	v_sub_f32_e32 v174, v174, v112
	v_exp_f32_e32 v174, v174
	v_sub_f32_e32 v175, v175, v112
	v_exp_f32_e32 v175, v175
	v_sub_f32_e32 v176, v176, v112
	v_exp_f32_e32 v176, v176
	v_sub_f32_e32 v177, v177, v112
	v_exp_f32_e32 v177, v177
	v_sub_f32_e32 v178, v178, v112
	v_exp_f32_e32 v178, v178
	v_sub_f32_e32 v179, v179, v112
	v_exp_f32_e32 v179, v179
	v_sub_f32_e32 v180, v180, v112
	v_exp_f32_e32 v180, v180
	v_sub_f32_e32 v181, v181, v112
	v_exp_f32_e32 v181, v181
	v_sub_f32_e32 v182, v182, v112
	v_exp_f32_e32 v182, v182
	v_sub_f32_e32 v183, v183, v112
	v_exp_f32_e32 v183, v183
	v_sub_f32_e32 v184, v184, v112
	v_exp_f32_e32 v184, v184
	v_sub_f32_e32 v185, v185, v112
	v_exp_f32_e32 v185, v185
	v_add_f32_e32 v113, v170, v171
	v_add_f32_e32 v113, v113, v172
	v_add_f32_e32 v113, v113, v173
	v_add_f32_e32 v113, v113, v174
	v_add_f32_e32 v113, v113, v175
	v_add_f32_e32 v113, v113, v176
	v_add_f32_e32 v113, v113, v177
	v_add_f32_e32 v113, v113, v178
	v_add_f32_e32 v113, v113, v179
	v_add_f32_e32 v113, v113, v180
	v_add_f32_e32 v113, v113, v181
	v_add_f32_e32 v113, v113, v182
	v_add_f32_e32 v113, v113, v183
	v_add_f32_e32 v113, v113, v184
	v_add_f32_e32 v113, v113, v185
	v_fmac_f32_e32 v113, v155, v118
	v_pk_mul_f32 v[110:111], v[110:111], v[118:119] op_sel_hi:[1,0]
	v_pk_mul_f32 v[108:109], v[108:109], v[118:119] op_sel_hi:[1,0]
	v_pk_mul_f32 v[106:107], v[106:107], v[118:119] op_sel_hi:[1,0]
	v_pk_mul_f32 v[104:105], v[104:105], v[118:119] op_sel_hi:[1,0]
	v_pk_mul_f32 v[102:103], v[102:103], v[118:119] op_sel_hi:[1,0]
	v_pk_mul_f32 v[100:101], v[100:101], v[118:119] op_sel_hi:[1,0]
	v_pk_mul_f32 v[116:117], v[94:95], v[118:119] op_sel_hi:[1,0]
	v_pk_mul_f32 v[114:115], v[92:93], v[118:119] op_sel_hi:[1,0]
	v_pk_mul_f32 v[94:95], v[98:99], v[118:119] op_sel_hi:[1,0]
	v_pk_mul_f32 v[92:93], v[96:97], v[118:119] op_sel_hi:[1,0]
	v_pk_mul_f32 v[90:91], v[90:91], v[118:119] op_sel_hi:[1,0]
	v_pk_mul_f32 v[88:89], v[88:89], v[118:119] op_sel_hi:[1,0]
	v_pk_mul_f32 v[86:87], v[86:87], v[118:119] op_sel_hi:[1,0]
	v_pk_mul_f32 v[84:85], v[84:85], v[118:119] op_sel_hi:[1,0]
	v_pk_mul_f32 v[82:83], v[82:83], v[118:119] op_sel_hi:[1,0]
	v_pk_mul_f32 v[80:81], v[80:81], v[118:119] op_sel_hi:[1,0]
	v_pk_mul_f32 v[78:79], v[78:79], v[118:119] op_sel_hi:[1,0]
	v_pk_mul_f32 v[76:77], v[76:77], v[118:119] op_sel_hi:[1,0]
	v_pk_mul_f32 v[74:75], v[74:75], v[118:119] op_sel_hi:[1,0]
	v_pk_mul_f32 v[72:73], v[72:73], v[118:119] op_sel_hi:[1,0]
	v_pk_mul_f32 v[70:71], v[70:71], v[118:119] op_sel_hi:[1,0]
	v_pk_mul_f32 v[68:69], v[68:69], v[118:119] op_sel_hi:[1,0]
	v_pk_mul_f32 v[66:67], v[66:67], v[118:119] op_sel_hi:[1,0]
	v_pk_mul_f32 v[64:65], v[64:65], v[118:119] op_sel_hi:[1,0]
	v_pk_mul_f32 v[62:63], v[62:63], v[118:119] op_sel_hi:[1,0]
	v_pk_mul_f32 v[60:61], v[60:61], v[118:119] op_sel_hi:[1,0]
	v_pk_mul_f32 v[58:59], v[58:59], v[118:119] op_sel_hi:[1,0]
	v_pk_mul_f32 v[56:57], v[56:57], v[118:119] op_sel_hi:[1,0]
	v_pk_mul_f32 v[54:55], v[54:55], v[118:119] op_sel_hi:[1,0]
	v_pk_mul_f32 v[52:53], v[52:53], v[118:119] op_sel_hi:[1,0]
	v_pk_mul_f32 v[98:99], v[50:51], v[118:119] op_sel_hi:[1,0]
	v_pk_mul_f32 v[96:97], v[48:49], v[118:119] op_sel_hi:[1,0]
	v_cvt_pk_bf16_f32 v118, v170, v171
	v_cvt_pk_bf16_f32 v119, v172, v173
	v_cvt_pk_bf16_f32 v120, v174, v175
	v_cvt_pk_bf16_f32 v121, v176, v177
	v_cvt_pk_bf16_f32 v48, v178, v179
	v_cvt_pk_bf16_f32 v49, v180, v181
	v_cvt_pk_bf16_f32 v50, v182, v183
	v_cvt_pk_bf16_f32 v51, v184, v185
	ds_read_b128 v[156:159], v143 offset:0
	ds_read_b128 v[166:169], v143 offset:2560
	ds_read_b128 v[170:173], v143 offset:5120
	ds_read_b128 v[174:177], v143 offset:7680
	ds_read_b128 v[178:181], v143 offset:10240
	ds_read_b128 v[182:185], v143 offset:12800
	s_waitcnt lgkmcnt(5)
	v_mfma_f32_16x16x32_bf16 v[108:111], v[156:159], v[118:121], v[108:111]
	s_waitcnt lgkmcnt(4)
	v_mfma_f32_16x16x32_bf16 v[104:107], v[166:169], v[118:121], v[104:107]
	s_waitcnt lgkmcnt(3)
	v_mfma_f32_16x16x32_bf16 v[100:103], v[170:173], v[118:121], v[100:103]
	s_waitcnt lgkmcnt(2)
	v_mfma_f32_16x16x32_bf16 v[114:117], v[174:177], v[118:121], v[114:117]
	ds_read_b128 v[156:159], v143 offset:20480
	ds_read_b128 v[166:169], v143 offset:23040
	ds_read_b128 v[170:173], v143 offset:25600
	ds_read_b128 v[174:177], v143 offset:28160
	s_waitcnt lgkmcnt(4)
	v_mfma_f32_16x16x32_bf16 v[88:91], v[182:185], v[118:121], v[88:91]
	v_mfma_f32_16x16x32_bf16 v[84:87], v[186:189], v[118:121], v[84:87]
	v_mfma_f32_16x16x32_bf16 v[80:83], v[190:193], v[118:121], v[80:83]
	v_mfma_f32_16x16x32_bf16 v[178:181], v[178:181], v[118:121], v[92:95]
	s_nop 2
	ds_read_b128 v[92:95], v143 offset:30720
	ds_read_b128 v[182:185], v143 offset:33280
	ds_read_b128 v[186:189], v143 offset:35840
	ds_read_b128 v[190:193], v143 offset:38400
	s_waitcnt lgkmcnt(7)
	v_mfma_f32_16x16x32_bf16 v[76:79], v[156:159], v[118:121], v[76:79]
	s_waitcnt lgkmcnt(6)
	v_mfma_f32_16x16x32_bf16 v[72:75], v[166:169], v[118:121], v[72:75]
	s_waitcnt lgkmcnt(5)
	v_mfma_f32_16x16x32_bf16 v[68:71], v[170:173], v[118:121], v[68:71]
	s_waitcnt lgkmcnt(4)
	v_mfma_f32_16x16x32_bf16 v[64:67], v[174:177], v[118:121], v[64:67]
	ds_read_b128 v[156:159], v143 offset:64
	ds_read_b128 v[166:169], v143 offset:2624
	ds_read_b128 v[170:173], v143 offset:5184
	ds_read_b128 v[174:177], v143 offset:7744
	s_waitcnt lgkmcnt(7)
	v_mfma_f32_16x16x32_bf16 v[60:63], v[92:95], v[118:121], v[60:63]
	s_waitcnt lgkmcnt(6)
	v_mfma_f32_16x16x32_bf16 v[56:59], v[182:185], v[118:121], v[56:59]
	s_waitcnt lgkmcnt(5)
	v_mfma_f32_16x16x32_bf16 v[52:55], v[186:189], v[118:121], v[52:55]
	s_waitcnt lgkmcnt(4)
	v_mfma_f32_16x16x32_bf16 v[118:121], v[190:193], v[118:121], v[96:99]
	s_nop 2
	ds_read_b128 v[96:99], v143 offset:10304
	ds_read_b128 v[182:185], v143 offset:12864
	ds_read_b128 v[186:189], v143 offset:15424
	ds_read_b128 v[190:193], v143 offset:17984
	s_waitcnt lgkmcnt(7)
	v_mfma_f32_16x16x32_bf16 v[108:111], v[156:159], v[48:51], v[108:111]
	s_waitcnt lgkmcnt(6)
	v_mfma_f32_16x16x32_bf16 v[104:107], v[166:169], v[48:51], v[104:107]
	s_waitcnt lgkmcnt(5)
	v_mfma_f32_16x16x32_bf16 v[100:103], v[170:173], v[48:51], v[100:103]
	s_waitcnt lgkmcnt(4)
	v_mfma_f32_16x16x32_bf16 v[92:95], v[174:177], v[48:51], v[114:117]
	s_nop 2
	ds_read_b128 v[114:117], v143 offset:20544
	ds_read_b128 v[156:159], v143 offset:23104
	ds_read_b128 v[166:169], v143 offset:25664
	ds_read_b128 v[170:173], v143 offset:28224
	s_waitcnt lgkmcnt(7)
	v_mfma_f32_16x16x32_bf16 v[96:99], v[96:99], v[48:51], v[178:181]
	s_waitcnt lgkmcnt(6)
	v_mfma_f32_16x16x32_bf16 v[88:91], v[182:185], v[48:51], v[88:91]
	s_waitcnt lgkmcnt(5)
	v_mfma_f32_16x16x32_bf16 v[84:87], v[186:189], v[48:51], v[84:87]
	s_waitcnt lgkmcnt(4)
	v_mfma_f32_16x16x32_bf16 v[80:83], v[190:193], v[48:51], v[80:83]
	ds_read_b128 v[174:177], v143 offset:30784
	ds_read_b128 v[178:181], v143 offset:33344
	ds_read_b128 v[182:185], v143 offset:35904
	ds_read_b128 v[186:189], v143 offset:38464
	s_waitcnt lgkmcnt(7)
	v_mfma_f32_16x16x32_bf16 v[76:79], v[114:117], v[48:51], v[76:79]
	s_waitcnt lgkmcnt(6)
	v_mfma_f32_16x16x32_bf16 v[72:75], v[156:159], v[48:51], v[72:75]
	s_waitcnt lgkmcnt(5)
	v_mfma_f32_16x16x32_bf16 v[68:71], v[166:169], v[48:51], v[68:71]
	s_waitcnt lgkmcnt(4)
	v_mfma_f32_16x16x32_bf16 v[64:67], v[170:173], v[48:51], v[64:67]
	s_waitcnt lgkmcnt(3)
	v_mfma_f32_16x16x32_bf16 v[60:63], v[174:177], v[48:51], v[60:63]
	s_waitcnt lgkmcnt(2)
	v_mfma_f32_16x16x32_bf16 v[56:59], v[178:181], v[48:51], v[56:59]
	s_waitcnt lgkmcnt(1)
	v_mfma_f32_16x16x32_bf16 v[52:55], v[182:185], v[48:51], v[52:55]
	s_waitcnt lgkmcnt(0)
	v_mfma_f32_16x16x32_bf16 v[48:51], v[186:189], v[48:51], v[118:121]
	s_mov_b64 s[34:35], 0x80
	v_lshl_add_u64 v[132:133], v[132:133], 0, s[34:35]
	s_mov_b64 s[34:35], 0x40000
	v_subrev_u32_e32 v144, 64, v144
	s_cmp_eq_u32 s30, s29
	v_lshl_add_u64 v[136:137], v[136:137], 0, s[34:35]
	s_cbranch_scc1 .LBB0_1084
	v_mov_b32_e32 v155, v113
	v_mov_b32_e32 v156, v112
	s_branch .LBB0_1080
.Lda_last:
	v_sub_f32_e32 v204, v204, v221
	v_sub_f32_e32 v205, v205, v221
	v_sub_f32_e32 v206, v206, v221
	v_sub_f32_e32 v207, v207, v221
	v_sub_f32_e32 v208, v208, v221
	v_sub_f32_e32 v209, v209, v221
	v_sub_f32_e32 v210, v210, v221
	v_sub_f32_e32 v211, v211, v221
	v_sub_f32_e32 v212, v212, v221
	v_sub_f32_e32 v213, v213, v221
	v_sub_f32_e32 v214, v214, v221
	v_sub_f32_e32 v215, v215, v221
	v_sub_f32_e32 v216, v216, v221
	v_sub_f32_e32 v217, v217, v221
	v_sub_f32_e32 v218, v218, v221
	v_sub_f32_e32 v219, v219, v221
	v_add_f32_e64 v204, |v204|, v221
	v_add_f32_e64 v205, |v205|, v221
	v_add_f32_e64 v206, |v206|, v221
	v_add_f32_e64 v207, |v207|, v221
	v_add_f32_e64 v208, |v208|, v221
	v_add_f32_e64 v209, |v209|, v221
	v_add_f32_e64 v210, |v210|, v221
	v_add_f32_e64 v211, |v211|, v221
	v_add_f32_e64 v212, |v212|, v221
	v_add_f32_e64 v213, |v213|, v221
	v_add_f32_e64 v214, |v214|, v221
	v_add_f32_e64 v215, |v215|, v221
	v_add_f32_e64 v216, |v216|, v221
	v_add_f32_e64 v217, |v217|, v221
	v_add_f32_e64 v218, |v218|, v221
	v_add_f32_e64 v219, |v219|, v221
	s_branch .LBB0_1082

	.amdhsa_kernel _Z4mega1P
		.amdhsa_group_segment_fixed_size 0
		.amdhsa_private_segment_fixed_size 0
		.amdhsa_kernarg_size 568
		.amdhsa_user_sgpr_count 2
		.amdhsa_user_sgpr_dispatch_ptr 0
		.amdhsa_user_sgpr_queue_ptr 0
		.amdhsa_user_sgpr_kernarg_segment_ptr 1
		.amdhsa_user_sgpr_dispatch_id 0
		.amdhsa_user_sgpr_kernarg_preload_length 0
		.amdhsa_user_sgpr_kernarg_preload_offset 0
		.amdhsa_user_sgpr_private_segment_size 0
		.amdhsa_uses_dynamic_stack 0
		.amdhsa_enable_private_segment 0
		.amdhsa_system_sgpr_workgroup_id_x 1
		.amdhsa_system_sgpr_workgroup_id_y 0
		.amdhsa_system_sgpr_workgroup_id_z 0
		.amdhsa_system_sgpr_workgroup_info 0
		.amdhsa_system_vgpr_workitem_id 2
		.amdhsa_next_free_vgpr 256
		.amdhsa_next_free_sgpr 102
		.amdhsa_accum_offset 256
		.amdhsa_reserve_vcc 1
		.amdhsa_float_round_mode_32 0
		.amdhsa_float_round_mode_16_64 0
		.amdhsa_float_denorm_mode_32 3
		.amdhsa_float_denorm_mode_16_64 3
		.amdhsa_dx10_clamp 1
		.amdhsa_ieee_mode 1
		.amdhsa_fp16_overflow 0
		.amdhsa_tg_split 0
		.amdhsa_exception_fp_ieee_invalid_op 0
		.amdhsa_exception_fp_denorm_src 0
		.amdhsa_exception_fp_ieee_div_zero 0
		.amdhsa_exception_fp_ieee_overflow 0
		.amdhsa_exception_fp_ieee_underflow 0
		.amdhsa_exception_fp_ieee_inexact 0
		.amdhsa_exception_int_div_zero 0
	.end_amdhsa_kernel

amdhsa.kernels:
  - .agpr_count:     0
    .args:
      - .offset:         0
        .size:           312
        .value_kind:     by_value
      - .offset:         312
        .size:           4
        .value_kind:     hidden_block_count_x
      - .offset:         316
        .size:           4
        .value_kind:     hidden_block_count_y
      - .offset:         320
        .size:           4
        .value_kind:     hidden_block_count_z
      - .offset:         324
        .size:           2
        .value_kind:     hidden_group_size_x
      - .offset:         326
        .size:           2
        .value_kind:     hidden_group_size_y
      - .offset:         328
        .size:           2
        .value_kind:     hidden_group_size_z
      - .offset:         330
        .size:           2
        .value_kind:     hidden_remainder_x
      - .offset:         332
        .size:           2
        .value_kind:     hidden_remainder_y
      - .offset:         334
        .size:           2
        .value_kind:     hidden_remainder_z
      - .offset:         352
        .size:           8
        .value_kind:     hidden_global_offset_x
      - .offset:         360
        .size:           8
        .value_kind:     hidden_global_offset_y
      - .offset:         368
        .size:           8
        .value_kind:     hidden_global_offset_z
      - .offset:         376
        .size:           2
        .value_kind:     hidden_grid_dims
      - .offset:         400
        .size:           8
        .value_kind:     hidden_multigrid_sync_arg
      - .offset:         432
        .size:           4
        .value_kind:     hidden_dynamic_lds_size
    .group_segment_fixed_size: 0
    .kernarg_segment_align: 8
    .kernarg_segment_size: 568
    .language:       OpenCL C
    .language_version:
      - 2
      - 0
    .max_flat_workgroup_size: 512
    .name:           _Z4mega1P
    .private_segment_fixed_size: 0
    .sgpr_count:     108
    .sgpr_spill_count: 723
    .symbol:         _Z4mega1P.kd
    .uniform_work_group_size: 1
    .uses_dynamic_stack: false
    .vgpr_count:     256
    .vgpr_spill_count: 0
    .wavefront_size: 64
